# v61 + m0->LDS-DMA wait states in K-loop load segments filled with the segment's own ds_reads instead of s_nop (78 s_nop removed per pass over the six loops)
# speedup vs baseline: 1.0224x; 1.0034x over previous
; #define PG8_STAGE(bufoff, gbase, voff) do { _Pragma("unroll") for (int _i = 0; _i < 2; ++_i) \
;         __builtin_amdgcn_global_load_lds((const unsigned*)((const char*)(gbase) + (voff)[_i]), (LAS unsigned*)(lds + (bufoff) + ldsw + _i * 8192), 16, 0, 0); } while (0)
; #define PG8_LDA(dst, b, h) do { _Pragma("unroll") for (int m = 0; m < 4; ++m) _Pragma("unroll") for (int k = 0; k < 2; ++k) dst[m][k] = *(const LAS bf16x8*)(lds + PG8_SA(b, h) + aoff + m * 2048 + k * 1024); } while (0)
; #define PG8_LDB(dst, b, h) do { _Pragma("unroll") for (int n = 0; n < 2; ++n) _Pragma("unroll") for (int k = 0; k < 2; ++k) dst[n][k] = *(const LAS bf16x8*)(lds + PG8_SB(b, h) + boff + n * 2048 + k * 1024); } while (0)
; #define PG8_MMA(ai, bj, At, Bt) do { __builtin_amdgcn_s_setprio(1); _Pragma("unroll") for (int m = 0; m < 4; ++m) _Pragma("unroll") for (int n = 0; n < 2; ++n) _Pragma("unroll") for (int k = 0; k < 2; ++k) \
;         acc[ai][bj][m][n] = __builtin_amdgcn_mfma_f32_16x16x32_bf16(Bt[n][k], At[m][k], acc[ai][bj][m][n], 0, 0, 0); __builtin_amdgcn_s_setprio(0); } while (0)
; #define PG8_WAIT_V(n) asm volatile("s_waitcnt vmcnt(" #n ")" ::: "memory")
; #define PG8_WAIT_L(n) asm volatile("s_waitcnt lgkmcnt(" #n ")" ::: "memory")
; template <class Epi, class Sched>
; __device__ __forceinline__ void gemm_phase(LAS unsigned char* lds, const Gemm g, const Sched& S, const Epi& E) {
;     ...
;         for (int t = 0; t < nt; t += 2) {
;             const bool last = (t == nt - 2);
;             const char* a1 = cA + (size_t)(t + 1) * kstep;
;             const char* a2 = last ? nA : cA + (size_t)(t + 2) * kstep; const char* b2 = last ? nB : cB + (size_t)(t + 2) * kstep;
;             const char* a3 = a2 + kstep; const char* b3 = b2 + kstep;
;             PG8_LDB(B0, 0, 0); PG8_SCHED; PG8_LDA(At, 0, 0); PG8_STAGE(PG8_SA(1, 1), a1 + hstep, voffA);
;             PG8_WAIT_L(8); PG8_BAR; PG8_WAIT_L(0); PG8_MMA(0, 0, At, B0); PG8_BAR; PG8_SCHED;
;             PG8_LDB(B1, 0, 1); PG8_STAGE(PG8_SB(0, 0), b2, voffB);
;             PG8_BAR; PG8_WAIT_L(0); PG8_MMA(0, 1, At, B1); PG8_BAR;
;             PG8_LDA(At, 0, 1); PG8_STAGE(PG8_SA(0, 0), a2, voffA);
;             PG8_BAR; PG8_WAIT_L(0); PG8_MMA(1, 0, At, B0); PG8_BAR; PG8_SCHED;
;             PG8_STAGE(PG8_SB(0, 1), b2 + hstep, voffB);
;             PG8_WAIT_V(6); PG8_BAR; PG8_MMA(1, 1, At, B1); PG8_BAR;
.LBB0_44:
	s_add_u32 s50, s28, 0x100
	s_addc_u32 s51, s29, 0
	s_cmpk_eq_i32 s75, 0x7c
	s_cselect_b32 s55, s27, s51
	s_cselect_b32 s54, s71, s50
	s_cselect_b32 s53, s25, s74
	s_cselect_b32 s52, s72, s73
	s_add_i32 m0, s9, 0xc000
	ds_read_b128 v[66:69], v226
	global_load_lds_dwordx4 v150, s[28:29]
	s_add_i32 m0, s9, 0xe000
	ds_read_b128 v[70:73], v226 offset:1024
	global_load_lds_dwordx4 v148, s[28:29]
	s_add_i32 s38, 0, 0x10000
	ds_read_b128 v[74:77], v226 offset:2048
	ds_read_b128 v[78:81], v226 offset:3072
	ds_read_b128 v[152:155], v165
	ds_read_b128 v[166:169], v165 offset:1024
	ds_read_b128 v[170:173], v165 offset:2048
	ds_read_b128 v[174:177], v165 offset:3072
	ds_read_b128 v[178:181], v165 offset:4096
	ds_read_b128 v[182:185], v165 offset:5120
	ds_read_b128 v[186:189], v165 offset:6144
	ds_read_b128 v[190:193], v165 offset:7168
	s_add_i32 s39, 0, 0x14000
	ds_read_b128 v[194:197], v226 offset:16384
	ds_read_b128 v[198:201], v226 offset:17408
	ds_read_b128 v[202:205], v226 offset:18432
	ds_read_b128 v[210:213], v226 offset:19456
	s_waitcnt lgkmcnt(4)
	s_barrier
	s_waitcnt lgkmcnt(0)
	v_mfma_f32_16x16x32_bf16 v[142:145], v[66:69], v[152:155], v[142:145]
	v_mfma_f32_16x16x32_bf16 v[138:141], v[74:77], v[152:155], v[138:141]
	v_mfma_f32_16x16x32_bf16 v[126:129], v[66:69], v[170:173], v[126:129]
	v_mfma_f32_16x16x32_bf16 v[122:125], v[74:77], v[170:173], v[122:125]
	v_mfma_f32_16x16x32_bf16 v[110:113], v[66:69], v[178:181], v[110:113]
	v_mfma_f32_16x16x32_bf16 v[106:109], v[74:77], v[178:181], v[106:109]
	v_mfma_f32_16x16x32_bf16 v[102:105], v[66:69], v[186:189], v[102:105]
	v_mfma_f32_16x16x32_bf16 v[98:101], v[74:77], v[186:189], v[98:101]
	v_mfma_f32_16x16x32_bf16 v[142:145], v[70:73], v[166:169], v[142:145]
	v_mfma_f32_16x16x32_bf16 v[138:141], v[78:81], v[166:169], v[138:141]
	v_mfma_f32_16x16x32_bf16 v[126:129], v[70:73], v[174:177], v[126:129]
	v_mfma_f32_16x16x32_bf16 v[122:125], v[78:81], v[174:177], v[122:125]
	v_mfma_f32_16x16x32_bf16 v[110:113], v[70:73], v[182:185], v[110:113]
	v_mfma_f32_16x16x32_bf16 v[106:109], v[78:81], v[182:185], v[106:109]
	v_mfma_f32_16x16x32_bf16 v[102:105], v[70:73], v[190:193], v[102:105]
	v_mfma_f32_16x16x32_bf16 v[98:101], v[78:81], v[190:193], v[98:101]
	v_mfma_f32_16x16x32_bf16 v[134:137], v[194:197], v[152:155], v[134:137]
	v_mfma_f32_16x16x32_bf16 v[130:133], v[202:205], v[152:155], v[130:133]
	v_mfma_f32_16x16x32_bf16 v[118:121], v[194:197], v[170:173], v[118:121]
	v_mfma_f32_16x16x32_bf16 v[114:117], v[202:205], v[170:173], v[114:117]
	v_mfma_f32_16x16x32_bf16 v[94:97], v[194:197], v[178:181], v[94:97]
	v_mfma_f32_16x16x32_bf16 v[90:93], v[202:205], v[178:181], v[90:93]
	v_mfma_f32_16x16x32_bf16 v[86:89], v[194:197], v[186:189], v[86:89]
	v_mfma_f32_16x16x32_bf16 v[82:85], v[202:205], v[186:189], v[82:85]
	v_mfma_f32_16x16x32_bf16 v[134:137], v[198:201], v[166:169], v[134:137]
	v_mfma_f32_16x16x32_bf16 v[130:133], v[210:213], v[166:169], v[130:133]
	v_mfma_f32_16x16x32_bf16 v[118:121], v[198:201], v[174:177], v[118:121]
	v_mfma_f32_16x16x32_bf16 v[114:117], v[210:213], v[174:177], v[114:117]
	v_mfma_f32_16x16x32_bf16 v[94:97], v[198:201], v[182:185], v[94:97]
	v_mfma_f32_16x16x32_bf16 v[90:93], v[210:213], v[182:185], v[90:93]
	v_mfma_f32_16x16x32_bf16 v[86:89], v[198:201], v[190:193], v[86:89]
	v_mfma_f32_16x16x32_bf16 v[82:85], v[210:213], v[190:193], v[82:85]
	s_barrier
	s_add_i32 s28, s38, s60
	s_mov_b32 m0, s28
	ds_read_b128 v[152:155], v165 offset:16384
	global_load_lds_dwordx4 v0, s[52:53]
	s_add_i32 m0, s28, 0x2000
	ds_read_b128 v[166:169], v165 offset:17408
	global_load_lds_dwordx4 v146, s[52:53]
	s_mov_b32 m0, s9
	ds_read_b128 v[170:173], v165 offset:18432
	global_load_lds_dwordx4 v0, s[54:55]
	s_mov_b32 m0, s61
	ds_read_b128 v[174:177], v165 offset:19456
	global_load_lds_dwordx4 v146, s[54:55]
	ds_read_b128 v[178:181], v165 offset:20480
	ds_read_b128 v[182:185], v165 offset:21504
	ds_read_b128 v[186:189], v165 offset:22528
	ds_read_b128 v[190:193], v165 offset:23552
	s_waitcnt vmcnt(4)
	s_waitcnt lgkmcnt(0)
	s_barrier
	v_mfma_f32_16x16x32_bf16 v[62:65], v[66:69], v[152:155], v[62:65]
	v_mfma_f32_16x16x32_bf16 v[58:61], v[74:77], v[152:155], v[58:61]
	v_mfma_f32_16x16x32_bf16 v[46:49], v[66:69], v[170:173], v[46:49]
	v_mfma_f32_16x16x32_bf16 v[42:45], v[74:77], v[170:173], v[42:45]
	v_mfma_f32_16x16x32_bf16 v[30:33], v[66:69], v[178:181], v[30:33]
	v_mfma_f32_16x16x32_bf16 v[26:29], v[74:77], v[178:181], v[26:29]
	v_mfma_f32_16x16x32_bf16 v[22:25], v[66:69], v[186:189], v[22:25]
	v_mfma_f32_16x16x32_bf16 v[14:17], v[74:77], v[186:189], v[14:17]
	v_mfma_f32_16x16x32_bf16 v[62:65], v[70:73], v[166:169], v[62:65]
	v_mfma_f32_16x16x32_bf16 v[58:61], v[78:81], v[166:169], v[58:61]
	v_mfma_f32_16x16x32_bf16 v[46:49], v[70:73], v[174:177], v[46:49]
	v_mfma_f32_16x16x32_bf16 v[42:45], v[78:81], v[174:177], v[42:45]
	v_mfma_f32_16x16x32_bf16 v[30:33], v[70:73], v[182:185], v[30:33]
	v_mfma_f32_16x16x32_bf16 v[26:29], v[78:81], v[182:185], v[26:29]
	v_mfma_f32_16x16x32_bf16 v[22:25], v[70:73], v[190:193], v[22:25]
	v_mfma_f32_16x16x32_bf16 v[14:17], v[78:81], v[190:193], v[14:17]
	v_mfma_f32_16x16x32_bf16 v[54:57], v[194:197], v[152:155], v[54:57]
	v_mfma_f32_16x16x32_bf16 v[50:53], v[202:205], v[152:155], v[50:53]
	v_mfma_f32_16x16x32_bf16 v[38:41], v[194:197], v[170:173], v[38:41]
	v_mfma_f32_16x16x32_bf16 v[34:37], v[202:205], v[170:173], v[34:37]
	v_mfma_f32_16x16x32_bf16 v[18:21], v[194:197], v[178:181], v[18:21]
	v_mfma_f32_16x16x32_bf16 v[10:13], v[202:205], v[178:181], v[10:13]
	v_mfma_f32_16x16x32_bf16 v[6:9], v[194:197], v[186:189], v[6:9]
	v_mfma_f32_16x16x32_bf16 v[2:5], v[202:205], v[186:189], v[2:5]
	v_mfma_f32_16x16x32_bf16 v[54:57], v[198:201], v[166:169], v[54:57]
	v_mfma_f32_16x16x32_bf16 v[50:53], v[210:213], v[166:169], v[50:53]
	v_mfma_f32_16x16x32_bf16 v[38:41], v[198:201], v[174:177], v[38:41]
	v_mfma_f32_16x16x32_bf16 v[34:37], v[210:213], v[174:177], v[34:37]
	v_mfma_f32_16x16x32_bf16 v[18:21], v[198:201], v[182:185], v[18:21]
	v_mfma_f32_16x16x32_bf16 v[10:13], v[210:213], v[182:185], v[10:13]
	v_mfma_f32_16x16x32_bf16 v[6:9], v[198:201], v[190:193], v[6:9]
	v_mfma_f32_16x16x32_bf16 v[2:5], v[210:213], v[190:193], v[2:5]
	s_barrier
; #define PG8_STAGE(bufoff, gbase, voff) do { _Pragma("unroll") for (int _i = 0; _i < 2; ++_i) \
;         __builtin_amdgcn_global_load_lds((const unsigned*)((const char*)(gbase) + (voff)[_i]), (LAS unsigned*)(lds + (bufoff) + ldsw + _i * 8192), 16, 0, 0); } while (0)
; #define PG8_LDA(dst, b, h) do { _Pragma("unroll") for (int m = 0; m < 4; ++m) _Pragma("unroll") for (int k = 0; k < 2; ++k) dst[m][k] = *(const LAS bf16x8*)(lds + PG8_SA(b, h) + aoff + m * 2048 + k * 1024); } while (0)
; #define PG8_LDB(dst, b, h) do { _Pragma("unroll") for (int n = 0; n < 2; ++n) _Pragma("unroll") for (int k = 0; k < 2; ++k) dst[n][k] = *(const LAS bf16x8*)(lds + PG8_SB(b, h) + boff + n * 2048 + k * 1024); } while (0)
; #define PG8_MMA(ai, bj, At, Bt) do { __builtin_amdgcn_s_setprio(1); _Pragma("unroll") for (int m = 0; m < 4; ++m) _Pragma("unroll") for (int n = 0; n < 2; ++n) _Pragma("unroll") for (int k = 0; k < 2; ++k) \
;         acc[ai][bj][m][n] = __builtin_amdgcn_mfma_f32_16x16x32_bf16(Bt[n][k], At[m][k], acc[ai][bj][m][n], 0, 0, 0); __builtin_amdgcn_s_setprio(0); } while (0)
; #define PG8_WAIT_V(n) asm volatile("s_waitcnt vmcnt(" #n ")" ::: "memory")
; #define PG8_WAIT_L(n) asm volatile("s_waitcnt lgkmcnt(" #n ")" ::: "memory")
; #define PG8_BAR __builtin_amdgcn_s_barrier()
;     __device__ __forceinline__ void operator()(const f32x4 (&acc)[2][2][4][2], const Unit& u, int wr, int wc, int fr, int fq) const {
;         const bool lat = u.pm < 64; const int r = lat ? (u.pm >> 3) : 8;
; template <class Epi, class Sched>
; __device__ __forceinline__ void gemm_phase(LAS unsigned char* lds, const Gemm g, const Sched& S, const Epi& E) {
;     ...
;             PG8_LDB(B0, 1, 0); PG8_SCHED; PG8_LDA(At, 1, 0); PG8_STAGE(PG8_SA(0, 1), a2 + hstep, voffA);
;             PG8_WAIT_L(8); PG8_BAR; PG8_WAIT_L(0); PG8_MMA(0, 0, At, B0); PG8_BAR; PG8_SCHED;
;             PG8_LDB(B1, 1, 1); PG8_STAGE(PG8_SB(1, 0), b3, voffB);
;             PG8_BAR; PG8_WAIT_L(0); PG8_MMA(0, 1, At, B1); PG8_BAR;
;             PG8_LDA(At, 1, 1); PG8_STAGE(PG8_SA(1, 0), a3, voffA);
;             PG8_BAR; PG8_WAIT_L(0); PG8_MMA(1, 0, At, B0); PG8_BAR; PG8_SCHED;
;             PG8_STAGE(PG8_SB(1, 1), b3 + hstep, voffB);
;             PG8_WAIT_V(6); PG8_BAR; PG8_MMA(1, 1, At, B1); PG8_BAR;
;         }
;         E(acc, cur, wr, wc, fr, fq);
;         if (!has_next) break;
	s_add_u32 s28, s52, 0x200000
	s_addc_u32 s29, s53, 0
	s_add_i32 s38, s39, s60
	s_mov_b32 m0, s38
	ds_read_b128 v[66:69], v226 offset:32768
	global_load_lds_dwordx4 v0, s[28:29]
	s_add_i32 m0, s38, 0x2000
	ds_read_b128 v[70:73], v226 offset:33792
	global_load_lds_dwordx4 v146, s[28:29]
	s_add_u32 s28, s54, 0x200000
	s_addc_u32 s29, s55, 0
	s_mov_b32 m0, s62
	ds_read_b128 v[74:77], v226 offset:34816
	global_load_lds_dwordx4 v0, s[28:29]
	s_mov_b32 m0, s63
	ds_read_b128 v[78:81], v226 offset:35840
	global_load_lds_dwordx4 v146, s[28:29]
	s_add_i32 s38, 0, 0x18000
	ds_read_b128 v[152:155], v165 offset:32768
	ds_read_b128 v[166:169], v165 offset:33792
	ds_read_b128 v[170:173], v165 offset:34816
	ds_read_b128 v[174:177], v165 offset:35840
	ds_read_b128 v[178:181], v165 offset:36864
	ds_read_b128 v[182:185], v165 offset:37888
	ds_read_b128 v[186:189], v165 offset:38912
	ds_read_b128 v[190:193], v165 offset:39936
	s_add_i32 s39, 0, 0x1c000
	ds_read_b128 v[194:197], v226 offset:49152
	ds_read_b128 v[198:201], v226 offset:50176
	ds_read_b128 v[202:205], v226 offset:51200
	ds_read_b128 v[210:213], v226 offset:52224
	s_waitcnt lgkmcnt(4)
	s_barrier
	s_waitcnt lgkmcnt(0)
	v_mfma_f32_16x16x32_bf16 v[142:145], v[66:69], v[152:155], v[142:145]
	v_mfma_f32_16x16x32_bf16 v[138:141], v[74:77], v[152:155], v[138:141]
	v_mfma_f32_16x16x32_bf16 v[126:129], v[66:69], v[170:173], v[126:129]
	v_mfma_f32_16x16x32_bf16 v[122:125], v[74:77], v[170:173], v[122:125]
	v_mfma_f32_16x16x32_bf16 v[110:113], v[66:69], v[178:181], v[110:113]
	v_mfma_f32_16x16x32_bf16 v[106:109], v[74:77], v[178:181], v[106:109]
	v_mfma_f32_16x16x32_bf16 v[102:105], v[66:69], v[186:189], v[102:105]
	v_mfma_f32_16x16x32_bf16 v[98:101], v[74:77], v[186:189], v[98:101]
	v_mfma_f32_16x16x32_bf16 v[142:145], v[70:73], v[166:169], v[142:145]
	v_mfma_f32_16x16x32_bf16 v[138:141], v[78:81], v[166:169], v[138:141]
	v_mfma_f32_16x16x32_bf16 v[126:129], v[70:73], v[174:177], v[126:129]
	v_mfma_f32_16x16x32_bf16 v[122:125], v[78:81], v[174:177], v[122:125]
	v_mfma_f32_16x16x32_bf16 v[110:113], v[70:73], v[182:185], v[110:113]
	v_mfma_f32_16x16x32_bf16 v[106:109], v[78:81], v[182:185], v[106:109]
	v_mfma_f32_16x16x32_bf16 v[102:105], v[70:73], v[190:193], v[102:105]
	v_mfma_f32_16x16x32_bf16 v[98:101], v[78:81], v[190:193], v[98:101]
	v_mfma_f32_16x16x32_bf16 v[134:137], v[194:197], v[152:155], v[134:137]
	v_mfma_f32_16x16x32_bf16 v[130:133], v[202:205], v[152:155], v[130:133]
	v_mfma_f32_16x16x32_bf16 v[118:121], v[194:197], v[170:173], v[118:121]
	v_mfma_f32_16x16x32_bf16 v[114:117], v[202:205], v[170:173], v[114:117]
	v_mfma_f32_16x16x32_bf16 v[94:97], v[194:197], v[178:181], v[94:97]
	v_mfma_f32_16x16x32_bf16 v[90:93], v[202:205], v[178:181], v[90:93]
	v_mfma_f32_16x16x32_bf16 v[86:89], v[194:197], v[186:189], v[86:89]
	v_mfma_f32_16x16x32_bf16 v[82:85], v[202:205], v[186:189], v[82:85]
	v_mfma_f32_16x16x32_bf16 v[134:137], v[198:201], v[166:169], v[134:137]
	v_mfma_f32_16x16x32_bf16 v[130:133], v[210:213], v[166:169], v[130:133]
	v_mfma_f32_16x16x32_bf16 v[118:121], v[198:201], v[174:177], v[118:121]
	v_mfma_f32_16x16x32_bf16 v[114:117], v[210:213], v[174:177], v[114:117]
	v_mfma_f32_16x16x32_bf16 v[94:97], v[198:201], v[182:185], v[94:97]
	v_mfma_f32_16x16x32_bf16 v[90:93], v[210:213], v[182:185], v[90:93]
	v_mfma_f32_16x16x32_bf16 v[86:89], v[198:201], v[190:193], v[86:89]
	v_mfma_f32_16x16x32_bf16 v[82:85], v[210:213], v[190:193], v[82:85]
	s_barrier
	s_add_i32 s28, s38, s60
	s_add_u32 s100, s52, s36
	s_addc_u32 s101, s53, s37
	s_mov_b32 m0, s28
	ds_read_b128 v[152:155], v165 offset:49152
	global_load_lds_dwordx4 v0, s[100:101]
	s_add_i32 m0, s28, 0x2000
	ds_read_b128 v[166:169], v165 offset:50176
	global_load_lds_dwordx4 v146, s[100:101]
	s_mov_b32 m0, s66
	s_add_u32 s100, s54, s36
	s_addc_u32 s101, s55, s37
	global_load_lds_dwordx4 v0, s[100:101]
	s_mov_b32 m0, s67
	ds_read_b128 v[170:173], v165 offset:51200
	global_load_lds_dwordx4 v146, s[100:101]
	ds_read_b128 v[174:177], v165 offset:52224
	ds_read_b128 v[178:181], v165 offset:53248
	ds_read_b128 v[182:185], v165 offset:54272
	ds_read_b128 v[186:189], v165 offset:55296
	ds_read_b128 v[190:193], v165 offset:56320
	s_waitcnt vmcnt(4)
	s_waitcnt lgkmcnt(0)
	s_barrier
	v_mfma_f32_16x16x32_bf16 v[62:65], v[66:69], v[152:155], v[62:65]
	v_mfma_f32_16x16x32_bf16 v[58:61], v[74:77], v[152:155], v[58:61]
	v_mfma_f32_16x16x32_bf16 v[46:49], v[66:69], v[170:173], v[46:49]
	v_mfma_f32_16x16x32_bf16 v[42:45], v[74:77], v[170:173], v[42:45]
	v_mfma_f32_16x16x32_bf16 v[30:33], v[66:69], v[178:181], v[30:33]
	v_mfma_f32_16x16x32_bf16 v[26:29], v[74:77], v[178:181], v[26:29]
	v_mfma_f32_16x16x32_bf16 v[22:25], v[66:69], v[186:189], v[22:25]
	v_mfma_f32_16x16x32_bf16 v[14:17], v[74:77], v[186:189], v[14:17]
	v_mfma_f32_16x16x32_bf16 v[62:65], v[70:73], v[166:169], v[62:65]
	v_mfma_f32_16x16x32_bf16 v[58:61], v[78:81], v[166:169], v[58:61]
	v_mfma_f32_16x16x32_bf16 v[46:49], v[70:73], v[174:177], v[46:49]
	v_mfma_f32_16x16x32_bf16 v[42:45], v[78:81], v[174:177], v[42:45]
	v_mfma_f32_16x16x32_bf16 v[30:33], v[70:73], v[182:185], v[30:33]
	v_mfma_f32_16x16x32_bf16 v[26:29], v[78:81], v[182:185], v[26:29]
	v_mfma_f32_16x16x32_bf16 v[22:25], v[70:73], v[190:193], v[22:25]
	v_mfma_f32_16x16x32_bf16 v[14:17], v[78:81], v[190:193], v[14:17]
	s_add_u32 s28, s52, 0x200080
	s_addc_u32 s29, s53, 0
	s_add_i32 s38, s39, s60
	s_mov_b32 m0, s38
	s_nop 0
	global_load_lds_dwordx4 v0, s[28:29]
	s_add_i32 m0, s38, 0x2000
	s_nop 0
	global_load_lds_dwordx4 v146, s[28:29]
	v_mfma_f32_16x16x32_bf16 v[54:57], v[194:197], v[152:155], v[54:57]
	v_mfma_f32_16x16x32_bf16 v[50:53], v[202:205], v[152:155], v[50:53]
	v_mfma_f32_16x16x32_bf16 v[38:41], v[194:197], v[170:173], v[38:41]
	v_mfma_f32_16x16x32_bf16 v[34:37], v[202:205], v[170:173], v[34:37]
	v_mfma_f32_16x16x32_bf16 v[18:21], v[194:197], v[178:181], v[18:21]
	v_mfma_f32_16x16x32_bf16 v[10:13], v[202:205], v[178:181], v[10:13]
	v_mfma_f32_16x16x32_bf16 v[6:9], v[194:197], v[186:189], v[6:9]
	v_mfma_f32_16x16x32_bf16 v[2:5], v[202:205], v[186:189], v[2:5]
	v_mfma_f32_16x16x32_bf16 v[54:57], v[198:201], v[166:169], v[54:57]
	v_mfma_f32_16x16x32_bf16 v[50:53], v[210:213], v[166:169], v[50:53]
	v_mfma_f32_16x16x32_bf16 v[38:41], v[198:201], v[174:177], v[38:41]
	v_mfma_f32_16x16x32_bf16 v[34:37], v[210:213], v[174:177], v[34:37]
	v_mfma_f32_16x16x32_bf16 v[18:21], v[198:201], v[182:185], v[18:21]
	v_mfma_f32_16x16x32_bf16 v[10:13], v[210:213], v[182:185], v[10:13]
	v_mfma_f32_16x16x32_bf16 v[6:9], v[198:201], v[190:193], v[6:9]
	v_mfma_f32_16x16x32_bf16 v[2:5], v[210:213], v[190:193], v[2:5]
	s_add_i32 s75, s75, 2
	s_add_u32 s73, s73, 0x100
	s_addc_u32 s74, s74, 0
	s_cmpk_gt_u32 s75, 0x7d
	s_mov_b64 s[28:29], s[50:51]
	s_barrier
	s_cbranch_scc0 .LBB0_44
	s_cmp_lt_i32 s8, 64
	s_cselect_b64 s[50:51], -1, 0
	s_cmp_gt_i32 s8, 63
	s_cbranch_scc0 .LBB0_35
	s_mov_b64 s[52:53], 0x18000
	s_mov_b64 s[28:29], s[46:47]
	s_branch .LBB0_36

; #define PG8_STAGE(bufoff, gbase, voff) do { _Pragma("unroll") for (int _i = 0; _i < 2; ++_i) \
;         __builtin_amdgcn_global_load_lds((const unsigned*)((const char*)(gbase) + (voff)[_i]), (LAS unsigned*)(lds + (bufoff) + ldsw + _i * 8192), 16, 0, 0); } while (0)
; #define PG8_LDA(dst, b, h) do { _Pragma("unroll") for (int m = 0; m < 4; ++m) _Pragma("unroll") for (int k = 0; k < 2; ++k) dst[m][k] = *(const LAS bf16x8*)(lds + PG8_SA(b, h) + aoff + m * 2048 + k * 1024); } while (0)
; #define PG8_LDB(dst, b, h) do { _Pragma("unroll") for (int n = 0; n < 2; ++n) _Pragma("unroll") for (int k = 0; k < 2; ++k) dst[n][k] = *(const LAS bf16x8*)(lds + PG8_SB(b, h) + boff + n * 2048 + k * 1024); } while (0)
; #define PG8_MMA(ai, bj, At, Bt) do { __builtin_amdgcn_s_setprio(1); _Pragma("unroll") for (int m = 0; m < 4; ++m) _Pragma("unroll") for (int n = 0; n < 2; ++n) _Pragma("unroll") for (int k = 0; k < 2; ++k) \
;         acc[ai][bj][m][n] = __builtin_amdgcn_mfma_f32_16x16x32_bf16(Bt[n][k], At[m][k], acc[ai][bj][m][n], 0, 0, 0); __builtin_amdgcn_s_setprio(0); } while (0)
; #define PG8_WAIT_V(n) asm volatile("s_waitcnt vmcnt(" #n ")" ::: "memory")
; #define PG8_WAIT_L(n) asm volatile("s_waitcnt lgkmcnt(" #n ")" ::: "memory")
; template <class Epi, class Sched>
; __device__ __forceinline__ void gemm_phase(LAS unsigned char* lds, const Gemm g, const Sched& S, const Epi& E) {
;     ...
;         for (int t = 0; t < nt; t += 2) {
;             const bool last = (t == nt - 2);
;             const char* a1 = cA + (size_t)(t + 1) * kstep;
;             const char* a2 = last ? nA : cA + (size_t)(t + 2) * kstep; const char* b2 = last ? nB : cB + (size_t)(t + 2) * kstep;
;             const char* a3 = a2 + kstep; const char* b3 = b2 + kstep;
;             PG8_LDB(B0, 0, 0); PG8_SCHED; PG8_LDA(At, 0, 0); PG8_STAGE(PG8_SA(1, 1), a1 + hstep, voffA);
;             PG8_WAIT_L(8); PG8_BAR; PG8_WAIT_L(0); PG8_MMA(0, 0, At, B0); PG8_BAR; PG8_SCHED;
;             PG8_LDB(B1, 0, 1); PG8_STAGE(PG8_SB(0, 0), b2, voffB);
;             PG8_BAR; PG8_WAIT_L(0); PG8_MMA(0, 1, At, B1); PG8_BAR;
;             PG8_LDA(At, 0, 1); PG8_STAGE(PG8_SA(0, 0), a2, voffA);
;             PG8_BAR; PG8_WAIT_L(0); PG8_MMA(1, 0, At, B0); PG8_BAR; PG8_SCHED;
;             PG8_STAGE(PG8_SB(0, 1), b2 + hstep, voffB);
;             PG8_WAIT_V(6); PG8_BAR; PG8_MMA(1, 1, At, B1); PG8_BAR;
.LBB0_58:
	s_add_u32 s52, s50, 0x100
	s_addc_u32 s53, s51, 0
	s_cmp_eq_u32 s71, 28
	s_cselect_b32 s57, s11, s53
	s_cselect_b32 s56, s29, s52
	s_cselect_b32 s55, s41, s70
	s_cselect_b32 s54, s43, s69
	s_add_i32 m0, s25, 0xc000
	ds_read_b128 v[140:143], v226
	global_load_lds_dwordx4 v134, s[50:51]
	s_add_i32 m0, s25, 0xe000
	ds_read_b128 v[144:147], v226 offset:1024
	global_load_lds_dwordx4 v132, s[50:51]
	s_add_i32 s38, 0, 0x10000
	ds_read_b128 v[148:151], v226 offset:2048
	ds_read_b128 v[152:155], v226 offset:3072
	ds_read_b128 v[160:163], v139
	ds_read_b128 v[164:167], v139 offset:1024
	ds_read_b128 v[168:171], v139 offset:2048
	ds_read_b128 v[172:175], v139 offset:3072
	ds_read_b128 v[176:179], v139 offset:4096
	ds_read_b128 v[180:183], v139 offset:5120
	ds_read_b128 v[184:187], v139 offset:6144
	ds_read_b128 v[188:191], v139 offset:7168
	s_add_i32 s50, 0, 0x14000
	ds_read_b128 v[192:195], v226 offset:16384
	ds_read_b128 v[196:199], v226 offset:17408
	ds_read_b128 v[200:203], v226 offset:18432
	ds_read_b128 v[204:207], v226 offset:19456
	s_waitcnt lgkmcnt(4)
	s_barrier
	s_waitcnt lgkmcnt(0)
	v_mfma_f32_16x16x32_bf16 v[126:129], v[140:143], v[160:163], v[126:129]
	v_mfma_f32_16x16x32_bf16 v[122:125], v[148:151], v[160:163], v[122:125]
	v_mfma_f32_16x16x32_bf16 v[118:121], v[140:143], v[168:171], v[118:121]
	v_mfma_f32_16x16x32_bf16 v[114:117], v[148:151], v[168:171], v[114:117]
	v_mfma_f32_16x16x32_bf16 v[106:109], v[140:143], v[176:179], v[106:109]
	v_mfma_f32_16x16x32_bf16 v[98:101], v[148:151], v[176:179], v[98:101]
	v_mfma_f32_16x16x32_bf16 v[90:93], v[140:143], v[184:187], v[90:93]
	v_mfma_f32_16x16x32_bf16 v[82:85], v[148:151], v[184:187], v[82:85]
	v_mfma_f32_16x16x32_bf16 v[126:129], v[144:147], v[164:167], v[126:129]
	v_mfma_f32_16x16x32_bf16 v[122:125], v[152:155], v[164:167], v[122:125]
	v_mfma_f32_16x16x32_bf16 v[118:121], v[144:147], v[172:175], v[118:121]
	v_mfma_f32_16x16x32_bf16 v[114:117], v[152:155], v[172:175], v[114:117]
	v_mfma_f32_16x16x32_bf16 v[106:109], v[144:147], v[180:183], v[106:109]
	v_mfma_f32_16x16x32_bf16 v[98:101], v[152:155], v[180:183], v[98:101]
	v_mfma_f32_16x16x32_bf16 v[90:93], v[144:147], v[188:191], v[90:93]
	v_mfma_f32_16x16x32_bf16 v[82:85], v[152:155], v[188:191], v[82:85]
	v_mfma_f32_16x16x32_bf16 v[110:113], v[192:195], v[160:163], v[110:113]
	v_mfma_f32_16x16x32_bf16 v[102:105], v[200:203], v[160:163], v[102:105]
	v_mfma_f32_16x16x32_bf16 v[94:97], v[192:195], v[168:171], v[94:97]
	v_mfma_f32_16x16x32_bf16 v[86:89], v[200:203], v[168:171], v[86:89]
	v_mfma_f32_16x16x32_bf16 v[78:81], v[192:195], v[176:179], v[78:81]
	v_mfma_f32_16x16x32_bf16 v[74:77], v[200:203], v[176:179], v[74:77]
	v_mfma_f32_16x16x32_bf16 v[70:73], v[192:195], v[184:187], v[70:73]
	v_mfma_f32_16x16x32_bf16 v[66:69], v[200:203], v[184:187], v[66:69]
	v_mfma_f32_16x16x32_bf16 v[110:113], v[196:199], v[164:167], v[110:113]
	v_mfma_f32_16x16x32_bf16 v[102:105], v[204:207], v[164:167], v[102:105]
	v_mfma_f32_16x16x32_bf16 v[94:97], v[196:199], v[172:175], v[94:97]
	v_mfma_f32_16x16x32_bf16 v[86:89], v[204:207], v[172:175], v[86:89]
	v_mfma_f32_16x16x32_bf16 v[78:81], v[196:199], v[180:183], v[78:81]
	v_mfma_f32_16x16x32_bf16 v[74:77], v[204:207], v[180:183], v[74:77]
	v_mfma_f32_16x16x32_bf16 v[70:73], v[196:199], v[188:191], v[70:73]
	v_mfma_f32_16x16x32_bf16 v[66:69], v[204:207], v[188:191], v[66:69]
	s_barrier
	s_add_i32 s38, s38, s63
	s_mov_b32 m0, s38
	ds_read_b128 v[160:163], v139 offset:16384
	global_load_lds_dwordx4 v0, s[54:55]
	s_add_i32 m0, s38, 0x2000
	ds_read_b128 v[164:167], v139 offset:17408
	global_load_lds_dwordx4 v130, s[54:55]
	s_mov_b32 m0, s25
	ds_read_b128 v[168:171], v139 offset:18432
	global_load_lds_dwordx4 v0, s[56:57]
	s_mov_b32 m0, s27
	ds_read_b128 v[172:175], v139 offset:19456
	global_load_lds_dwordx4 v130, s[56:57]
	ds_read_b128 v[176:179], v139 offset:20480
	ds_read_b128 v[180:183], v139 offset:21504
	ds_read_b128 v[184:187], v139 offset:22528
	ds_read_b128 v[188:191], v139 offset:23552
	s_waitcnt vmcnt(4)
	s_waitcnt lgkmcnt(0)
	s_barrier
	v_mfma_f32_16x16x32_bf16 v[62:65], v[140:143], v[160:163], v[62:65]
	v_mfma_f32_16x16x32_bf16 v[58:61], v[148:151], v[160:163], v[58:61]
	v_mfma_f32_16x16x32_bf16 v[54:57], v[140:143], v[168:171], v[54:57]
	v_mfma_f32_16x16x32_bf16 v[50:53], v[148:151], v[168:171], v[50:53]
	v_mfma_f32_16x16x32_bf16 v[38:41], v[140:143], v[176:179], v[38:41]
	v_mfma_f32_16x16x32_bf16 v[34:37], v[148:151], v[176:179], v[34:37]
	v_mfma_f32_16x16x32_bf16 v[22:25], v[140:143], v[184:187], v[22:25]
	v_mfma_f32_16x16x32_bf16 v[18:21], v[148:151], v[184:187], v[18:21]
	v_mfma_f32_16x16x32_bf16 v[62:65], v[144:147], v[164:167], v[62:65]
	v_mfma_f32_16x16x32_bf16 v[58:61], v[152:155], v[164:167], v[58:61]
	v_mfma_f32_16x16x32_bf16 v[54:57], v[144:147], v[172:175], v[54:57]
	v_mfma_f32_16x16x32_bf16 v[50:53], v[152:155], v[172:175], v[50:53]
	v_mfma_f32_16x16x32_bf16 v[38:41], v[144:147], v[180:183], v[38:41]
	v_mfma_f32_16x16x32_bf16 v[34:37], v[152:155], v[180:183], v[34:37]
	v_mfma_f32_16x16x32_bf16 v[22:25], v[144:147], v[188:191], v[22:25]
	v_mfma_f32_16x16x32_bf16 v[18:21], v[152:155], v[188:191], v[18:21]
	v_mfma_f32_16x16x32_bf16 v[46:49], v[192:195], v[160:163], v[46:49]
	v_mfma_f32_16x16x32_bf16 v[42:45], v[200:203], v[160:163], v[42:45]
	v_mfma_f32_16x16x32_bf16 v[30:33], v[192:195], v[168:171], v[30:33]
	v_mfma_f32_16x16x32_bf16 v[26:29], v[200:203], v[168:171], v[26:29]
	v_mfma_f32_16x16x32_bf16 v[14:17], v[192:195], v[176:179], v[14:17]
	v_mfma_f32_16x16x32_bf16 v[10:13], v[200:203], v[176:179], v[10:13]
	v_mfma_f32_16x16x32_bf16 v[6:9], v[192:195], v[184:187], v[6:9]
	v_mfma_f32_16x16x32_bf16 v[2:5], v[200:203], v[184:187], v[2:5]
	v_mfma_f32_16x16x32_bf16 v[46:49], v[196:199], v[164:167], v[46:49]
	v_mfma_f32_16x16x32_bf16 v[42:45], v[204:207], v[164:167], v[42:45]
	v_mfma_f32_16x16x32_bf16 v[30:33], v[196:199], v[172:175], v[30:33]
	v_mfma_f32_16x16x32_bf16 v[26:29], v[204:207], v[172:175], v[26:29]
	v_mfma_f32_16x16x32_bf16 v[14:17], v[196:199], v[180:183], v[14:17]
	v_mfma_f32_16x16x32_bf16 v[10:13], v[204:207], v[180:183], v[10:13]
	v_mfma_f32_16x16x32_bf16 v[6:9], v[196:199], v[188:191], v[6:9]
	v_mfma_f32_16x16x32_bf16 v[2:5], v[204:207], v[188:191], v[2:5]
	s_barrier
; #define PG8_STAGE(bufoff, gbase, voff) do { _Pragma("unroll") for (int _i = 0; _i < 2; ++_i) \
;         __builtin_amdgcn_global_load_lds((const unsigned*)((const char*)(gbase) + (voff)[_i]), (LAS unsigned*)(lds + (bufoff) + ldsw + _i * 8192), 16, 0, 0); } while (0)
; #define PG8_LDA(dst, b, h) do { _Pragma("unroll") for (int m = 0; m < 4; ++m) _Pragma("unroll") for (int k = 0; k < 2; ++k) dst[m][k] = *(const LAS bf16x8*)(lds + PG8_SA(b, h) + aoff + m * 2048 + k * 1024); } while (0)
; #define PG8_LDB(dst, b, h) do { _Pragma("unroll") for (int n = 0; n < 2; ++n) _Pragma("unroll") for (int k = 0; k < 2; ++k) dst[n][k] = *(const LAS bf16x8*)(lds + PG8_SB(b, h) + boff + n * 2048 + k * 1024); } while (0)
; #define PG8_MMA(ai, bj, At, Bt) do { __builtin_amdgcn_s_setprio(1); _Pragma("unroll") for (int m = 0; m < 4; ++m) _Pragma("unroll") for (int n = 0; n < 2; ++n) _Pragma("unroll") for (int k = 0; k < 2; ++k) \
;         acc[ai][bj][m][n] = __builtin_amdgcn_mfma_f32_16x16x32_bf16(Bt[n][k], At[m][k], acc[ai][bj][m][n], 0, 0, 0); __builtin_amdgcn_s_setprio(0); } while (0)
; #define PG8_WAIT_L(n) asm volatile("s_waitcnt lgkmcnt(" #n ")" ::: "memory")
; #define PG8_BAR __builtin_amdgcn_s_barrier()
; #define PG8_SCHED __builtin_amdgcn_sched_barrier(0)
; template <class Epi, class Sched>
; __device__ __forceinline__ void gemm_phase(LAS unsigned char* lds, const Gemm g, const Sched& S, const Epi& E) {
;     ...
;             PG8_LDB(B0, 1, 0); PG8_SCHED; PG8_LDA(At, 1, 0); PG8_STAGE(PG8_SA(0, 1), a2 + hstep, voffA);
;             PG8_WAIT_L(8); PG8_BAR; PG8_WAIT_L(0); PG8_MMA(0, 0, At, B0); PG8_BAR; PG8_SCHED;
;             PG8_LDB(B1, 1, 1); PG8_STAGE(PG8_SB(1, 0), b3, voffB);
;             PG8_BAR; PG8_WAIT_L(0); PG8_MMA(0, 1, At, B1); PG8_BAR;
;             PG8_LDA(At, 1, 1); PG8_STAGE(PG8_SA(1, 0), a3, voffA);
;             PG8_BAR; PG8_WAIT_L(0); PG8_MMA(1, 0, At, B0); PG8_BAR; PG8_SCHED;
	s_add_u32 s38, s54, 0x200000
	s_addc_u32 s39, s55, 0
	s_add_i32 s50, s50, s63
	s_mov_b32 m0, s50
	ds_read_b128 v[140:143], v226 offset:32768
	global_load_lds_dwordx4 v0, s[38:39]
	s_add_i32 m0, s50, 0x2000
	ds_read_b128 v[144:147], v226 offset:33792
	global_load_lds_dwordx4 v130, s[38:39]
	s_add_u32 s38, s56, 0x200000
	s_addc_u32 s39, s57, 0
	s_mov_b32 m0, s64
	ds_read_b128 v[148:151], v226 offset:34816
	global_load_lds_dwordx4 v0, s[38:39]
	s_mov_b32 m0, s65
	ds_read_b128 v[152:155], v226 offset:35840
	global_load_lds_dwordx4 v130, s[38:39]
	s_add_i32 s50, 0, 0x18000
	ds_read_b128 v[160:163], v139 offset:32768
	ds_read_b128 v[164:167], v139 offset:33792
	ds_read_b128 v[168:171], v139 offset:34816
	ds_read_b128 v[172:175], v139 offset:35840
	ds_read_b128 v[176:179], v139 offset:36864
	ds_read_b128 v[180:183], v139 offset:37888
	ds_read_b128 v[184:187], v139 offset:38912
	ds_read_b128 v[188:191], v139 offset:39936
	s_add_i32 s51, 0, 0x1c000
	ds_read_b128 v[192:195], v226 offset:49152
	ds_read_b128 v[196:199], v226 offset:50176
	ds_read_b128 v[200:203], v226 offset:51200
	ds_read_b128 v[204:207], v226 offset:52224
	s_waitcnt lgkmcnt(4)
	s_barrier
	s_waitcnt lgkmcnt(0)
	v_mfma_f32_16x16x32_bf16 v[126:129], v[140:143], v[160:163], v[126:129]
	v_mfma_f32_16x16x32_bf16 v[122:125], v[148:151], v[160:163], v[122:125]
	v_mfma_f32_16x16x32_bf16 v[118:121], v[140:143], v[168:171], v[118:121]
	v_mfma_f32_16x16x32_bf16 v[114:117], v[148:151], v[168:171], v[114:117]
	v_mfma_f32_16x16x32_bf16 v[106:109], v[140:143], v[176:179], v[106:109]
	v_mfma_f32_16x16x32_bf16 v[98:101], v[148:151], v[176:179], v[98:101]
	v_mfma_f32_16x16x32_bf16 v[90:93], v[140:143], v[184:187], v[90:93]
	v_mfma_f32_16x16x32_bf16 v[82:85], v[148:151], v[184:187], v[82:85]
	v_mfma_f32_16x16x32_bf16 v[126:129], v[144:147], v[164:167], v[126:129]
	v_mfma_f32_16x16x32_bf16 v[122:125], v[152:155], v[164:167], v[122:125]
	v_mfma_f32_16x16x32_bf16 v[118:121], v[144:147], v[172:175], v[118:121]
	v_mfma_f32_16x16x32_bf16 v[114:117], v[152:155], v[172:175], v[114:117]
	v_mfma_f32_16x16x32_bf16 v[106:109], v[144:147], v[180:183], v[106:109]
	v_mfma_f32_16x16x32_bf16 v[98:101], v[152:155], v[180:183], v[98:101]
	v_mfma_f32_16x16x32_bf16 v[90:93], v[144:147], v[188:191], v[90:93]
	v_mfma_f32_16x16x32_bf16 v[82:85], v[152:155], v[188:191], v[82:85]
	v_mfma_f32_16x16x32_bf16 v[110:113], v[192:195], v[160:163], v[110:113]
	v_mfma_f32_16x16x32_bf16 v[102:105], v[200:203], v[160:163], v[102:105]
	v_mfma_f32_16x16x32_bf16 v[94:97], v[192:195], v[168:171], v[94:97]
	v_mfma_f32_16x16x32_bf16 v[86:89], v[200:203], v[168:171], v[86:89]
	v_mfma_f32_16x16x32_bf16 v[78:81], v[192:195], v[176:179], v[78:81]
	v_mfma_f32_16x16x32_bf16 v[74:77], v[200:203], v[176:179], v[74:77]
	v_mfma_f32_16x16x32_bf16 v[70:73], v[192:195], v[184:187], v[70:73]
	v_mfma_f32_16x16x32_bf16 v[66:69], v[200:203], v[184:187], v[66:69]
	v_mfma_f32_16x16x32_bf16 v[110:113], v[196:199], v[164:167], v[110:113]
	v_mfma_f32_16x16x32_bf16 v[102:105], v[204:207], v[164:167], v[102:105]
	v_mfma_f32_16x16x32_bf16 v[94:97], v[196:199], v[172:175], v[94:97]
	v_mfma_f32_16x16x32_bf16 v[86:89], v[204:207], v[172:175], v[86:89]
	v_mfma_f32_16x16x32_bf16 v[78:81], v[196:199], v[180:183], v[78:81]
	v_mfma_f32_16x16x32_bf16 v[74:77], v[204:207], v[180:183], v[74:77]
	v_mfma_f32_16x16x32_bf16 v[70:73], v[196:199], v[188:191], v[70:73]
	v_mfma_f32_16x16x32_bf16 v[66:69], v[204:207], v[188:191], v[66:69]
	s_barrier
	s_add_i32 s38, s50, s63
	s_add_u32 s100, s54, s36
	s_addc_u32 s101, s55, s37
	s_mov_b32 m0, s38
	ds_read_b128 v[160:163], v139 offset:49152
	global_load_lds_dwordx4 v0, s[100:101]
	s_add_i32 m0, s38, 0x2000
	ds_read_b128 v[164:167], v139 offset:50176
	global_load_lds_dwordx4 v130, s[100:101]
	s_mov_b32 m0, s66
	s_add_u32 s100, s56, s36
	s_addc_u32 s101, s57, s37
	global_load_lds_dwordx4 v0, s[100:101]
	s_mov_b32 m0, s67
	ds_read_b128 v[168:171], v139 offset:51200
	global_load_lds_dwordx4 v130, s[100:101]
	ds_read_b128 v[172:175], v139 offset:52224
	ds_read_b128 v[176:179], v139 offset:53248
	ds_read_b128 v[180:183], v139 offset:54272
	ds_read_b128 v[184:187], v139 offset:55296
	ds_read_b128 v[188:191], v139 offset:56320
	s_waitcnt vmcnt(4)
	s_waitcnt lgkmcnt(0)
	s_barrier
; #define PG8_STAGE(bufoff, gbase, voff) do { _Pragma("unroll") for (int _i = 0; _i < 2; ++_i) \
;         __builtin_amdgcn_global_load_lds((const unsigned*)((const char*)(gbase) + (voff)[_i]), (LAS unsigned*)(lds + (bufoff) + ldsw + _i * 8192), 16, 0, 0); } while (0)
; #define PG8_MMA(ai, bj, At, Bt) do { __builtin_amdgcn_s_setprio(1); _Pragma("unroll") for (int m = 0; m < 4; ++m) _Pragma("unroll") for (int n = 0; n < 2; ++n) _Pragma("unroll") for (int k = 0; k < 2; ++k) \
;         acc[ai][bj][m][n] = __builtin_amdgcn_mfma_f32_16x16x32_bf16(Bt[n][k], At[m][k], acc[ai][bj][m][n], 0, 0, 0); __builtin_amdgcn_s_setprio(0); } while (0)
; #define PG8_WAIT_V(n) asm volatile("s_waitcnt vmcnt(" #n ")" ::: "memory")
; #define PG8_BAR __builtin_amdgcn_s_barrier()
;     __device__ __forceinline__ void operator()(const f32x4 (&acc)[2][2][4][2], const Unit& u, int wr, int wc, int fr, int fq) const {
;         const int row0 = u.pm * BM + wr * 64 + fr, col0 = u.pn * BM + wc * 32 + 4 * fq;
;         float* base = part + (size_t)u.ks * Mp * ldc;
; #pragma unroll
;         for (int ai = 0; ai < 2; ++ai)
; #pragma unroll
;             for (int m = 0; m < 4; ++m) { float* rowp = base + (size_t)(row0 + ai * HALF + m * 16) * ldc + col0;
; #pragma unroll
;                 for (int bj = 0; bj < 2; ++bj)
; #pragma unroll
;                     for (int n = 0; n < 2; ++n) *(f32x4*)(rowp + bj * HALF + n * 16) = acc[ai][bj][m][n]; }
;     }
; template <class Epi, class Sched>
; __device__ __forceinline__ void gemm_phase(LAS unsigned char* lds, const Gemm g, const Sched& S, const Epi& E) {
;     ...
;             PG8_STAGE(PG8_SB(1, 1), b3 + hstep, voffB);
;             PG8_WAIT_V(6); PG8_BAR; PG8_MMA(1, 1, At, B1); PG8_BAR;
;         }
;         E(acc, cur, wr, wc, fr, fq);
;         if (!has_next) break;
	v_mfma_f32_16x16x32_bf16 v[62:65], v[140:143], v[160:163], v[62:65]
	v_mfma_f32_16x16x32_bf16 v[58:61], v[148:151], v[160:163], v[58:61]
	v_mfma_f32_16x16x32_bf16 v[54:57], v[140:143], v[168:171], v[54:57]
	v_mfma_f32_16x16x32_bf16 v[50:53], v[148:151], v[168:171], v[50:53]
	v_mfma_f32_16x16x32_bf16 v[38:41], v[140:143], v[176:179], v[38:41]
	v_mfma_f32_16x16x32_bf16 v[34:37], v[148:151], v[176:179], v[34:37]
	v_mfma_f32_16x16x32_bf16 v[22:25], v[140:143], v[184:187], v[22:25]
	v_mfma_f32_16x16x32_bf16 v[18:21], v[148:151], v[184:187], v[18:21]
	v_mfma_f32_16x16x32_bf16 v[62:65], v[144:147], v[164:167], v[62:65]
	v_mfma_f32_16x16x32_bf16 v[58:61], v[152:155], v[164:167], v[58:61]
	v_mfma_f32_16x16x32_bf16 v[54:57], v[144:147], v[172:175], v[54:57]
	v_mfma_f32_16x16x32_bf16 v[50:53], v[152:155], v[172:175], v[50:53]
	v_mfma_f32_16x16x32_bf16 v[38:41], v[144:147], v[180:183], v[38:41]
	v_mfma_f32_16x16x32_bf16 v[34:37], v[152:155], v[180:183], v[34:37]
	v_mfma_f32_16x16x32_bf16 v[22:25], v[144:147], v[188:191], v[22:25]
	v_mfma_f32_16x16x32_bf16 v[18:21], v[152:155], v[188:191], v[18:21]
	s_add_u32 s38, s54, 0x200080
	s_addc_u32 s39, s55, 0
	s_add_i32 s50, s51, s63
	s_mov_b32 m0, s50
	s_nop 0
	global_load_lds_dwordx4 v0, s[38:39]
	s_add_i32 m0, s50, 0x2000
	s_nop 0
	global_load_lds_dwordx4 v130, s[38:39]
	v_mfma_f32_16x16x32_bf16 v[46:49], v[192:195], v[160:163], v[46:49]
	v_mfma_f32_16x16x32_bf16 v[42:45], v[200:203], v[160:163], v[42:45]
	v_mfma_f32_16x16x32_bf16 v[30:33], v[192:195], v[168:171], v[30:33]
	v_mfma_f32_16x16x32_bf16 v[26:29], v[200:203], v[168:171], v[26:29]
	v_mfma_f32_16x16x32_bf16 v[14:17], v[192:195], v[176:179], v[14:17]
	v_mfma_f32_16x16x32_bf16 v[10:13], v[200:203], v[176:179], v[10:13]
	v_mfma_f32_16x16x32_bf16 v[6:9], v[192:195], v[184:187], v[6:9]
	v_mfma_f32_16x16x32_bf16 v[2:5], v[200:203], v[184:187], v[2:5]
	v_mfma_f32_16x16x32_bf16 v[46:49], v[196:199], v[164:167], v[46:49]
	v_mfma_f32_16x16x32_bf16 v[42:45], v[204:207], v[164:167], v[42:45]
	v_mfma_f32_16x16x32_bf16 v[30:33], v[196:199], v[172:175], v[30:33]
	v_mfma_f32_16x16x32_bf16 v[26:29], v[204:207], v[172:175], v[26:29]
	v_mfma_f32_16x16x32_bf16 v[14:17], v[196:199], v[180:183], v[14:17]
	v_mfma_f32_16x16x32_bf16 v[10:13], v[204:207], v[180:183], v[10:13]
	v_mfma_f32_16x16x32_bf16 v[6:9], v[196:199], v[188:191], v[6:9]
	v_mfma_f32_16x16x32_bf16 v[2:5], v[204:207], v[188:191], v[2:5]
	s_add_i32 s71, s71, 2
	s_add_u32 s69, s69, 0x100
	s_addc_u32 s70, s70, 0
	s_cmp_gt_u32 s71, 29
	s_mov_b64 s[50:51], s[52:53]
	s_barrier
	s_cbranch_scc0 .LBB0_58
	s_ashr_i32 s11, s10, 31
	s_lshl_b64 s[10:11], s[10:11], 24
	v_lshl_or_b32 v140, s26, 8, v138
	s_add_u32 s10, s8, s10
	v_lshl_add_u32 v142, s24, 8, v136
	s_addc_u32 s11, s9, s11
	v_ashrrev_i32_e32 v141, 31, v140
	v_ashrrev_i32_e32 v143, 31, v142
	v_lshl_add_u64 v[140:141], v[140:141], 2, s[10:11]
	v_lshlrev_b64 v[144:145], 13, v[142:143]
	v_lshl_add_u64 v[144:145], v[140:141], 0, v[144:145]
	global_store_dwordx4 v[144:145], v[126:129], off
	global_store_dwordx4 v[144:145], v[122:125], off offset:64
	global_store_dwordx4 v[144:145], v[110:113], off offset:512
	global_store_dwordx4 v[144:145], v[102:105], off offset:576
	s_mov_b64 s[10:11], 0x100000
	s_mov_b32 s26, s40
	v_or_b32_e32 v102, 16, v142
	v_ashrrev_i32_e32 v103, 31, v102
	v_lshlrev_b64 v[102:103], 13, v[102:103]
	v_lshl_add_u64 v[102:103], v[140:141], 0, v[102:103]
	global_store_dwordx4 v[102:103], v[118:121], off
	global_store_dwordx4 v[102:103], v[114:117], off offset:64
	global_store_dwordx4 v[102:103], v[94:97], off offset:512
	global_store_dwordx4 v[102:103], v[86:89], off offset:576
	s_mov_b32 s24, s42
	s_mov_b64 s[52:53], s[48:49]
	v_or_b32_e32 v86, 32, v142
	v_ashrrev_i32_e32 v87, 31, v86
	v_lshlrev_b64 v[86:87], 13, v[86:87]
	v_lshl_add_u64 v[86:87], v[140:141], 0, v[86:87]
	global_store_dwordx4 v[86:87], v[106:109], off
	global_store_dwordx4 v[86:87], v[98:101], off offset:64
	global_store_dwordx4 v[86:87], v[78:81], off offset:512
	global_store_dwordx4 v[86:87], v[74:77], off offset:576
	s_mov_b64 s[50:51], s[46:47]
	s_nop 0
	v_or_b32_e32 v74, 48, v142
	v_ashrrev_i32_e32 v75, 31, v74
	v_lshlrev_b64 v[74:75], 13, v[74:75]
	v_lshl_add_u64 v[74:75], v[140:141], 0, v[74:75]
	global_store_dwordx4 v[74:75], v[90:93], off
	global_store_dwordx4 v[74:75], v[82:85], off offset:64
	global_store_dwordx4 v[74:75], v[70:73], off offset:512
	global_store_dwordx4 v[74:75], v[66:69], off offset:576
	s_nop 1
	v_add_co_u32_e32 v68, vcc, s93, v144
	v_lshl_add_u64 v[66:67], v[144:145], 0, s[10:11]
	s_nop 0
	v_addc_co_u32_e32 v69, vcc, 0, v145, vcc
	s_mov_b64 s[10:11], 0x120000
	global_store_dwordx4 v[68:69], v[62:65], off
	global_store_dwordx4 v[66:67], v[58:61], off offset:64
	global_store_dwordx4 v[66:67], v[46:49], off offset:512
	global_store_dwordx4 v[66:67], v[42:45], off offset:576
	s_nop 1
	v_lshl_add_u64 v[42:43], v[144:145], 0, s[10:11]
	s_mov_b32 s10, 0x120000
	v_add_co_u32_e32 v44, vcc, s10, v144
	s_mov_b64 s[10:11], 0x140000
	s_nop 0
	v_addc_co_u32_e32 v45, vcc, 0, v145, vcc
	global_store_dwordx4 v[44:45], v[54:57], off
	global_store_dwordx4 v[42:43], v[50:53], off offset:64
	global_store_dwordx4 v[42:43], v[30:33], off offset:512
	global_store_dwordx4 v[42:43], v[26:29], off offset:576
	s_nop 1
	v_lshl_add_u64 v[26:27], v[144:145], 0, s[10:11]
	s_mov_b32 s10, 0x140000
	v_add_co_u32_e32 v28, vcc, s10, v144
	s_mov_b64 s[10:11], 0x160000
	s_nop 0
	v_addc_co_u32_e32 v29, vcc, 0, v145, vcc
	global_store_dwordx4 v[28:29], v[38:41], off
	global_store_dwordx4 v[26:27], v[34:37], off offset:64
	global_store_dwordx4 v[26:27], v[14:17], off offset:512
	global_store_dwordx4 v[26:27], v[10:13], off offset:576
	s_nop 1
	v_add_co_u32_e32 v12, vcc, 0x160000, v144
	v_lshl_add_u64 v[10:11], v[144:145], 0, s[10:11]
	s_nop 0
	v_addc_co_u32_e32 v13, vcc, 0, v145, vcc
	s_and_b64 vcc, exec, s[44:45]
	s_mov_b32 s10, s28
	global_store_dwordx4 v[12:13], v[22:25], off
	global_store_dwordx4 v[10:11], v[18:21], off offset:64
	global_store_dwordx4 v[10:11], v[6:9], off offset:512
	global_store_dwordx4 v[10:11], v[2:5], off offset:576
	s_cbranch_vccz .LBB0_55
	s_waitcnt vmcnt(0)
	s_cmpk_gt_u32 s60, 0xff
	s_cbranch_scc1 .LBB0_62
	s_barrier

; #define PG8_STAGE(bufoff, gbase, voff) do { _Pragma("unroll") for (int _i = 0; _i < 2; ++_i) \
;         __builtin_amdgcn_global_load_lds((const unsigned*)((const char*)(gbase) + (voff)[_i]), (LAS unsigned*)(lds + (bufoff) + ldsw + _i * 8192), 16, 0, 0); } while (0)
; #define PG8_LDA(dst, b, h) do { _Pragma("unroll") for (int m = 0; m < 4; ++m) _Pragma("unroll") for (int k = 0; k < 2; ++k) dst[m][k] = *(const LAS bf16x8*)(lds + PG8_SA(b, h) + aoff + m * 2048 + k * 1024); } while (0)
; #define PG8_LDB(dst, b, h) do { _Pragma("unroll") for (int n = 0; n < 2; ++n) _Pragma("unroll") for (int k = 0; k < 2; ++k) dst[n][k] = *(const LAS bf16x8*)(lds + PG8_SB(b, h) + boff + n * 2048 + k * 1024); } while (0)
; #define PG8_MMA(ai, bj, At, Bt) do { __builtin_amdgcn_s_setprio(1); _Pragma("unroll") for (int m = 0; m < 4; ++m) _Pragma("unroll") for (int n = 0; n < 2; ++n) _Pragma("unroll") for (int k = 0; k < 2; ++k) \
;         acc[ai][bj][m][n] = __builtin_amdgcn_mfma_f32_16x16x32_bf16(Bt[n][k], At[m][k], acc[ai][bj][m][n], 0, 0, 0); __builtin_amdgcn_s_setprio(0); } while (0)
; #define PG8_WAIT_V(n) asm volatile("s_waitcnt vmcnt(" #n ")" ::: "memory")
; #define PG8_WAIT_L(n) asm volatile("s_waitcnt lgkmcnt(" #n ")" ::: "memory")
; template <class Epi, class Sched>
; __device__ __forceinline__ void gemm_phase(LAS unsigned char* lds, const Gemm g, const Sched& S, const Epi& E) {
;     ...
;         for (int t = 0; t < nt; t += 2) {
;             const bool last = (t == nt - 2);
;             const char* a1 = cA + (size_t)(t + 1) * kstep;
;             const char* a2 = last ? nA : cA + (size_t)(t + 2) * kstep; const char* b2 = last ? nB : cB + (size_t)(t + 2) * kstep;
;             const char* a3 = a2 + kstep; const char* b3 = b2 + kstep;
;             PG8_LDB(B0, 0, 0); PG8_SCHED; PG8_LDA(At, 0, 0); PG8_STAGE(PG8_SA(1, 1), a1 + hstep, voffA);
;             PG8_WAIT_L(8); PG8_BAR; PG8_WAIT_L(0); PG8_MMA(0, 0, At, B0); PG8_BAR; PG8_SCHED;
;             PG8_LDB(B1, 0, 1); PG8_STAGE(PG8_SB(0, 0), b2, voffB);
;             PG8_BAR; PG8_WAIT_L(0); PG8_MMA(0, 1, At, B1); PG8_BAR;
;             PG8_LDA(At, 0, 1); PG8_STAGE(PG8_SA(0, 0), a2, voffA);
;             PG8_BAR; PG8_WAIT_L(0); PG8_MMA(1, 0, At, B0); PG8_BAR; PG8_SCHED;
;             PG8_STAGE(PG8_SB(0, 1), b2 + hstep, voffB);
;             PG8_WAIT_V(6); PG8_BAR; PG8_MMA(1, 1, At, B1); PG8_BAR;
.LBB0_73:
	s_add_u32 s38, s46, 0xfff80080
	s_addc_u32 s39, s47, -1
	s_cmp_eq_u32 s73, 28
	s_cselect_b32 s51, s29, s39
	s_cselect_b32 s50, s69, s38
	s_cselect_b32 s49, s27, s72
	s_cselect_b32 s48, s70, s71
	s_add_i32 m0, s9, 0xc000
	ds_read_b128 v[146:149], v226
	global_load_lds_dwordx4 v138, s[46:47]
	s_add_i32 m0, s9, 0xe000
	ds_read_b128 v[150:153], v226 offset:1024
	global_load_lds_dwordx4 v136, s[46:47]
	s_add_i32 s74, 0, 0x10000
	ds_read_b128 v[154:157], v226 offset:2048
	ds_read_b128 v[160:163], v226 offset:3072
	ds_read_b128 v[164:167], v145
	ds_read_b128 v[168:171], v145 offset:1024
	ds_read_b128 v[172:175], v145 offset:2048
	ds_read_b128 v[176:179], v145 offset:3072
	ds_read_b128 v[180:183], v145 offset:4096
	ds_read_b128 v[184:187], v145 offset:5120
	ds_read_b128 v[188:191], v145 offset:6144
	ds_read_b128 v[192:195], v145 offset:7168
	s_add_i32 s75, 0, 0x14000
	ds_read_b128 v[196:199], v226 offset:16384
	ds_read_b128 v[200:203], v226 offset:17408
	ds_read_b128 v[204:207], v226 offset:18432
	ds_read_b128 v[210:213], v226 offset:19456
	s_waitcnt lgkmcnt(4)
	s_barrier
	s_waitcnt lgkmcnt(0)
	v_mfma_f32_16x16x32_bf16 v[126:129], v[146:149], v[164:167], v[126:129]
	v_mfma_f32_16x16x32_bf16 v[122:125], v[154:157], v[164:167], v[122:125]
	v_mfma_f32_16x16x32_bf16 v[110:113], v[146:149], v[172:175], v[110:113]
	v_mfma_f32_16x16x32_bf16 v[106:109], v[154:157], v[172:175], v[106:109]
	v_mfma_f32_16x16x32_bf16 v[94:97], v[146:149], v[180:183], v[94:97]
	v_mfma_f32_16x16x32_bf16 v[90:93], v[154:157], v[180:183], v[90:93]
	v_mfma_f32_16x16x32_bf16 v[78:81], v[146:149], v[188:191], v[78:81]
	v_mfma_f32_16x16x32_bf16 v[74:77], v[154:157], v[188:191], v[74:77]
	v_mfma_f32_16x16x32_bf16 v[126:129], v[150:153], v[168:171], v[126:129]
	v_mfma_f32_16x16x32_bf16 v[122:125], v[160:163], v[168:171], v[122:125]
	v_mfma_f32_16x16x32_bf16 v[110:113], v[150:153], v[176:179], v[110:113]
	v_mfma_f32_16x16x32_bf16 v[106:109], v[160:163], v[176:179], v[106:109]
	v_mfma_f32_16x16x32_bf16 v[94:97], v[150:153], v[184:187], v[94:97]
	v_mfma_f32_16x16x32_bf16 v[90:93], v[160:163], v[184:187], v[90:93]
	v_mfma_f32_16x16x32_bf16 v[78:81], v[150:153], v[192:195], v[78:81]
	v_mfma_f32_16x16x32_bf16 v[74:77], v[160:163], v[192:195], v[74:77]
	v_mfma_f32_16x16x32_bf16 v[118:121], v[196:199], v[164:167], v[118:121]
	v_mfma_f32_16x16x32_bf16 v[114:117], v[204:207], v[164:167], v[114:117]
	v_mfma_f32_16x16x32_bf16 v[102:105], v[196:199], v[172:175], v[102:105]
	v_mfma_f32_16x16x32_bf16 v[98:101], v[204:207], v[172:175], v[98:101]
	v_mfma_f32_16x16x32_bf16 v[86:89], v[196:199], v[180:183], v[86:89]
	v_mfma_f32_16x16x32_bf16 v[82:85], v[204:207], v[180:183], v[82:85]
	v_mfma_f32_16x16x32_bf16 v[70:73], v[196:199], v[188:191], v[70:73]
	v_mfma_f32_16x16x32_bf16 v[66:69], v[204:207], v[188:191], v[66:69]
	v_mfma_f32_16x16x32_bf16 v[118:121], v[200:203], v[168:171], v[118:121]
	v_mfma_f32_16x16x32_bf16 v[114:117], v[210:213], v[168:171], v[114:117]
	v_mfma_f32_16x16x32_bf16 v[102:105], v[200:203], v[176:179], v[102:105]
	v_mfma_f32_16x16x32_bf16 v[98:101], v[210:213], v[176:179], v[98:101]
	v_mfma_f32_16x16x32_bf16 v[86:89], v[200:203], v[184:187], v[86:89]
	v_mfma_f32_16x16x32_bf16 v[82:85], v[210:213], v[184:187], v[82:85]
	v_mfma_f32_16x16x32_bf16 v[70:73], v[200:203], v[192:195], v[70:73]
	v_mfma_f32_16x16x32_bf16 v[66:69], v[210:213], v[192:195], v[66:69]
	s_barrier
	s_add_i32 s38, s74, s56
	s_mov_b32 m0, s38
	ds_read_b128 v[164:167], v145 offset:16384
	global_load_lds_dwordx4 v0, s[48:49]
	s_add_i32 m0, s38, 0x2000
	ds_read_b128 v[168:171], v145 offset:17408
	global_load_lds_dwordx4 v130, s[48:49]
	s_mov_b32 m0, s9
	ds_read_b128 v[172:175], v145 offset:18432
	global_load_lds_dwordx4 v134, s[50:51]
	s_mov_b32 m0, s60
	ds_read_b128 v[176:179], v145 offset:19456
	global_load_lds_dwordx4 v132, s[50:51]
	ds_read_b128 v[180:183], v145 offset:20480
	ds_read_b128 v[184:187], v145 offset:21504
	ds_read_b128 v[188:191], v145 offset:22528
	ds_read_b128 v[192:195], v145 offset:23552
	s_waitcnt vmcnt(4)
	s_waitcnt lgkmcnt(0)
	s_barrier
	v_mfma_f32_16x16x32_bf16 v[62:65], v[146:149], v[164:167], v[62:65]
	v_mfma_f32_16x16x32_bf16 v[58:61], v[154:157], v[164:167], v[58:61]
	v_mfma_f32_16x16x32_bf16 v[46:49], v[146:149], v[172:175], v[46:49]
	v_mfma_f32_16x16x32_bf16 v[42:45], v[154:157], v[172:175], v[42:45]
	v_mfma_f32_16x16x32_bf16 v[30:33], v[146:149], v[180:183], v[30:33]
	v_mfma_f32_16x16x32_bf16 v[26:29], v[154:157], v[180:183], v[26:29]
	v_mfma_f32_16x16x32_bf16 v[14:17], v[146:149], v[188:191], v[14:17]
	v_mfma_f32_16x16x32_bf16 v[10:13], v[154:157], v[188:191], v[10:13]
	v_mfma_f32_16x16x32_bf16 v[62:65], v[150:153], v[168:171], v[62:65]
	v_mfma_f32_16x16x32_bf16 v[58:61], v[160:163], v[168:171], v[58:61]
	v_mfma_f32_16x16x32_bf16 v[46:49], v[150:153], v[176:179], v[46:49]
	v_mfma_f32_16x16x32_bf16 v[42:45], v[160:163], v[176:179], v[42:45]
	v_mfma_f32_16x16x32_bf16 v[30:33], v[150:153], v[184:187], v[30:33]
	v_mfma_f32_16x16x32_bf16 v[26:29], v[160:163], v[184:187], v[26:29]
	v_mfma_f32_16x16x32_bf16 v[14:17], v[150:153], v[192:195], v[14:17]
	v_mfma_f32_16x16x32_bf16 v[10:13], v[160:163], v[192:195], v[10:13]
	v_mfma_f32_16x16x32_bf16 v[54:57], v[196:199], v[164:167], v[54:57]
	v_mfma_f32_16x16x32_bf16 v[50:53], v[204:207], v[164:167], v[50:53]
	v_mfma_f32_16x16x32_bf16 v[38:41], v[196:199], v[172:175], v[38:41]
	v_mfma_f32_16x16x32_bf16 v[34:37], v[204:207], v[172:175], v[34:37]
	v_mfma_f32_16x16x32_bf16 v[22:25], v[196:199], v[180:183], v[22:25]
	v_mfma_f32_16x16x32_bf16 v[18:21], v[204:207], v[180:183], v[18:21]
	v_mfma_f32_16x16x32_bf16 v[6:9], v[196:199], v[188:191], v[6:9]
	v_mfma_f32_16x16x32_bf16 v[2:5], v[204:207], v[188:191], v[2:5]
	v_mfma_f32_16x16x32_bf16 v[54:57], v[200:203], v[168:171], v[54:57]
	v_mfma_f32_16x16x32_bf16 v[50:53], v[210:213], v[168:171], v[50:53]
	v_mfma_f32_16x16x32_bf16 v[38:41], v[200:203], v[176:179], v[38:41]
	v_mfma_f32_16x16x32_bf16 v[34:37], v[210:213], v[176:179], v[34:37]
	v_mfma_f32_16x16x32_bf16 v[22:25], v[200:203], v[184:187], v[22:25]
	v_mfma_f32_16x16x32_bf16 v[18:21], v[210:213], v[184:187], v[18:21]
	v_mfma_f32_16x16x32_bf16 v[6:9], v[200:203], v[192:195], v[6:9]
	v_mfma_f32_16x16x32_bf16 v[2:5], v[210:213], v[192:195], v[2:5]
	s_barrier
; #define PG8_STAGE(bufoff, gbase, voff) do { _Pragma("unroll") for (int _i = 0; _i < 2; ++_i) \
;         __builtin_amdgcn_global_load_lds((const unsigned*)((const char*)(gbase) + (voff)[_i]), (LAS unsigned*)(lds + (bufoff) + ldsw + _i * 8192), 16, 0, 0); } while (0)
; #define PG8_LDA(dst, b, h) do { _Pragma("unroll") for (int m = 0; m < 4; ++m) _Pragma("unroll") for (int k = 0; k < 2; ++k) dst[m][k] = *(const LAS bf16x8*)(lds + PG8_SA(b, h) + aoff + m * 2048 + k * 1024); } while (0)
; #define PG8_LDB(dst, b, h) do { _Pragma("unroll") for (int n = 0; n < 2; ++n) _Pragma("unroll") for (int k = 0; k < 2; ++k) dst[n][k] = *(const LAS bf16x8*)(lds + PG8_SB(b, h) + boff + n * 2048 + k * 1024); } while (0)
; #define PG8_MMA(ai, bj, At, Bt) do { __builtin_amdgcn_s_setprio(1); _Pragma("unroll") for (int m = 0; m < 4; ++m) _Pragma("unroll") for (int n = 0; n < 2; ++n) _Pragma("unroll") for (int k = 0; k < 2; ++k) \
;         acc[ai][bj][m][n] = __builtin_amdgcn_mfma_f32_16x16x32_bf16(Bt[n][k], At[m][k], acc[ai][bj][m][n], 0, 0, 0); __builtin_amdgcn_s_setprio(0); } while (0)
; #define PG8_WAIT_V(n) asm volatile("s_waitcnt vmcnt(" #n ")" ::: "memory")
; #define PG8_WAIT_L(n) asm volatile("s_waitcnt lgkmcnt(" #n ")" ::: "memory")
; #define PG8_BAR __builtin_amdgcn_s_barrier()
; #define PG8_SCHED __builtin_amdgcn_sched_barrier(0)
; template <class Epi, class Sched>
; __device__ __forceinline__ void gemm_phase(LAS unsigned char* lds, const Gemm g, const Sched& S, const Epi& E) {
;     ...
;             PG8_LDB(B0, 1, 0); PG8_SCHED; PG8_LDA(At, 1, 0); PG8_STAGE(PG8_SA(0, 1), a2 + hstep, voffA);
;             PG8_WAIT_L(8); PG8_BAR; PG8_WAIT_L(0); PG8_MMA(0, 0, At, B0); PG8_BAR; PG8_SCHED;
;             PG8_LDB(B1, 1, 1); PG8_STAGE(PG8_SB(1, 0), b3, voffB);
;             PG8_BAR; PG8_WAIT_L(0); PG8_MMA(0, 1, At, B1); PG8_BAR;
;             PG8_LDA(At, 1, 1); PG8_STAGE(PG8_SA(1, 0), a3, voffA);
;             PG8_BAR; PG8_WAIT_L(0); PG8_MMA(1, 0, At, B0); PG8_BAR; PG8_SCHED;
;             PG8_STAGE(PG8_SB(1, 1), b3 + hstep, voffB);
;             PG8_WAIT_V(6); PG8_BAR; PG8_MMA(1, 1, At, B1); PG8_BAR;
;         }
	s_add_u32 s38, s48, 0x80000
	s_addc_u32 s39, s49, 0
	s_add_i32 s74, s75, s56
	s_mov_b32 m0, s74
	ds_read_b128 v[146:149], v226 offset:32768
	global_load_lds_dwordx4 v0, s[38:39]
	s_add_i32 m0, s74, 0x2000
	ds_read_b128 v[150:153], v226 offset:33792
	global_load_lds_dwordx4 v130, s[38:39]
	s_add_u32 s38, s50, 0x80000
	s_addc_u32 s39, s51, 0
	s_mov_b32 m0, s61
	ds_read_b128 v[154:157], v226 offset:34816
	global_load_lds_dwordx4 v134, s[38:39]
	s_mov_b32 m0, s62
	ds_read_b128 v[160:163], v226 offset:35840
	global_load_lds_dwordx4 v132, s[38:39]
	s_add_i32 s74, 0, 0x18000
	ds_read_b128 v[164:167], v145 offset:32768
	ds_read_b128 v[168:171], v145 offset:33792
	ds_read_b128 v[172:175], v145 offset:34816
	ds_read_b128 v[176:179], v145 offset:35840
	ds_read_b128 v[180:183], v145 offset:36864
	ds_read_b128 v[184:187], v145 offset:37888
	ds_read_b128 v[188:191], v145 offset:38912
	ds_read_b128 v[192:195], v145 offset:39936
	s_nop 0
	ds_read_b128 v[196:199], v226 offset:49152
	ds_read_b128 v[200:203], v226 offset:50176
	ds_read_b128 v[204:207], v226 offset:51200
	ds_read_b128 v[210:213], v226 offset:52224
	s_waitcnt lgkmcnt(4)
	s_barrier
	s_waitcnt lgkmcnt(0)
	v_mfma_f32_16x16x32_bf16 v[126:129], v[146:149], v[164:167], v[126:129]
	v_mfma_f32_16x16x32_bf16 v[122:125], v[154:157], v[164:167], v[122:125]
	v_mfma_f32_16x16x32_bf16 v[110:113], v[146:149], v[172:175], v[110:113]
	v_mfma_f32_16x16x32_bf16 v[106:109], v[154:157], v[172:175], v[106:109]
	v_mfma_f32_16x16x32_bf16 v[94:97], v[146:149], v[180:183], v[94:97]
	v_mfma_f32_16x16x32_bf16 v[90:93], v[154:157], v[180:183], v[90:93]
	v_mfma_f32_16x16x32_bf16 v[78:81], v[146:149], v[188:191], v[78:81]
	v_mfma_f32_16x16x32_bf16 v[74:77], v[154:157], v[188:191], v[74:77]
	v_mfma_f32_16x16x32_bf16 v[126:129], v[150:153], v[168:171], v[126:129]
	v_mfma_f32_16x16x32_bf16 v[122:125], v[160:163], v[168:171], v[122:125]
	v_mfma_f32_16x16x32_bf16 v[110:113], v[150:153], v[176:179], v[110:113]
	v_mfma_f32_16x16x32_bf16 v[106:109], v[160:163], v[176:179], v[106:109]
	v_mfma_f32_16x16x32_bf16 v[94:97], v[150:153], v[184:187], v[94:97]
	v_mfma_f32_16x16x32_bf16 v[90:93], v[160:163], v[184:187], v[90:93]
	v_mfma_f32_16x16x32_bf16 v[78:81], v[150:153], v[192:195], v[78:81]
	v_mfma_f32_16x16x32_bf16 v[74:77], v[160:163], v[192:195], v[74:77]
	v_mfma_f32_16x16x32_bf16 v[118:121], v[196:199], v[164:167], v[118:121]
	v_mfma_f32_16x16x32_bf16 v[114:117], v[204:207], v[164:167], v[114:117]
	v_mfma_f32_16x16x32_bf16 v[102:105], v[196:199], v[172:175], v[102:105]
	v_mfma_f32_16x16x32_bf16 v[98:101], v[204:207], v[172:175], v[98:101]
	v_mfma_f32_16x16x32_bf16 v[86:89], v[196:199], v[180:183], v[86:89]
	v_mfma_f32_16x16x32_bf16 v[82:85], v[204:207], v[180:183], v[82:85]
	v_mfma_f32_16x16x32_bf16 v[70:73], v[196:199], v[188:191], v[70:73]
	v_mfma_f32_16x16x32_bf16 v[66:69], v[204:207], v[188:191], v[66:69]
	v_mfma_f32_16x16x32_bf16 v[118:121], v[200:203], v[168:171], v[118:121]
	v_mfma_f32_16x16x32_bf16 v[114:117], v[210:213], v[168:171], v[114:117]
	v_mfma_f32_16x16x32_bf16 v[102:105], v[200:203], v[176:179], v[102:105]
	v_mfma_f32_16x16x32_bf16 v[98:101], v[210:213], v[176:179], v[98:101]
	v_mfma_f32_16x16x32_bf16 v[86:89], v[200:203], v[184:187], v[86:89]
	v_mfma_f32_16x16x32_bf16 v[82:85], v[210:213], v[184:187], v[82:85]
	v_mfma_f32_16x16x32_bf16 v[70:73], v[200:203], v[192:195], v[70:73]
	v_mfma_f32_16x16x32_bf16 v[66:69], v[210:213], v[192:195], v[66:69]
	s_barrier
	s_add_i32 s38, s74, s56
	s_add_u32 s100, s48, s36
	s_addc_u32 s101, s49, s37
	s_mov_b32 m0, s38
	ds_read_b128 v[164:167], v145 offset:49152
	global_load_lds_dwordx4 v0, s[100:101]
	s_add_i32 m0, s38, 0x2000
	ds_read_b128 v[168:171], v145 offset:50176
	global_load_lds_dwordx4 v130, s[100:101]
	s_mov_b32 m0, s64
	s_add_u32 s100, s50, s36
	s_addc_u32 s101, s51, s37
	global_load_lds_dwordx4 v134, s[100:101]
	s_mov_b32 m0, s65
	ds_read_b128 v[172:175], v145 offset:51200
	global_load_lds_dwordx4 v132, s[100:101]
	ds_read_b128 v[176:179], v145 offset:52224
	ds_read_b128 v[180:183], v145 offset:53248
	ds_read_b128 v[184:187], v145 offset:54272
	ds_read_b128 v[188:191], v145 offset:55296
	ds_read_b128 v[192:195], v145 offset:56320
	s_waitcnt vmcnt(4)
	s_waitcnt lgkmcnt(0)
	s_barrier
	v_mfma_f32_16x16x32_bf16 v[62:65], v[146:149], v[164:167], v[62:65]
	v_mfma_f32_16x16x32_bf16 v[58:61], v[154:157], v[164:167], v[58:61]
	v_mfma_f32_16x16x32_bf16 v[46:49], v[146:149], v[172:175], v[46:49]
	v_mfma_f32_16x16x32_bf16 v[42:45], v[154:157], v[172:175], v[42:45]
	v_mfma_f32_16x16x32_bf16 v[30:33], v[146:149], v[180:183], v[30:33]
	v_mfma_f32_16x16x32_bf16 v[26:29], v[154:157], v[180:183], v[26:29]
	v_mfma_f32_16x16x32_bf16 v[14:17], v[146:149], v[188:191], v[14:17]
	v_mfma_f32_16x16x32_bf16 v[10:13], v[154:157], v[188:191], v[10:13]
	v_mfma_f32_16x16x32_bf16 v[62:65], v[150:153], v[168:171], v[62:65]
	v_mfma_f32_16x16x32_bf16 v[58:61], v[160:163], v[168:171], v[58:61]
	v_mfma_f32_16x16x32_bf16 v[46:49], v[150:153], v[176:179], v[46:49]
	v_mfma_f32_16x16x32_bf16 v[42:45], v[160:163], v[176:179], v[42:45]
	v_mfma_f32_16x16x32_bf16 v[30:33], v[150:153], v[184:187], v[30:33]
	v_mfma_f32_16x16x32_bf16 v[26:29], v[160:163], v[184:187], v[26:29]
	v_mfma_f32_16x16x32_bf16 v[14:17], v[150:153], v[192:195], v[14:17]
	v_mfma_f32_16x16x32_bf16 v[10:13], v[160:163], v[192:195], v[10:13]
	s_add_u32 s38, s48, 0x80080
	s_addc_u32 s39, s49, 0
	s_add_i32 s48, s56, 0x1c000
	s_mov_b32 m0, s48
	s_nop 0
	global_load_lds_dwordx4 v0, s[38:39]
	s_add_i32 m0, s48, 0x2000
	s_nop 0
	global_load_lds_dwordx4 v130, s[38:39]
	v_mfma_f32_16x16x32_bf16 v[54:57], v[196:199], v[164:167], v[54:57]
	v_mfma_f32_16x16x32_bf16 v[50:53], v[204:207], v[164:167], v[50:53]
	v_mfma_f32_16x16x32_bf16 v[38:41], v[196:199], v[172:175], v[38:41]
	v_mfma_f32_16x16x32_bf16 v[34:37], v[204:207], v[172:175], v[34:37]
	v_mfma_f32_16x16x32_bf16 v[22:25], v[196:199], v[180:183], v[22:25]
	v_mfma_f32_16x16x32_bf16 v[18:21], v[204:207], v[180:183], v[18:21]
	v_mfma_f32_16x16x32_bf16 v[6:9], v[196:199], v[188:191], v[6:9]
	v_mfma_f32_16x16x32_bf16 v[2:5], v[204:207], v[188:191], v[2:5]
	v_mfma_f32_16x16x32_bf16 v[54:57], v[200:203], v[168:171], v[54:57]
	v_mfma_f32_16x16x32_bf16 v[50:53], v[210:213], v[168:171], v[50:53]
	v_mfma_f32_16x16x32_bf16 v[38:41], v[200:203], v[176:179], v[38:41]
	v_mfma_f32_16x16x32_bf16 v[34:37], v[210:213], v[176:179], v[34:37]
	v_mfma_f32_16x16x32_bf16 v[22:25], v[200:203], v[184:187], v[22:25]
	v_mfma_f32_16x16x32_bf16 v[18:21], v[210:213], v[184:187], v[18:21]
	v_mfma_f32_16x16x32_bf16 v[6:9], v[200:203], v[192:195], v[6:9]
	v_mfma_f32_16x16x32_bf16 v[2:5], v[210:213], v[192:195], v[2:5]
	s_add_i32 s73, s73, 2
	s_add_u32 s71, s71, 0x100
	s_addc_u32 s72, s72, 0
	s_add_u32 s46, s46, 0x100
	s_addc_u32 s47, s47, 0
	s_cmp_gt_u32 s73, 29
	s_barrier
; __device__ __forceinline__ unsigned cvt_pk_bf16(float lo, float hi) { unsigned r; asm("v_cvt_pk_bf16_f32 %0, %1, %2" : "=v"(r) : "v"(lo), "v"(hi)); return r; }
;     __device__ __forceinline__ void operator()(const f32x4 (&acc)[2][2][4][2], const Unit& u, int wr, int wc, int fr, int fq) const {
;         const int row0 = u.pm * BM + wr * 64 + fr, col0 = u.pn * BM + wc * 32 + 8 * fq;
; #pragma unroll
;         for (int ai = 0; ai < 2; ++ai)
; #pragma unroll
;             for (int m = 0; m < 4; ++m) { bf16_t* rowp = O + (size_t)(row0 + ai * HALF + m * 16) * ldc + col0;
; #pragma unroll
;                 for (int bj = 0; bj < 2; ++bj) { f32x4 v0 = acc[ai][bj][m][0], v1 = acc[ai][bj][m][1];
;                     if (ACT == 1) {
; #pragma unroll
;                         for (int j = 0; j < 4; ++j) { float a = fmaxf(v0[j], 0.f), b = fmaxf(v1[j], 0.f); v0[j] = a * a; v1[j] = b * b; } }
;                     u32x4 w; w.x = cvt_pk_bf16(v0[0], v0[1]); w.y = cvt_pk_bf16(v0[2], v0[3]); w.z = cvt_pk_bf16(v1[0], v1[1]); w.w = cvt_pk_bf16(v1[2], v1[3]);
;                     if (ACT == 1) __builtin_nontemporal_store(w, (u32x4*)(rowp + bj * HALF));
;                     else *(u32x4*)(rowp + bj * HALF) = w; } }
	s_cbranch_scc0 .LBB0_73
	v_lshl_add_u32 v146, s8, 8, v142
	v_max_f32_e32 v122, v122, v122
	v_ashrrev_i32_e32 v147, 31, v146
	v_max_f32_e32 v122, 0, v122
	v_max_f32_e32 v123, v123, v123
	v_max_f32_e32 v124, v124, v124
	v_lshl_or_b32 v140, s68, 8, v144
	v_lshlrev_b64 v[148:149], 14, v[146:147]
	v_mul_f32_e32 v147, v122, v122
	v_max_f32_e32 v122, v127, v127
	v_max_f32_e32 v123, 0, v123
	v_max_f32_e32 v124, 0, v124
	v_ashrrev_i32_e32 v141, 31, v140
	v_max_f32_e32 v126, v126, v126
	v_max_f32_e32 v122, 0, v122
	v_mul_f32_e32 v127, v123, v123
	v_max_f32_e32 v123, v128, v128
	v_mul_f32_e32 v128, v124, v124
	v_max_f32_e32 v124, v129, v129
	v_max_f32_e32 v125, v125, v125
	v_lshl_add_u64 v[148:149], s[24:25], 0, v[148:149]
	v_lshlrev_b64 v[150:151], 1, v[140:141]
	v_max_f32_e32 v126, 0, v126
	v_mul_f32_e32 v122, v122, v122
	v_max_f32_e32 v123, 0, v123
	v_max_f32_e32 v124, 0, v124
	v_max_f32_e32 v125, 0, v125
	v_max_f32_e32 v114, v114, v114
	v_lshl_add_u64 v[140:141], v[148:149], 0, v[150:151]
	v_mul_f32_e32 v126, v126, v126
	v_mul_f32_e32 v123, v123, v123
	v_mul_f32_e32 v124, v124, v124
	v_mul_f32_e32 v125, v125, v125
	v_cvt_pk_bf16_f32 v122, v126, v122
	v_max_f32_e32 v114, 0, v114
	v_max_f32_e32 v115, v115, v115
	v_max_f32_e32 v116, v116, v116
	v_cvt_pk_bf16_f32 v123, v123, v124
	v_cvt_pk_bf16_f32 v124, v147, v127
	v_cvt_pk_bf16_f32 v125, v128, v125
	global_store_dwordx4 v[140:141], v[122:125], off nt
	v_max_f32_e32 v115, 0, v115
	v_max_f32_e32 v116, 0, v116
	v_mul_f32_e32 v122, v114, v114
	v_max_f32_e32 v114, v119, v119
	v_max_f32_e32 v118, v118, v118
	v_max_f32_e32 v114, 0, v114
	v_mul_f32_e32 v119, v115, v115
	v_max_f32_e32 v115, v120, v120
	v_mul_f32_e32 v120, v116, v116
	v_max_f32_e32 v116, v121, v121
	v_max_f32_e32 v117, v117, v117
	v_max_f32_e32 v118, 0, v118
	v_mul_f32_e32 v114, v114, v114
	v_max_f32_e32 v115, 0, v115
	v_max_f32_e32 v116, 0, v116
	v_max_f32_e32 v117, 0, v117
	v_mul_f32_e32 v118, v118, v118
	v_mul_f32_e32 v115, v115, v115
	v_mul_f32_e32 v116, v116, v116
	v_mul_f32_e32 v117, v117, v117
	v_cvt_pk_bf16_f32 v114, v118, v114
	v_max_f32_e32 v106, v106, v106
	v_cvt_pk_bf16_f32 v115, v115, v116
	v_cvt_pk_bf16_f32 v116, v122, v119
	v_cvt_pk_bf16_f32 v117, v120, v117
	global_store_dwordx4 v[140:141], v[114:117], off offset:256 nt
	v_max_f32_e32 v106, 0, v106
	v_max_f32_e32 v107, v107, v107
	v_or_b32_e32 v114, 16, v146
	v_max_f32_e32 v108, v108, v108
	v_ashrrev_i32_e32 v115, 31, v114
	v_mul_f32_e32 v116, v106, v106
	v_max_f32_e32 v106, v111, v111
	v_max_f32_e32 v107, 0, v107
	v_max_f32_e32 v108, 0, v108
	v_lshlrev_b64 v[114:115], 14, v[114:115]
	v_max_f32_e32 v110, v110, v110
	v_max_f32_e32 v106, 0, v106
	v_mul_f32_e32 v111, v107, v107
	v_max_f32_e32 v107, v112, v112
	v_mul_f32_e32 v112, v108, v108
	v_max_f32_e32 v108, v113, v113
	v_max_f32_e32 v109, v109, v109
	v_lshl_add_u64 v[114:115], s[24:25], 0, v[114:115]
	v_max_f32_e32 v110, 0, v110
	v_mul_f32_e32 v106, v106, v106
	v_max_f32_e32 v107, 0, v107
	v_max_f32_e32 v108, 0, v108
	v_max_f32_e32 v109, 0, v109
	v_max_f32_e32 v98, v98, v98
	v_lshl_add_u64 v[114:115], v[114:115], 0, v[150:151]
	v_mul_f32_e32 v110, v110, v110
	v_mul_f32_e32 v107, v107, v107
	v_mul_f32_e32 v108, v108, v108
	v_mul_f32_e32 v109, v109, v109
	v_cvt_pk_bf16_f32 v106, v110, v106
	v_max_f32_e32 v98, 0, v98
	v_max_f32_e32 v99, v99, v99
	v_max_f32_e32 v100, v100, v100
	v_cvt_pk_bf16_f32 v107, v107, v108
	v_cvt_pk_bf16_f32 v108, v116, v111
	v_cvt_pk_bf16_f32 v109, v112, v109
	global_store_dwordx4 v[114:115], v[106:109], off nt
	v_max_f32_e32 v99, 0, v99
	v_max_f32_e32 v100, 0, v100
	v_mul_f32_e32 v106, v98, v98
	v_max_f32_e32 v98, v103, v103
	v_max_f32_e32 v102, v102, v102
	v_max_f32_e32 v98, 0, v98
	v_mul_f32_e32 v103, v99, v99
	v_max_f32_e32 v99, v104, v104
	v_mul_f32_e32 v104, v100, v100
	v_max_f32_e32 v100, v105, v105
	v_max_f32_e32 v101, v101, v101
	v_max_f32_e32 v102, 0, v102
	v_mul_f32_e32 v98, v98, v98
	v_max_f32_e32 v99, 0, v99
	v_max_f32_e32 v100, 0, v100
	v_max_f32_e32 v101, 0, v101
	v_mul_f32_e32 v102, v102, v102
	v_mul_f32_e32 v99, v99, v99
	v_mul_f32_e32 v100, v100, v100
	v_mul_f32_e32 v101, v101, v101
	v_cvt_pk_bf16_f32 v98, v102, v98
	v_max_f32_e32 v90, v90, v90
	v_cvt_pk_bf16_f32 v99, v99, v100
	v_cvt_pk_bf16_f32 v100, v106, v103
	v_cvt_pk_bf16_f32 v101, v104, v101
	global_store_dwordx4 v[114:115], v[98:101], off offset:256 nt
	v_max_f32_e32 v90, 0, v90
	v_max_f32_e32 v91, v91, v91
	v_or_b32_e32 v98, 32, v146
	v_max_f32_e32 v92, v92, v92
	v_ashrrev_i32_e32 v99, 31, v98
	v_mul_f32_e32 v100, v90, v90
	v_max_f32_e32 v90, v95, v95
	v_max_f32_e32 v91, 0, v91
	v_max_f32_e32 v92, 0, v92
	v_lshlrev_b64 v[98:99], 14, v[98:99]
	v_max_f32_e32 v94, v94, v94
	v_max_f32_e32 v90, 0, v90
	v_mul_f32_e32 v95, v91, v91
	v_max_f32_e32 v91, v96, v96
	v_mul_f32_e32 v96, v92, v92
	v_max_f32_e32 v92, v97, v97
	v_max_f32_e32 v93, v93, v93
	v_lshl_add_u64 v[98:99], s[24:25], 0, v[98:99]
	v_max_f32_e32 v94, 0, v94
	v_mul_f32_e32 v90, v90, v90
	v_max_f32_e32 v91, 0, v91
	v_max_f32_e32 v92, 0, v92
	v_max_f32_e32 v93, 0, v93
	v_max_f32_e32 v82, v82, v82
	v_lshl_add_u64 v[98:99], v[98:99], 0, v[150:151]
	v_mul_f32_e32 v94, v94, v94
	v_mul_f32_e32 v91, v91, v91
	v_mul_f32_e32 v92, v92, v92
	v_mul_f32_e32 v93, v93, v93
	v_cvt_pk_bf16_f32 v90, v94, v90
	v_max_f32_e32 v82, 0, v82
	v_max_f32_e32 v83, v83, v83
	v_max_f32_e32 v84, v84, v84
	v_cvt_pk_bf16_f32 v91, v91, v92
	v_cvt_pk_bf16_f32 v92, v100, v95
	v_cvt_pk_bf16_f32 v93, v96, v93
	global_store_dwordx4 v[98:99], v[90:93], off nt
	v_max_f32_e32 v83, 0, v83
	v_max_f32_e32 v84, 0, v84
	v_mul_f32_e32 v90, v82, v82
	v_max_f32_e32 v82, v87, v87
	v_max_f32_e32 v86, v86, v86
; __device__ __forceinline__ unsigned cvt_pk_bf16(float lo, float hi) { unsigned r; asm("v_cvt_pk_bf16_f32 %0, %1, %2" : "=v"(r) : "v"(lo), "v"(hi)); return r; }
;     __device__ __forceinline__ void operator()(const f32x4 (&acc)[2][2][4][2], const Unit& u, int wr, int wc, int fr, int fq) const {
;     ...
;         for (int ai = 0; ai < 2; ++ai)
; #pragma unroll
;             for (int m = 0; m < 4; ++m) { bf16_t* rowp = O + (size_t)(row0 + ai * HALF + m * 16) * ldc + col0;
; #pragma unroll
;                 for (int bj = 0; bj < 2; ++bj) { f32x4 v0 = acc[ai][bj][m][0], v1 = acc[ai][bj][m][1];
;                     if (ACT == 1) {
; #pragma unroll
;                         for (int j = 0; j < 4; ++j) { float a = fmaxf(v0[j], 0.f), b = fmaxf(v1[j], 0.f); v0[j] = a * a; v1[j] = b * b; } }
;                     u32x4 w; w.x = cvt_pk_bf16(v0[0], v0[1]); w.y = cvt_pk_bf16(v0[2], v0[3]); w.z = cvt_pk_bf16(v1[0], v1[1]); w.w = cvt_pk_bf16(v1[2], v1[3]);
;                     if (ACT == 1) __builtin_nontemporal_store(w, (u32x4*)(rowp + bj * HALF));
;                     else *(u32x4*)(rowp + bj * HALF) = w; } }
	v_max_f32_e32 v82, 0, v82
	v_mul_f32_e32 v87, v83, v83
	v_max_f32_e32 v83, v88, v88
	v_mul_f32_e32 v88, v84, v84
	v_max_f32_e32 v84, v89, v89
	v_max_f32_e32 v85, v85, v85
	v_max_f32_e32 v86, 0, v86
	v_mul_f32_e32 v82, v82, v82
	v_max_f32_e32 v83, 0, v83
	v_max_f32_e32 v84, 0, v84
	v_max_f32_e32 v85, 0, v85
	v_mul_f32_e32 v86, v86, v86
	v_mul_f32_e32 v83, v83, v83
	v_mul_f32_e32 v84, v84, v84
	v_mul_f32_e32 v85, v85, v85
	v_cvt_pk_bf16_f32 v82, v86, v82
	v_max_f32_e32 v74, v74, v74
	v_cvt_pk_bf16_f32 v83, v83, v84
	v_cvt_pk_bf16_f32 v84, v90, v87
	v_cvt_pk_bf16_f32 v85, v88, v85
	global_store_dwordx4 v[98:99], v[82:85], off offset:256 nt
	v_max_f32_e32 v74, 0, v74
	v_max_f32_e32 v75, v75, v75
	v_or_b32_e32 v82, 48, v146
	v_max_f32_e32 v76, v76, v76
	v_ashrrev_i32_e32 v83, 31, v82
	v_mul_f32_e32 v84, v74, v74
	v_max_f32_e32 v74, v79, v79
	v_max_f32_e32 v75, 0, v75
	v_max_f32_e32 v76, 0, v76
	v_lshlrev_b64 v[82:83], 14, v[82:83]
	v_max_f32_e32 v78, v78, v78
	v_max_f32_e32 v74, 0, v74
	v_mul_f32_e32 v79, v75, v75
	v_max_f32_e32 v75, v80, v80
	v_mul_f32_e32 v80, v76, v76
	v_max_f32_e32 v76, v81, v81
	v_max_f32_e32 v77, v77, v77
	v_lshl_add_u64 v[82:83], s[24:25], 0, v[82:83]
	v_max_f32_e32 v78, 0, v78
	v_mul_f32_e32 v74, v74, v74
	v_max_f32_e32 v75, 0, v75
	v_max_f32_e32 v76, 0, v76
	v_max_f32_e32 v77, 0, v77
	v_max_f32_e32 v66, v66, v66
	v_max_f32_e32 v67, v67, v67
	v_max_f32_e32 v68, v68, v68
	v_lshl_add_u64 v[82:83], v[82:83], 0, v[150:151]
	v_mul_f32_e32 v78, v78, v78
	v_mul_f32_e32 v75, v75, v75
	v_mul_f32_e32 v76, v76, v76
	v_mul_f32_e32 v77, v77, v77
	v_cvt_pk_bf16_f32 v74, v78, v74
	v_max_f32_e32 v66, 0, v66
	v_max_f32_e32 v67, 0, v67
	v_max_f32_e32 v68, 0, v68
	v_cvt_pk_bf16_f32 v75, v75, v76
	v_cvt_pk_bf16_f32 v76, v84, v79
	v_cvt_pk_bf16_f32 v77, v80, v77
	global_store_dwordx4 v[82:83], v[74:77], off nt
	v_max_f32_e32 v69, v69, v69
	v_max_f32_e32 v70, v70, v70
	v_mul_f32_e32 v74, v66, v66
	v_max_f32_e32 v66, v71, v71
	v_mul_f32_e32 v71, v67, v67
	v_max_f32_e32 v67, v72, v72
	v_mul_f32_e32 v72, v68, v68
	v_max_f32_e32 v68, v73, v73
	v_max_f32_e32 v67, 0, v67
	v_max_f32_e32 v68, 0, v68
	v_max_f32_e32 v66, 0, v66
	v_mul_f32_e32 v67, v67, v67
	v_max_f32_e32 v69, 0, v69
	v_mul_f32_e32 v68, v68, v68
	v_max_f32_e32 v58, v58, v58
	v_max_f32_e32 v70, 0, v70
	v_mul_f32_e32 v66, v66, v66
	v_mul_f32_e32 v69, v69, v69
	v_cvt_pk_bf16_f32 v67, v67, v68
	v_cvt_pk_bf16_f32 v68, v74, v71
	v_max_f32_e32 v58, 0, v58
	v_max_f32_e32 v59, v59, v59
	v_max_f32_e32 v60, v60, v60
	v_mul_f32_e32 v70, v70, v70
	v_cvt_pk_bf16_f32 v66, v70, v66
	v_cvt_pk_bf16_f32 v69, v72, v69
	global_store_dwordx4 v[82:83], v[66:69], off offset:256 nt
	v_max_f32_e32 v62, v62, v62
	v_max_f32_e32 v59, 0, v59
	v_mul_f32_e32 v68, v58, v58
	v_max_f32_e32 v58, v63, v63
	v_max_f32_e32 v60, 0, v60
	v_max_f32_e32 v62, 0, v62
	v_max_f32_e32 v58, 0, v58
	v_mul_f32_e32 v63, v59, v59
	v_max_f32_e32 v59, v64, v64
	v_mul_f32_e32 v64, v60, v60
	v_max_f32_e32 v60, v65, v65
	v_mul_f32_e32 v62, v62, v62
	v_mul_f32_e32 v58, v58, v58
	v_max_f32_e32 v59, 0, v59
	v_max_f32_e32 v60, 0, v60
	v_max_f32_e32 v61, v61, v61
	s_mov_b32 s8, 0x200000
	v_mul_f32_e32 v59, v59, v59
	v_max_f32_e32 v61, 0, v61
	v_mul_f32_e32 v60, v60, v60
	v_cvt_pk_bf16_f32 v58, v62, v58
	v_add_co_u32_e32 v62, vcc, s8, v140
	v_max_f32_e32 v50, v50, v50
	v_max_f32_e32 v51, v51, v51
	v_max_f32_e32 v52, v52, v52
	v_mul_f32_e32 v61, v61, v61
	v_cvt_pk_bf16_f32 v59, v59, v60
	v_cvt_pk_bf16_f32 v60, v68, v63
	v_addc_co_u32_e32 v63, vcc, 0, v141, vcc
	v_max_f32_e32 v50, 0, v50
	v_max_f32_e32 v51, 0, v51
	v_max_f32_e32 v52, 0, v52
	v_cvt_pk_bf16_f32 v61, v64, v61
	global_store_dwordx4 v[62:63], v[58:61], off nt
	v_max_f32_e32 v53, v53, v53
	s_mov_b64 s[38:39], 0x200000
	v_mul_f32_e32 v58, v50, v50
	v_max_f32_e32 v50, v55, v55
	v_mul_f32_e32 v55, v51, v51
	v_max_f32_e32 v51, v56, v56
	v_mul_f32_e32 v56, v52, v52
	v_max_f32_e32 v52, v57, v57
	v_max_f32_e32 v51, 0, v51
	v_max_f32_e32 v52, 0, v52
	v_max_f32_e32 v54, v54, v54
	v_max_f32_e32 v50, 0, v50
	v_mul_f32_e32 v51, v51, v51
	v_max_f32_e32 v53, 0, v53
	v_mul_f32_e32 v52, v52, v52
	v_max_f32_e32 v42, v42, v42
	v_lshl_add_u64 v[66:67], v[140:141], 0, s[38:39]
	v_max_f32_e32 v54, 0, v54
	v_mul_f32_e32 v50, v50, v50
	v_mul_f32_e32 v53, v53, v53
	v_cvt_pk_bf16_f32 v51, v51, v52
	v_cvt_pk_bf16_f32 v52, v58, v55
	v_max_f32_e32 v42, 0, v42
	v_max_f32_e32 v43, v43, v43
	v_max_f32_e32 v44, v44, v44
	v_mul_f32_e32 v54, v54, v54
	v_cvt_pk_bf16_f32 v50, v54, v50
	v_cvt_pk_bf16_f32 v53, v56, v53
	global_store_dwordx4 v[66:67], v[50:53], off offset:256 nt
	v_max_f32_e32 v46, v46, v46
	v_max_f32_e32 v43, 0, v43
	v_mul_f32_e32 v52, v42, v42
	v_max_f32_e32 v42, v47, v47
	v_max_f32_e32 v44, 0, v44
	v_max_f32_e32 v46, 0, v46
	v_max_f32_e32 v42, 0, v42
	v_mul_f32_e32 v47, v43, v43
	v_max_f32_e32 v43, v48, v48
	v_mul_f32_e32 v48, v44, v44
	v_max_f32_e32 v44, v49, v49
	v_mul_f32_e32 v46, v46, v46
	v_mul_f32_e32 v42, v42, v42
	v_max_f32_e32 v43, 0, v43
	v_max_f32_e32 v44, 0, v44
	v_max_f32_e32 v45, v45, v45
	s_mov_b32 s8, 0x240000
	v_mul_f32_e32 v43, v43, v43
	v_max_f32_e32 v45, 0, v45
	v_mul_f32_e32 v44, v44, v44
	v_cvt_pk_bf16_f32 v42, v46, v42
; __device__ __forceinline__ unsigned cvt_pk_bf16(float lo, float hi) { unsigned r; asm("v_cvt_pk_bf16_f32 %0, %1, %2" : "=v"(r) : "v"(lo), "v"(hi)); return r; }
;     __device__ __forceinline__ void operator()(const f32x4 (&acc)[2][2][4][2], const Unit& u, int wr, int wc, int fr, int fq) const {
;     ...
;             for (int m = 0; m < 4; ++m) { bf16_t* rowp = O + (size_t)(row0 + ai * HALF + m * 16) * ldc + col0;
; #pragma unroll
;                 for (int bj = 0; bj < 2; ++bj) { f32x4 v0 = acc[ai][bj][m][0], v1 = acc[ai][bj][m][1];
;                     if (ACT == 1) {
; #pragma unroll
;                         for (int j = 0; j < 4; ++j) { float a = fmaxf(v0[j], 0.f), b = fmaxf(v1[j], 0.f); v0[j] = a * a; v1[j] = b * b; } }
;                     u32x4 w; w.x = cvt_pk_bf16(v0[0], v0[1]); w.y = cvt_pk_bf16(v0[2], v0[3]); w.z = cvt_pk_bf16(v1[0], v1[1]); w.w = cvt_pk_bf16(v1[2], v1[3]);
;                     if (ACT == 1) __builtin_nontemporal_store(w, (u32x4*)(rowp + bj * HALF));
;                     else *(u32x4*)(rowp + bj * HALF) = w; } }
	v_add_co_u32_e32 v46, vcc, s8, v140
	v_max_f32_e32 v34, v34, v34
	v_max_f32_e32 v35, v35, v35
	v_max_f32_e32 v36, v36, v36
	v_mul_f32_e32 v45, v45, v45
	v_cvt_pk_bf16_f32 v43, v43, v44
	v_cvt_pk_bf16_f32 v44, v52, v47
	v_addc_co_u32_e32 v47, vcc, 0, v141, vcc
	v_max_f32_e32 v34, 0, v34
	v_max_f32_e32 v35, 0, v35
	v_max_f32_e32 v36, 0, v36
	v_cvt_pk_bf16_f32 v45, v48, v45
	global_store_dwordx4 v[46:47], v[42:45], off nt
	v_max_f32_e32 v37, v37, v37
	s_mov_b64 s[38:39], 0x240000
	v_mul_f32_e32 v42, v34, v34
	v_max_f32_e32 v34, v39, v39
	v_mul_f32_e32 v39, v35, v35
	v_max_f32_e32 v35, v40, v40
	v_mul_f32_e32 v40, v36, v36
	v_max_f32_e32 v36, v41, v41
	v_max_f32_e32 v35, 0, v35
	v_max_f32_e32 v36, 0, v36
	v_max_f32_e32 v38, v38, v38
	v_max_f32_e32 v34, 0, v34
	v_mul_f32_e32 v35, v35, v35
	v_max_f32_e32 v37, 0, v37
	v_mul_f32_e32 v36, v36, v36
	v_max_f32_e32 v26, v26, v26
	v_lshl_add_u64 v[50:51], v[140:141], 0, s[38:39]
	v_max_f32_e32 v38, 0, v38
	v_mul_f32_e32 v34, v34, v34
	v_mul_f32_e32 v37, v37, v37
	v_cvt_pk_bf16_f32 v35, v35, v36
	v_cvt_pk_bf16_f32 v36, v42, v39
	v_max_f32_e32 v26, 0, v26
	v_max_f32_e32 v27, v27, v27
	v_max_f32_e32 v28, v28, v28
	v_mul_f32_e32 v38, v38, v38
	v_cvt_pk_bf16_f32 v34, v38, v34
	v_cvt_pk_bf16_f32 v37, v40, v37
	global_store_dwordx4 v[50:51], v[34:37], off offset:256 nt
	v_max_f32_e32 v30, v30, v30
	v_max_f32_e32 v27, 0, v27
	v_mul_f32_e32 v36, v26, v26
	v_max_f32_e32 v26, v31, v31
	v_max_f32_e32 v28, 0, v28
	v_max_f32_e32 v30, 0, v30
	v_max_f32_e32 v26, 0, v26
	v_mul_f32_e32 v31, v27, v27
	v_max_f32_e32 v27, v32, v32
	v_mul_f32_e32 v32, v28, v28
	v_max_f32_e32 v28, v33, v33
	v_mul_f32_e32 v30, v30, v30
	v_mul_f32_e32 v26, v26, v26
	v_max_f32_e32 v27, 0, v27
	v_max_f32_e32 v28, 0, v28
	v_max_f32_e32 v29, v29, v29
	s_mov_b32 s8, 0x280000
	v_mul_f32_e32 v27, v27, v27
	v_max_f32_e32 v29, 0, v29
	v_mul_f32_e32 v28, v28, v28
	v_cvt_pk_bf16_f32 v26, v30, v26
	v_add_co_u32_e32 v30, vcc, s8, v140
	v_max_f32_e32 v18, v18, v18
	v_max_f32_e32 v19, v19, v19
	v_max_f32_e32 v20, v20, v20
	v_mul_f32_e32 v29, v29, v29
	v_cvt_pk_bf16_f32 v27, v27, v28
	v_cvt_pk_bf16_f32 v28, v36, v31
	v_addc_co_u32_e32 v31, vcc, 0, v141, vcc
	v_max_f32_e32 v18, 0, v18
	v_max_f32_e32 v19, 0, v19
	v_max_f32_e32 v20, 0, v20
	v_cvt_pk_bf16_f32 v29, v32, v29
	global_store_dwordx4 v[30:31], v[26:29], off nt
	v_max_f32_e32 v21, v21, v21
	s_mov_b64 s[38:39], 0x280000
	v_mul_f32_e32 v26, v18, v18
	v_max_f32_e32 v18, v23, v23
	v_mul_f32_e32 v23, v19, v19
	v_max_f32_e32 v19, v24, v24
	v_mul_f32_e32 v24, v20, v20
	v_max_f32_e32 v20, v25, v25
	v_max_f32_e32 v19, 0, v19
	v_max_f32_e32 v20, 0, v20
	v_max_f32_e32 v22, v22, v22
	v_max_f32_e32 v18, 0, v18
	v_mul_f32_e32 v19, v19, v19
	v_max_f32_e32 v21, 0, v21
	v_mul_f32_e32 v20, v20, v20
	v_max_f32_e32 v10, v10, v10
	v_lshl_add_u64 v[34:35], v[140:141], 0, s[38:39]
	v_max_f32_e32 v22, 0, v22
	v_mul_f32_e32 v18, v18, v18
	v_mul_f32_e32 v21, v21, v21
	v_cvt_pk_bf16_f32 v19, v19, v20
	v_cvt_pk_bf16_f32 v20, v26, v23
	v_max_f32_e32 v10, 0, v10
	v_max_f32_e32 v11, v11, v11
	v_max_f32_e32 v12, v12, v12
	v_mul_f32_e32 v22, v22, v22
	v_cvt_pk_bf16_f32 v18, v22, v18
	v_cvt_pk_bf16_f32 v21, v24, v21
	global_store_dwordx4 v[34:35], v[18:21], off offset:256 nt
	v_max_f32_e32 v14, v14, v14
	v_max_f32_e32 v11, 0, v11
	v_mul_f32_e32 v20, v10, v10
	v_max_f32_e32 v10, v15, v15
	v_max_f32_e32 v12, 0, v12
	v_max_f32_e32 v14, 0, v14
	v_max_f32_e32 v10, 0, v10
	v_mul_f32_e32 v15, v11, v11
	v_max_f32_e32 v11, v16, v16
	v_mul_f32_e32 v16, v12, v12
	v_max_f32_e32 v12, v17, v17
	v_mul_f32_e32 v14, v14, v14
	v_mul_f32_e32 v10, v10, v10
	v_max_f32_e32 v11, 0, v11
	v_max_f32_e32 v12, 0, v12
	v_max_f32_e32 v13, v13, v13
	s_mov_b32 s8, 0x2c0000
	v_mul_f32_e32 v11, v11, v11
	v_max_f32_e32 v13, 0, v13
	v_mul_f32_e32 v12, v12, v12
	v_cvt_pk_bf16_f32 v10, v14, v10
	v_add_co_u32_e32 v14, vcc, s8, v140
	v_max_f32_e32 v2, v2, v2
	v_max_f32_e32 v3, v3, v3
	v_max_f32_e32 v4, v4, v4
	v_mul_f32_e32 v13, v13, v13
	v_cvt_pk_bf16_f32 v11, v11, v12
	v_cvt_pk_bf16_f32 v12, v20, v15
	v_addc_co_u32_e32 v15, vcc, 0, v141, vcc
	v_max_f32_e32 v2, 0, v2
	v_max_f32_e32 v3, 0, v3
	v_max_f32_e32 v4, 0, v4
	v_cvt_pk_bf16_f32 v13, v16, v13
	global_store_dwordx4 v[14:15], v[10:13], off nt
	v_max_f32_e32 v5, v5, v5
	s_mov_b64 s[38:39], 0x2c0000
	v_mul_f32_e32 v10, v2, v2
	v_max_f32_e32 v2, v7, v7
	v_mul_f32_e32 v7, v3, v3
	v_max_f32_e32 v3, v8, v8
	v_mul_f32_e32 v8, v4, v4
	v_max_f32_e32 v4, v9, v9
	v_max_f32_e32 v6, v6, v6
	v_max_f32_e32 v2, 0, v2
	v_max_f32_e32 v3, 0, v3
	v_max_f32_e32 v4, 0, v4
	v_max_f32_e32 v5, 0, v5
	v_lshl_add_u64 v[18:19], v[140:141], 0, s[38:39]
	v_max_f32_e32 v6, 0, v6
	v_mul_f32_e32 v2, v2, v2
	v_mul_f32_e32 v3, v3, v3
	v_mul_f32_e32 v4, v4, v4
	v_mul_f32_e32 v5, v5, v5
	s_and_b64 vcc, exec, s[40:41]
	s_mov_b32 s68, s26
	s_mov_b32 s8, s28
	s_mov_b64 s[46:47], s[44:45]
	s_mov_b64 s[48:49], s[42:43]
	v_mul_f32_e32 v6, v6, v6
	v_cvt_pk_bf16_f32 v2, v6, v2
	v_cvt_pk_bf16_f32 v3, v3, v4
	v_cvt_pk_bf16_f32 v4, v10, v7
	v_cvt_pk_bf16_f32 v5, v8, v5
	global_store_dwordx4 v[18:19], v[2:5], off offset:256 nt
	s_cbranch_vccz .LBB0_70
	s_waitcnt vmcnt(0)
	s_cmpk_gt_u32 s52, 0xff
	s_cbranch_scc1 .LBB0_77
	s_barrier

; #define PG8_STAGE(bufoff, gbase, voff) do { _Pragma("unroll") for (int _i = 0; _i < 2; ++_i) \
;         __builtin_amdgcn_global_load_lds((const unsigned*)((const char*)(gbase) + (voff)[_i]), (LAS unsigned*)(lds + (bufoff) + ldsw + _i * 8192), 16, 0, 0); } while (0)
; #define PG8_LDA(dst, b, h) do { _Pragma("unroll") for (int m = 0; m < 4; ++m) _Pragma("unroll") for (int k = 0; k < 2; ++k) dst[m][k] = *(const LAS bf16x8*)(lds + PG8_SA(b, h) + aoff + m * 2048 + k * 1024); } while (0)
; #define PG8_LDB(dst, b, h) do { _Pragma("unroll") for (int n = 0; n < 2; ++n) _Pragma("unroll") for (int k = 0; k < 2; ++k) dst[n][k] = *(const LAS bf16x8*)(lds + PG8_SB(b, h) + boff + n * 2048 + k * 1024); } while (0)
; #define PG8_MMA(ai, bj, At, Bt) do { __builtin_amdgcn_s_setprio(1); _Pragma("unroll") for (int m = 0; m < 4; ++m) _Pragma("unroll") for (int n = 0; n < 2; ++n) _Pragma("unroll") for (int k = 0; k < 2; ++k) \
;         acc[ai][bj][m][n] = __builtin_amdgcn_mfma_f32_16x16x32_bf16(Bt[n][k], At[m][k], acc[ai][bj][m][n], 0, 0, 0); __builtin_amdgcn_s_setprio(0); } while (0)
; #define PG8_WAIT_V(n) asm volatile("s_waitcnt vmcnt(" #n ")" ::: "memory")
; #define PG8_WAIT_L(n) asm volatile("s_waitcnt lgkmcnt(" #n ")" ::: "memory")
; template <class Epi, class Sched>
; __device__ __forceinline__ void gemm_phase(LAS unsigned char* lds, const Gemm g, const Sched& S, const Epi& E) {
;     ...
;         for (int t = 0; t < nt; t += 2) {
;             const bool last = (t == nt - 2);
;             const char* a1 = cA + (size_t)(t + 1) * kstep;
;             const char* a2 = last ? nA : cA + (size_t)(t + 2) * kstep; const char* b2 = last ? nB : cB + (size_t)(t + 2) * kstep;
;             const char* a3 = a2 + kstep; const char* b3 = b2 + kstep;
;             PG8_LDB(B0, 0, 0); PG8_SCHED; PG8_LDA(At, 0, 0); PG8_STAGE(PG8_SA(1, 1), a1 + hstep, voffA);
;             PG8_WAIT_L(8); PG8_BAR; PG8_WAIT_L(0); PG8_MMA(0, 0, At, B0); PG8_BAR; PG8_SCHED;
;             PG8_LDB(B1, 0, 1); PG8_STAGE(PG8_SB(0, 0), b2, voffB);
;             PG8_BAR; PG8_WAIT_L(0); PG8_MMA(0, 1, At, B1); PG8_BAR;
;             PG8_LDA(At, 0, 1); PG8_STAGE(PG8_SA(0, 0), a2, voffA);
;             PG8_BAR; PG8_WAIT_L(0); PG8_MMA(1, 0, At, B0); PG8_BAR; PG8_SCHED;
;             PG8_STAGE(PG8_SB(0, 1), b2 + hstep, voffB);
;             PG8_WAIT_V(6); PG8_BAR; PG8_MMA(1, 1, At, B1); PG8_BAR;
.LBB0_99:
	s_add_u32 s56, s28, 0x100
	s_addc_u32 s57, s29, 0
	s_cmp_eq_u32 s81, 28
	s_cselect_b32 s61, s51, s57
	s_cselect_b32 s60, s77, s56
	s_cselect_b32 s59, s49, s80
	s_cselect_b32 s58, s78, s79
	s_add_i32 m0, s9, 0xc000
	ds_read_b128 v[98:101], v226
	global_load_lds_dwordx4 v150, s[28:29]
	s_add_i32 m0, s9, 0xe000
	ds_read_b128 v[102:105], v226 offset:1024
	global_load_lds_dwordx4 v148, s[28:29]
	s_add_i32 s38, 0, 0x10000
	ds_read_b128 v[106:109], v226 offset:2048
	ds_read_b128 v[110:113], v226 offset:3072
	ds_read_b128 v[152:155], v171
	ds_read_b128 v[160:163], v171 offset:1024
	ds_read_b128 v[164:167], v171 offset:2048
	ds_read_b128 v[172:175], v171 offset:3072
	ds_read_b128 v[176:179], v171 offset:4096
	ds_read_b128 v[180:183], v171 offset:5120
	ds_read_b128 v[184:187], v171 offset:6144
	ds_read_b128 v[188:191], v171 offset:7168
	s_add_i32 s39, 0, 0x14000
	ds_read_b128 v[192:195], v226 offset:16384
	ds_read_b128 v[196:199], v226 offset:17408
	ds_read_b128 v[200:203], v226 offset:18432
	ds_read_b128 v[204:207], v226 offset:19456
	s_waitcnt lgkmcnt(4)
	s_barrier
	s_waitcnt lgkmcnt(0)
	v_mfma_f32_16x16x32_bf16 v[142:145], v[98:101], v[152:155], v[142:145]
	v_mfma_f32_16x16x32_bf16 v[138:141], v[106:109], v[152:155], v[138:141]
	v_mfma_f32_16x16x32_bf16 v[126:129], v[98:101], v[164:167], v[126:129]
	v_mfma_f32_16x16x32_bf16 v[122:125], v[106:109], v[164:167], v[122:125]
	v_mfma_f32_16x16x32_bf16 v[94:97], v[98:101], v[176:179], v[94:97]
	v_mfma_f32_16x16x32_bf16 v[90:93], v[106:109], v[176:179], v[90:93]
	v_mfma_f32_16x16x32_bf16 v[86:89], v[98:101], v[184:187], v[86:89]
	v_mfma_f32_16x16x32_bf16 v[82:85], v[106:109], v[184:187], v[82:85]
	v_mfma_f32_16x16x32_bf16 v[142:145], v[102:105], v[160:163], v[142:145]
	v_mfma_f32_16x16x32_bf16 v[138:141], v[110:113], v[160:163], v[138:141]
	v_mfma_f32_16x16x32_bf16 v[126:129], v[102:105], v[172:175], v[126:129]
	v_mfma_f32_16x16x32_bf16 v[122:125], v[110:113], v[172:175], v[122:125]
	v_mfma_f32_16x16x32_bf16 v[94:97], v[102:105], v[180:183], v[94:97]
	v_mfma_f32_16x16x32_bf16 v[90:93], v[110:113], v[180:183], v[90:93]
	v_mfma_f32_16x16x32_bf16 v[86:89], v[102:105], v[188:191], v[86:89]
	v_mfma_f32_16x16x32_bf16 v[82:85], v[110:113], v[188:191], v[82:85]
	v_mfma_f32_16x16x32_bf16 v[134:137], v[192:195], v[152:155], v[134:137]
	v_mfma_f32_16x16x32_bf16 v[130:133], v[200:203], v[152:155], v[130:133]
	v_mfma_f32_16x16x32_bf16 v[118:121], v[192:195], v[164:167], v[118:121]
	v_mfma_f32_16x16x32_bf16 v[114:117], v[200:203], v[164:167], v[114:117]
	v_mfma_f32_16x16x32_bf16 v[78:81], v[192:195], v[176:179], v[78:81]
	v_mfma_f32_16x16x32_bf16 v[74:77], v[200:203], v[176:179], v[74:77]
	v_mfma_f32_16x16x32_bf16 v[70:73], v[192:195], v[184:187], v[70:73]
	v_mfma_f32_16x16x32_bf16 v[66:69], v[200:203], v[184:187], v[66:69]
	v_mfma_f32_16x16x32_bf16 v[134:137], v[196:199], v[160:163], v[134:137]
	v_mfma_f32_16x16x32_bf16 v[130:133], v[204:207], v[160:163], v[130:133]
	v_mfma_f32_16x16x32_bf16 v[118:121], v[196:199], v[172:175], v[118:121]
	v_mfma_f32_16x16x32_bf16 v[114:117], v[204:207], v[172:175], v[114:117]
	v_mfma_f32_16x16x32_bf16 v[78:81], v[196:199], v[180:183], v[78:81]
	v_mfma_f32_16x16x32_bf16 v[74:77], v[204:207], v[180:183], v[74:77]
	v_mfma_f32_16x16x32_bf16 v[70:73], v[196:199], v[188:191], v[70:73]
	v_mfma_f32_16x16x32_bf16 v[66:69], v[204:207], v[188:191], v[66:69]
	s_barrier
	s_add_i32 s28, s38, s67
	s_mov_b32 m0, s28
	ds_read_b128 v[152:155], v171 offset:16384
	global_load_lds_dwordx4 v0, s[58:59]
	s_add_i32 m0, s28, 0x2000
	ds_read_b128 v[160:163], v171 offset:17408
	global_load_lds_dwordx4 v146, s[58:59]
	s_mov_b32 m0, s9
	ds_read_b128 v[164:167], v171 offset:18432
	global_load_lds_dwordx4 v0, s[60:61]
	s_mov_b32 m0, s68
	ds_read_b128 v[172:175], v171 offset:19456
	global_load_lds_dwordx4 v146, s[60:61]
	ds_read_b128 v[176:179], v171 offset:20480
	ds_read_b128 v[180:183], v171 offset:21504
	ds_read_b128 v[184:187], v171 offset:22528
	ds_read_b128 v[188:191], v171 offset:23552
	s_waitcnt vmcnt(4)
	s_waitcnt lgkmcnt(0)
	s_barrier
	v_mfma_f32_16x16x32_bf16 v[62:65], v[98:101], v[152:155], v[62:65]
	v_mfma_f32_16x16x32_bf16 v[58:61], v[106:109], v[152:155], v[58:61]
	v_mfma_f32_16x16x32_bf16 v[46:49], v[98:101], v[164:167], v[46:49]
	v_mfma_f32_16x16x32_bf16 v[42:45], v[106:109], v[164:167], v[42:45]
	v_mfma_f32_16x16x32_bf16 v[30:33], v[98:101], v[176:179], v[30:33]
	v_mfma_f32_16x16x32_bf16 v[26:29], v[106:109], v[176:179], v[26:29]
	v_mfma_f32_16x16x32_bf16 v[22:25], v[98:101], v[184:187], v[22:25]
	v_mfma_f32_16x16x32_bf16 v[18:21], v[106:109], v[184:187], v[18:21]
	v_mfma_f32_16x16x32_bf16 v[62:65], v[102:105], v[160:163], v[62:65]
	v_mfma_f32_16x16x32_bf16 v[58:61], v[110:113], v[160:163], v[58:61]
	v_mfma_f32_16x16x32_bf16 v[46:49], v[102:105], v[172:175], v[46:49]
	v_mfma_f32_16x16x32_bf16 v[42:45], v[110:113], v[172:175], v[42:45]
	v_mfma_f32_16x16x32_bf16 v[30:33], v[102:105], v[180:183], v[30:33]
	v_mfma_f32_16x16x32_bf16 v[26:29], v[110:113], v[180:183], v[26:29]
	v_mfma_f32_16x16x32_bf16 v[22:25], v[102:105], v[188:191], v[22:25]
	v_mfma_f32_16x16x32_bf16 v[18:21], v[110:113], v[188:191], v[18:21]
	v_mfma_f32_16x16x32_bf16 v[54:57], v[192:195], v[152:155], v[54:57]
	v_mfma_f32_16x16x32_bf16 v[50:53], v[200:203], v[152:155], v[50:53]
	v_mfma_f32_16x16x32_bf16 v[38:41], v[192:195], v[164:167], v[38:41]
	v_mfma_f32_16x16x32_bf16 v[34:37], v[200:203], v[164:167], v[34:37]
	v_mfma_f32_16x16x32_bf16 v[14:17], v[192:195], v[176:179], v[14:17]
	v_mfma_f32_16x16x32_bf16 v[10:13], v[200:203], v[176:179], v[10:13]
	v_mfma_f32_16x16x32_bf16 v[6:9], v[192:195], v[184:187], v[6:9]
	v_mfma_f32_16x16x32_bf16 v[2:5], v[200:203], v[184:187], v[2:5]
	v_mfma_f32_16x16x32_bf16 v[54:57], v[196:199], v[160:163], v[54:57]
	v_mfma_f32_16x16x32_bf16 v[50:53], v[204:207], v[160:163], v[50:53]
	v_mfma_f32_16x16x32_bf16 v[38:41], v[196:199], v[172:175], v[38:41]
	v_mfma_f32_16x16x32_bf16 v[34:37], v[204:207], v[172:175], v[34:37]
	v_mfma_f32_16x16x32_bf16 v[14:17], v[196:199], v[180:183], v[14:17]
	v_mfma_f32_16x16x32_bf16 v[10:13], v[204:207], v[180:183], v[10:13]
	v_mfma_f32_16x16x32_bf16 v[6:9], v[196:199], v[188:191], v[6:9]
	v_mfma_f32_16x16x32_bf16 v[2:5], v[204:207], v[188:191], v[2:5]
	s_barrier
; #define PG8_STAGE(bufoff, gbase, voff) do { _Pragma("unroll") for (int _i = 0; _i < 2; ++_i) \
;         __builtin_amdgcn_global_load_lds((const unsigned*)((const char*)(gbase) + (voff)[_i]), (LAS unsigned*)(lds + (bufoff) + ldsw + _i * 8192), 16, 0, 0); } while (0)
; #define PG8_LDA(dst, b, h) do { _Pragma("unroll") for (int m = 0; m < 4; ++m) _Pragma("unroll") for (int k = 0; k < 2; ++k) dst[m][k] = *(const LAS bf16x8*)(lds + PG8_SA(b, h) + aoff + m * 2048 + k * 1024); } while (0)
; #define PG8_LDB(dst, b, h) do { _Pragma("unroll") for (int n = 0; n < 2; ++n) _Pragma("unroll") for (int k = 0; k < 2; ++k) dst[n][k] = *(const LAS bf16x8*)(lds + PG8_SB(b, h) + boff + n * 2048 + k * 1024); } while (0)
; #define PG8_MMA(ai, bj, At, Bt) do { __builtin_amdgcn_s_setprio(1); _Pragma("unroll") for (int m = 0; m < 4; ++m) _Pragma("unroll") for (int n = 0; n < 2; ++n) _Pragma("unroll") for (int k = 0; k < 2; ++k) \
;         acc[ai][bj][m][n] = __builtin_amdgcn_mfma_f32_16x16x32_bf16(Bt[n][k], At[m][k], acc[ai][bj][m][n], 0, 0, 0); __builtin_amdgcn_s_setprio(0); } while (0)
; #define PG8_WAIT_V(n) asm volatile("s_waitcnt vmcnt(" #n ")" ::: "memory")
; #define PG8_BAR __builtin_amdgcn_s_barrier()
;     __device__ __forceinline__ void operator()(const f32x4 (&acc)[2][2][4][2], const Unit& u, int wr, int wc, int fr, int fq) const {
;         const bool lat = u.pm < 64; const int r = lat ? (u.pm >> 3) : 8;
;         const float* s = lat ? src_lat : src_ctx; float* d = lat ? dst_lat : dst_ctx;
;         const int row0 = (lat ? u.pm : u.pm - 64) * BM + wr * 64 + fr, col0 = u.pn * BM + wc * 32 + 4 * fq;
; template <class Epi, class Sched>
; __device__ __forceinline__ void gemm_phase(LAS unsigned char* lds, const Gemm g, const Sched& S, const Epi& E) {
;     ...
;             PG8_LDB(B0, 1, 0); PG8_SCHED; PG8_LDA(At, 1, 0); PG8_STAGE(PG8_SA(0, 1), a2 + hstep, voffA);
;             PG8_WAIT_L(8); PG8_BAR; PG8_WAIT_L(0); PG8_MMA(0, 0, At, B0); PG8_BAR; PG8_SCHED;
;             PG8_LDB(B1, 1, 1); PG8_STAGE(PG8_SB(1, 0), b3, voffB);
;             PG8_BAR; PG8_WAIT_L(0); PG8_MMA(0, 1, At, B1); PG8_BAR;
;             PG8_LDA(At, 1, 1); PG8_STAGE(PG8_SA(1, 0), a3, voffA);
;             PG8_BAR; PG8_WAIT_L(0); PG8_MMA(1, 0, At, B0); PG8_BAR; PG8_SCHED;
;             PG8_STAGE(PG8_SB(1, 1), b3 + hstep, voffB);
;             PG8_WAIT_V(6); PG8_BAR; PG8_MMA(1, 1, At, B1); PG8_BAR;
	s_add_u32 s28, s58, 0x80000
	s_addc_u32 s29, s59, 0
	s_add_i32 s38, s39, s67
	s_mov_b32 m0, s38
	ds_read_b128 v[98:101], v226 offset:32768
	global_load_lds_dwordx4 v0, s[28:29]
	s_add_i32 m0, s38, 0x2000
	ds_read_b128 v[102:105], v226 offset:33792
	global_load_lds_dwordx4 v146, s[28:29]
	s_add_u32 s28, s60, 0x80000
	s_addc_u32 s29, s61, 0
	s_mov_b32 m0, s69
	ds_read_b128 v[106:109], v226 offset:34816
	global_load_lds_dwordx4 v0, s[28:29]
	s_mov_b32 m0, s70
	ds_read_b128 v[110:113], v226 offset:35840
	global_load_lds_dwordx4 v146, s[28:29]
	s_add_i32 s38, 0, 0x18000
	ds_read_b128 v[152:155], v171 offset:32768
	ds_read_b128 v[160:163], v171 offset:33792
	ds_read_b128 v[164:167], v171 offset:34816
	ds_read_b128 v[172:175], v171 offset:35840
	ds_read_b128 v[176:179], v171 offset:36864
	ds_read_b128 v[180:183], v171 offset:37888
	ds_read_b128 v[184:187], v171 offset:38912
	ds_read_b128 v[188:191], v171 offset:39936
	s_add_i32 s39, 0, 0x1c000
	ds_read_b128 v[192:195], v226 offset:49152
	ds_read_b128 v[196:199], v226 offset:50176
	ds_read_b128 v[200:203], v226 offset:51200
	ds_read_b128 v[204:207], v226 offset:52224
	s_waitcnt lgkmcnt(4)
	s_barrier
	s_waitcnt lgkmcnt(0)
	v_mfma_f32_16x16x32_bf16 v[142:145], v[98:101], v[152:155], v[142:145]
	v_mfma_f32_16x16x32_bf16 v[138:141], v[106:109], v[152:155], v[138:141]
	v_mfma_f32_16x16x32_bf16 v[126:129], v[98:101], v[164:167], v[126:129]
	v_mfma_f32_16x16x32_bf16 v[122:125], v[106:109], v[164:167], v[122:125]
	v_mfma_f32_16x16x32_bf16 v[94:97], v[98:101], v[176:179], v[94:97]
	v_mfma_f32_16x16x32_bf16 v[90:93], v[106:109], v[176:179], v[90:93]
	v_mfma_f32_16x16x32_bf16 v[86:89], v[98:101], v[184:187], v[86:89]
	v_mfma_f32_16x16x32_bf16 v[82:85], v[106:109], v[184:187], v[82:85]
	v_mfma_f32_16x16x32_bf16 v[142:145], v[102:105], v[160:163], v[142:145]
	v_mfma_f32_16x16x32_bf16 v[138:141], v[110:113], v[160:163], v[138:141]
	v_mfma_f32_16x16x32_bf16 v[126:129], v[102:105], v[172:175], v[126:129]
	v_mfma_f32_16x16x32_bf16 v[122:125], v[110:113], v[172:175], v[122:125]
	v_mfma_f32_16x16x32_bf16 v[94:97], v[102:105], v[180:183], v[94:97]
	v_mfma_f32_16x16x32_bf16 v[90:93], v[110:113], v[180:183], v[90:93]
	v_mfma_f32_16x16x32_bf16 v[86:89], v[102:105], v[188:191], v[86:89]
	v_mfma_f32_16x16x32_bf16 v[82:85], v[110:113], v[188:191], v[82:85]
	v_mfma_f32_16x16x32_bf16 v[134:137], v[192:195], v[152:155], v[134:137]
	v_mfma_f32_16x16x32_bf16 v[130:133], v[200:203], v[152:155], v[130:133]
	v_mfma_f32_16x16x32_bf16 v[118:121], v[192:195], v[164:167], v[118:121]
	v_mfma_f32_16x16x32_bf16 v[114:117], v[200:203], v[164:167], v[114:117]
	v_mfma_f32_16x16x32_bf16 v[78:81], v[192:195], v[176:179], v[78:81]
	v_mfma_f32_16x16x32_bf16 v[74:77], v[200:203], v[176:179], v[74:77]
	v_mfma_f32_16x16x32_bf16 v[70:73], v[192:195], v[184:187], v[70:73]
	v_mfma_f32_16x16x32_bf16 v[66:69], v[200:203], v[184:187], v[66:69]
	v_mfma_f32_16x16x32_bf16 v[134:137], v[196:199], v[160:163], v[134:137]
	v_mfma_f32_16x16x32_bf16 v[130:133], v[204:207], v[160:163], v[130:133]
	v_mfma_f32_16x16x32_bf16 v[118:121], v[196:199], v[172:175], v[118:121]
	v_mfma_f32_16x16x32_bf16 v[114:117], v[204:207], v[172:175], v[114:117]
	v_mfma_f32_16x16x32_bf16 v[78:81], v[196:199], v[180:183], v[78:81]
	v_mfma_f32_16x16x32_bf16 v[74:77], v[204:207], v[180:183], v[74:77]
	v_mfma_f32_16x16x32_bf16 v[70:73], v[196:199], v[188:191], v[70:73]
	v_mfma_f32_16x16x32_bf16 v[66:69], v[204:207], v[188:191], v[66:69]
	s_barrier
	s_add_i32 s28, s38, s67
	s_add_u32 s100, s58, s36
	s_addc_u32 s101, s59, s37
	s_mov_b32 m0, s28
	ds_read_b128 v[152:155], v171 offset:49152
	global_load_lds_dwordx4 v0, s[100:101]
	s_add_i32 m0, s28, 0x2000
	ds_read_b128 v[160:163], v171 offset:50176
	global_load_lds_dwordx4 v146, s[100:101]
	s_mov_b32 m0, s72
	s_add_u32 s100, s60, s36
	s_addc_u32 s101, s61, s37
	global_load_lds_dwordx4 v0, s[100:101]
	s_mov_b32 m0, s73
	ds_read_b128 v[164:167], v171 offset:51200
	global_load_lds_dwordx4 v146, s[100:101]
	ds_read_b128 v[172:175], v171 offset:52224
	ds_read_b128 v[176:179], v171 offset:53248
	ds_read_b128 v[180:183], v171 offset:54272
	ds_read_b128 v[184:187], v171 offset:55296
	ds_read_b128 v[188:191], v171 offset:56320
	s_waitcnt vmcnt(4)
	s_waitcnt lgkmcnt(0)
	s_barrier
	v_mfma_f32_16x16x32_bf16 v[62:65], v[98:101], v[152:155], v[62:65]
	v_mfma_f32_16x16x32_bf16 v[58:61], v[106:109], v[152:155], v[58:61]
	v_mfma_f32_16x16x32_bf16 v[46:49], v[98:101], v[164:167], v[46:49]
	v_mfma_f32_16x16x32_bf16 v[42:45], v[106:109], v[164:167], v[42:45]
	v_mfma_f32_16x16x32_bf16 v[30:33], v[98:101], v[176:179], v[30:33]
	v_mfma_f32_16x16x32_bf16 v[26:29], v[106:109], v[176:179], v[26:29]
	v_mfma_f32_16x16x32_bf16 v[22:25], v[98:101], v[184:187], v[22:25]
	v_mfma_f32_16x16x32_bf16 v[18:21], v[106:109], v[184:187], v[18:21]
	v_mfma_f32_16x16x32_bf16 v[62:65], v[102:105], v[160:163], v[62:65]
	v_mfma_f32_16x16x32_bf16 v[58:61], v[110:113], v[160:163], v[58:61]
	v_mfma_f32_16x16x32_bf16 v[46:49], v[102:105], v[172:175], v[46:49]
	v_mfma_f32_16x16x32_bf16 v[42:45], v[110:113], v[172:175], v[42:45]
	v_mfma_f32_16x16x32_bf16 v[30:33], v[102:105], v[180:183], v[30:33]
	v_mfma_f32_16x16x32_bf16 v[26:29], v[110:113], v[180:183], v[26:29]
	v_mfma_f32_16x16x32_bf16 v[22:25], v[102:105], v[188:191], v[22:25]
	v_mfma_f32_16x16x32_bf16 v[18:21], v[110:113], v[188:191], v[18:21]
	s_add_u32 s28, s58, 0x80080
	s_addc_u32 s29, s59, 0
	s_add_i32 s38, s39, s67
	s_mov_b32 m0, s38
	s_nop 0
	global_load_lds_dwordx4 v0, s[28:29]
	s_add_i32 m0, s38, 0x2000
	s_nop 0
	global_load_lds_dwordx4 v146, s[28:29]
	v_mfma_f32_16x16x32_bf16 v[54:57], v[192:195], v[152:155], v[54:57]
	v_mfma_f32_16x16x32_bf16 v[50:53], v[200:203], v[152:155], v[50:53]
	v_mfma_f32_16x16x32_bf16 v[38:41], v[192:195], v[164:167], v[38:41]
	v_mfma_f32_16x16x32_bf16 v[34:37], v[200:203], v[164:167], v[34:37]
	v_mfma_f32_16x16x32_bf16 v[14:17], v[192:195], v[176:179], v[14:17]
	v_mfma_f32_16x16x32_bf16 v[10:13], v[200:203], v[176:179], v[10:13]
	v_mfma_f32_16x16x32_bf16 v[6:9], v[192:195], v[184:187], v[6:9]
	v_mfma_f32_16x16x32_bf16 v[2:5], v[200:203], v[184:187], v[2:5]
	v_mfma_f32_16x16x32_bf16 v[54:57], v[196:199], v[160:163], v[54:57]
	v_mfma_f32_16x16x32_bf16 v[50:53], v[204:207], v[160:163], v[50:53]
	v_mfma_f32_16x16x32_bf16 v[38:41], v[196:199], v[172:175], v[38:41]
	v_mfma_f32_16x16x32_bf16 v[34:37], v[204:207], v[172:175], v[34:37]
	v_mfma_f32_16x16x32_bf16 v[14:17], v[196:199], v[180:183], v[14:17]
	v_mfma_f32_16x16x32_bf16 v[10:13], v[204:207], v[180:183], v[10:13]
	v_mfma_f32_16x16x32_bf16 v[6:9], v[196:199], v[188:191], v[6:9]
	v_mfma_f32_16x16x32_bf16 v[2:5], v[204:207], v[188:191], v[2:5]
	s_add_i32 s81, s81, 2
	s_add_u32 s79, s79, 0x100
	s_addc_u32 s80, s80, 0
	s_cmp_gt_u32 s81, 29
	s_mov_b64 s[28:29], s[56:57]
	s_barrier
	s_cbranch_scc0 .LBB0_99
	s_cmp_lt_i32 s8, 64
	s_cselect_b64 s[58:59], -1, 0
	s_cmp_gt_i32 s8, 63
	s_cbranch_scc0 .LBB0_90
	s_mov_b64 s[60:61], 0x18000
	s_mov_b64 s[28:29], s[46:47]
	s_mov_b64 s[56:57], s[24:25]
	s_branch .LBB0_91

; #define PG8_STAGE(bufoff, gbase, voff) do { _Pragma("unroll") for (int _i = 0; _i < 2; ++_i) \
;         __builtin_amdgcn_global_load_lds((const unsigned*)((const char*)(gbase) + (voff)[_i]), (LAS unsigned*)(lds + (bufoff) + ldsw + _i * 8192), 16, 0, 0); } while (0)
; #define PG8_LDA(dst, b, h) do { _Pragma("unroll") for (int m = 0; m < 4; ++m) _Pragma("unroll") for (int k = 0; k < 2; ++k) dst[m][k] = *(const LAS bf16x8*)(lds + PG8_SA(b, h) + aoff + m * 2048 + k * 1024); } while (0)
; #define PG8_LDB(dst, b, h) do { _Pragma("unroll") for (int n = 0; n < 2; ++n) _Pragma("unroll") for (int k = 0; k < 2; ++k) dst[n][k] = *(const LAS bf16x8*)(lds + PG8_SB(b, h) + boff + n * 2048 + k * 1024); } while (0)
; #define PG8_MMA(ai, bj, At, Bt) do { __builtin_amdgcn_s_setprio(1); _Pragma("unroll") for (int m = 0; m < 4; ++m) _Pragma("unroll") for (int n = 0; n < 2; ++n) _Pragma("unroll") for (int k = 0; k < 2; ++k) \
;         acc[ai][bj][m][n] = __builtin_amdgcn_mfma_f32_16x16x32_bf16(Bt[n][k], At[m][k], acc[ai][bj][m][n], 0, 0, 0); __builtin_amdgcn_s_setprio(0); } while (0)
; #define PG8_WAIT_V(n) asm volatile("s_waitcnt vmcnt(" #n ")" ::: "memory")
; #define PG8_WAIT_L(n) asm volatile("s_waitcnt lgkmcnt(" #n ")" ::: "memory")
; template <class Epi, class Sched>
; __device__ __forceinline__ void gemm_phase(LAS unsigned char* lds, const Gemm g, const Sched& S, const Epi& E) {
;     ...
;         for (int t = 0; t < nt; t += 2) {
;             const bool last = (t == nt - 2);
;             const char* a1 = cA + (size_t)(t + 1) * kstep;
;             const char* a2 = last ? nA : cA + (size_t)(t + 2) * kstep; const char* b2 = last ? nB : cB + (size_t)(t + 2) * kstep;
;             const char* a3 = a2 + kstep; const char* b3 = b2 + kstep;
;             PG8_LDB(B0, 0, 0); PG8_SCHED; PG8_LDA(At, 0, 0); PG8_STAGE(PG8_SA(1, 1), a1 + hstep, voffA);
;             PG8_WAIT_L(8); PG8_BAR; PG8_WAIT_L(0); PG8_MMA(0, 0, At, B0); PG8_BAR; PG8_SCHED;
;             PG8_LDB(B1, 0, 1); PG8_STAGE(PG8_SB(0, 0), b2, voffB);
;             PG8_BAR; PG8_WAIT_L(0); PG8_MMA(0, 1, At, B1); PG8_BAR;
;             PG8_LDA(At, 0, 1); PG8_STAGE(PG8_SA(0, 0), a2, voffA);
;             PG8_BAR; PG8_WAIT_L(0); PG8_MMA(1, 0, At, B0); PG8_BAR; PG8_SCHED;
;             PG8_STAGE(PG8_SB(0, 1), b2 + hstep, voffB);
;             PG8_WAIT_V(6); PG8_BAR; PG8_MMA(1, 1, At, B1); PG8_BAR;
.LBB0_113:
	s_add_u32 s54, s52, 0x100
	s_addc_u32 s55, s53, 0
	s_cmp_eq_u32 s73, 4
	s_cselect_b32 s59, s11, s55
	s_cselect_b32 s58, s29, s54
	s_cselect_b32 s57, s41, s72
	s_cselect_b32 s56, s45, s71
	s_add_i32 m0, s25, 0xc000
	ds_read_b128 v[140:143], v226
	global_load_lds_dwordx4 v134, s[52:53]
	s_add_i32 m0, s25, 0xe000
	ds_read_b128 v[144:147], v226 offset:1024
	global_load_lds_dwordx4 v132, s[52:53]
	s_add_i32 s38, 0, 0x10000
	ds_read_b128 v[148:151], v226 offset:2048
	ds_read_b128 v[152:155], v226 offset:3072
	ds_read_b128 v[160:163], v139
	ds_read_b128 v[164:167], v139 offset:1024
	ds_read_b128 v[168:171], v139 offset:2048
	ds_read_b128 v[172:175], v139 offset:3072
	ds_read_b128 v[176:179], v139 offset:4096
	ds_read_b128 v[180:183], v139 offset:5120
	ds_read_b128 v[184:187], v139 offset:6144
	ds_read_b128 v[188:191], v139 offset:7168
	s_add_i32 s52, 0, 0x14000
	ds_read_b128 v[192:195], v226 offset:16384
	ds_read_b128 v[196:199], v226 offset:17408
	ds_read_b128 v[200:203], v226 offset:18432
	ds_read_b128 v[204:207], v226 offset:19456
	s_waitcnt lgkmcnt(4)
	s_barrier
	s_waitcnt lgkmcnt(0)
	v_mfma_f32_16x16x32_bf16 v[126:129], v[140:143], v[160:163], v[126:129]
	v_mfma_f32_16x16x32_bf16 v[122:125], v[148:151], v[160:163], v[122:125]
	v_mfma_f32_16x16x32_bf16 v[118:121], v[140:143], v[168:171], v[118:121]
	v_mfma_f32_16x16x32_bf16 v[114:117], v[148:151], v[168:171], v[114:117]
	v_mfma_f32_16x16x32_bf16 v[106:109], v[140:143], v[176:179], v[106:109]
	v_mfma_f32_16x16x32_bf16 v[98:101], v[148:151], v[176:179], v[98:101]
	v_mfma_f32_16x16x32_bf16 v[90:93], v[140:143], v[184:187], v[90:93]
	v_mfma_f32_16x16x32_bf16 v[82:85], v[148:151], v[184:187], v[82:85]
	v_mfma_f32_16x16x32_bf16 v[126:129], v[144:147], v[164:167], v[126:129]
	v_mfma_f32_16x16x32_bf16 v[122:125], v[152:155], v[164:167], v[122:125]
	v_mfma_f32_16x16x32_bf16 v[118:121], v[144:147], v[172:175], v[118:121]
	v_mfma_f32_16x16x32_bf16 v[114:117], v[152:155], v[172:175], v[114:117]
	v_mfma_f32_16x16x32_bf16 v[106:109], v[144:147], v[180:183], v[106:109]
	v_mfma_f32_16x16x32_bf16 v[98:101], v[152:155], v[180:183], v[98:101]
	v_mfma_f32_16x16x32_bf16 v[90:93], v[144:147], v[188:191], v[90:93]
	v_mfma_f32_16x16x32_bf16 v[82:85], v[152:155], v[188:191], v[82:85]
	v_mfma_f32_16x16x32_bf16 v[110:113], v[192:195], v[160:163], v[110:113]
	v_mfma_f32_16x16x32_bf16 v[102:105], v[200:203], v[160:163], v[102:105]
	v_mfma_f32_16x16x32_bf16 v[94:97], v[192:195], v[168:171], v[94:97]
	v_mfma_f32_16x16x32_bf16 v[86:89], v[200:203], v[168:171], v[86:89]
	v_mfma_f32_16x16x32_bf16 v[78:81], v[192:195], v[176:179], v[78:81]
	v_mfma_f32_16x16x32_bf16 v[74:77], v[200:203], v[176:179], v[74:77]
	v_mfma_f32_16x16x32_bf16 v[70:73], v[192:195], v[184:187], v[70:73]
	v_mfma_f32_16x16x32_bf16 v[66:69], v[200:203], v[184:187], v[66:69]
	v_mfma_f32_16x16x32_bf16 v[110:113], v[196:199], v[164:167], v[110:113]
	v_mfma_f32_16x16x32_bf16 v[102:105], v[204:207], v[164:167], v[102:105]
	v_mfma_f32_16x16x32_bf16 v[94:97], v[196:199], v[172:175], v[94:97]
	v_mfma_f32_16x16x32_bf16 v[86:89], v[204:207], v[172:175], v[86:89]
	v_mfma_f32_16x16x32_bf16 v[78:81], v[196:199], v[180:183], v[78:81]
	v_mfma_f32_16x16x32_bf16 v[74:77], v[204:207], v[180:183], v[74:77]
	v_mfma_f32_16x16x32_bf16 v[70:73], v[196:199], v[188:191], v[70:73]
	v_mfma_f32_16x16x32_bf16 v[66:69], v[204:207], v[188:191], v[66:69]
	s_barrier
	s_add_i32 s38, s38, s65
	s_mov_b32 m0, s38
	ds_read_b128 v[160:163], v139 offset:16384
	global_load_lds_dwordx4 v0, s[56:57]
	s_add_i32 m0, s38, 0x2000
	ds_read_b128 v[164:167], v139 offset:17408
	global_load_lds_dwordx4 v130, s[56:57]
	s_mov_b32 m0, s25
	ds_read_b128 v[168:171], v139 offset:18432
	global_load_lds_dwordx4 v0, s[58:59]
	s_mov_b32 m0, s27
	ds_read_b128 v[172:175], v139 offset:19456
	global_load_lds_dwordx4 v130, s[58:59]
	ds_read_b128 v[176:179], v139 offset:20480
	ds_read_b128 v[180:183], v139 offset:21504
	ds_read_b128 v[184:187], v139 offset:22528
	ds_read_b128 v[188:191], v139 offset:23552
	s_waitcnt vmcnt(4)
	s_waitcnt lgkmcnt(0)
	s_barrier
	v_mfma_f32_16x16x32_bf16 v[62:65], v[140:143], v[160:163], v[62:65]
	v_mfma_f32_16x16x32_bf16 v[58:61], v[148:151], v[160:163], v[58:61]
	v_mfma_f32_16x16x32_bf16 v[54:57], v[140:143], v[168:171], v[54:57]
	v_mfma_f32_16x16x32_bf16 v[50:53], v[148:151], v[168:171], v[50:53]
	v_mfma_f32_16x16x32_bf16 v[38:41], v[140:143], v[176:179], v[38:41]
	v_mfma_f32_16x16x32_bf16 v[34:37], v[148:151], v[176:179], v[34:37]
	v_mfma_f32_16x16x32_bf16 v[22:25], v[140:143], v[184:187], v[22:25]
	v_mfma_f32_16x16x32_bf16 v[18:21], v[148:151], v[184:187], v[18:21]
	v_mfma_f32_16x16x32_bf16 v[62:65], v[144:147], v[164:167], v[62:65]
	v_mfma_f32_16x16x32_bf16 v[58:61], v[152:155], v[164:167], v[58:61]
	v_mfma_f32_16x16x32_bf16 v[54:57], v[144:147], v[172:175], v[54:57]
	v_mfma_f32_16x16x32_bf16 v[50:53], v[152:155], v[172:175], v[50:53]
	v_mfma_f32_16x16x32_bf16 v[38:41], v[144:147], v[180:183], v[38:41]
	v_mfma_f32_16x16x32_bf16 v[34:37], v[152:155], v[180:183], v[34:37]
	v_mfma_f32_16x16x32_bf16 v[22:25], v[144:147], v[188:191], v[22:25]
	v_mfma_f32_16x16x32_bf16 v[18:21], v[152:155], v[188:191], v[18:21]
	v_mfma_f32_16x16x32_bf16 v[46:49], v[192:195], v[160:163], v[46:49]
	v_mfma_f32_16x16x32_bf16 v[42:45], v[200:203], v[160:163], v[42:45]
	v_mfma_f32_16x16x32_bf16 v[30:33], v[192:195], v[168:171], v[30:33]
	v_mfma_f32_16x16x32_bf16 v[26:29], v[200:203], v[168:171], v[26:29]
	v_mfma_f32_16x16x32_bf16 v[14:17], v[192:195], v[176:179], v[14:17]
	v_mfma_f32_16x16x32_bf16 v[10:13], v[200:203], v[176:179], v[10:13]
	v_mfma_f32_16x16x32_bf16 v[6:9], v[192:195], v[184:187], v[6:9]
	v_mfma_f32_16x16x32_bf16 v[2:5], v[200:203], v[184:187], v[2:5]
	v_mfma_f32_16x16x32_bf16 v[46:49], v[196:199], v[164:167], v[46:49]
	v_mfma_f32_16x16x32_bf16 v[42:45], v[204:207], v[164:167], v[42:45]
	v_mfma_f32_16x16x32_bf16 v[30:33], v[196:199], v[172:175], v[30:33]
	v_mfma_f32_16x16x32_bf16 v[26:29], v[204:207], v[172:175], v[26:29]
	v_mfma_f32_16x16x32_bf16 v[14:17], v[196:199], v[180:183], v[14:17]
	v_mfma_f32_16x16x32_bf16 v[10:13], v[204:207], v[180:183], v[10:13]
	v_mfma_f32_16x16x32_bf16 v[6:9], v[196:199], v[188:191], v[6:9]
	v_mfma_f32_16x16x32_bf16 v[2:5], v[204:207], v[188:191], v[2:5]
	s_barrier
; #define PG8_STAGE(bufoff, gbase, voff) do { _Pragma("unroll") for (int _i = 0; _i < 2; ++_i) \
;         __builtin_amdgcn_global_load_lds((const unsigned*)((const char*)(gbase) + (voff)[_i]), (LAS unsigned*)(lds + (bufoff) + ldsw + _i * 8192), 16, 0, 0); } while (0)
; #define PG8_LDA(dst, b, h) do { _Pragma("unroll") for (int m = 0; m < 4; ++m) _Pragma("unroll") for (int k = 0; k < 2; ++k) dst[m][k] = *(const LAS bf16x8*)(lds + PG8_SA(b, h) + aoff + m * 2048 + k * 1024); } while (0)
; #define PG8_LDB(dst, b, h) do { _Pragma("unroll") for (int n = 0; n < 2; ++n) _Pragma("unroll") for (int k = 0; k < 2; ++k) dst[n][k] = *(const LAS bf16x8*)(lds + PG8_SB(b, h) + boff + n * 2048 + k * 1024); } while (0)
; #define PG8_MMA(ai, bj, At, Bt) do { __builtin_amdgcn_s_setprio(1); _Pragma("unroll") for (int m = 0; m < 4; ++m) _Pragma("unroll") for (int n = 0; n < 2; ++n) _Pragma("unroll") for (int k = 0; k < 2; ++k) \
;         acc[ai][bj][m][n] = __builtin_amdgcn_mfma_f32_16x16x32_bf16(Bt[n][k], At[m][k], acc[ai][bj][m][n], 0, 0, 0); __builtin_amdgcn_s_setprio(0); } while (0)
; #define PG8_WAIT_L(n) asm volatile("s_waitcnt lgkmcnt(" #n ")" ::: "memory")
; #define PG8_BAR __builtin_amdgcn_s_barrier()
; #define PG8_SCHED __builtin_amdgcn_sched_barrier(0)
; template <class Epi, class Sched>
; __device__ __forceinline__ void gemm_phase(LAS unsigned char* lds, const Gemm g, const Sched& S, const Epi& E) {
;     ...
;             PG8_LDB(B0, 1, 0); PG8_SCHED; PG8_LDA(At, 1, 0); PG8_STAGE(PG8_SA(0, 1), a2 + hstep, voffA);
;             PG8_WAIT_L(8); PG8_BAR; PG8_WAIT_L(0); PG8_MMA(0, 0, At, B0); PG8_BAR; PG8_SCHED;
;             PG8_LDB(B1, 1, 1); PG8_STAGE(PG8_SB(1, 0), b3, voffB);
;             PG8_BAR; PG8_WAIT_L(0); PG8_MMA(0, 1, At, B1); PG8_BAR;
;             PG8_LDA(At, 1, 1); PG8_STAGE(PG8_SA(1, 0), a3, voffA);
;             PG8_BAR; PG8_WAIT_L(0); PG8_MMA(1, 0, At, B0); PG8_BAR; PG8_SCHED;
	s_add_u32 s38, s56, 0x80000
	s_addc_u32 s39, s57, 0
	s_add_i32 s52, s52, s65
	s_mov_b32 m0, s52
	ds_read_b128 v[140:143], v226 offset:32768
	global_load_lds_dwordx4 v0, s[38:39]
	s_add_i32 m0, s52, 0x2000
	ds_read_b128 v[144:147], v226 offset:33792
	global_load_lds_dwordx4 v130, s[38:39]
	s_add_u32 s38, s58, 0x80000
	s_addc_u32 s39, s59, 0
	s_mov_b32 m0, s66
	ds_read_b128 v[148:151], v226 offset:34816
	global_load_lds_dwordx4 v0, s[38:39]
	s_mov_b32 m0, s67
	ds_read_b128 v[152:155], v226 offset:35840
	global_load_lds_dwordx4 v130, s[38:39]
	s_add_i32 s52, 0, 0x18000
	ds_read_b128 v[160:163], v139 offset:32768
	ds_read_b128 v[164:167], v139 offset:33792
	ds_read_b128 v[168:171], v139 offset:34816
	ds_read_b128 v[172:175], v139 offset:35840
	ds_read_b128 v[176:179], v139 offset:36864
	ds_read_b128 v[180:183], v139 offset:37888
	ds_read_b128 v[184:187], v139 offset:38912
	ds_read_b128 v[188:191], v139 offset:39936
	s_add_i32 s53, 0, 0x1c000
	ds_read_b128 v[192:195], v226 offset:49152
	ds_read_b128 v[196:199], v226 offset:50176
	ds_read_b128 v[200:203], v226 offset:51200
	ds_read_b128 v[204:207], v226 offset:52224
	s_waitcnt lgkmcnt(4)
	s_barrier
	s_waitcnt lgkmcnt(0)
	v_mfma_f32_16x16x32_bf16 v[126:129], v[140:143], v[160:163], v[126:129]
	v_mfma_f32_16x16x32_bf16 v[122:125], v[148:151], v[160:163], v[122:125]
	v_mfma_f32_16x16x32_bf16 v[118:121], v[140:143], v[168:171], v[118:121]
	v_mfma_f32_16x16x32_bf16 v[114:117], v[148:151], v[168:171], v[114:117]
	v_mfma_f32_16x16x32_bf16 v[106:109], v[140:143], v[176:179], v[106:109]
	v_mfma_f32_16x16x32_bf16 v[98:101], v[148:151], v[176:179], v[98:101]
	v_mfma_f32_16x16x32_bf16 v[90:93], v[140:143], v[184:187], v[90:93]
	v_mfma_f32_16x16x32_bf16 v[82:85], v[148:151], v[184:187], v[82:85]
	v_mfma_f32_16x16x32_bf16 v[126:129], v[144:147], v[164:167], v[126:129]
	v_mfma_f32_16x16x32_bf16 v[122:125], v[152:155], v[164:167], v[122:125]
	v_mfma_f32_16x16x32_bf16 v[118:121], v[144:147], v[172:175], v[118:121]
	v_mfma_f32_16x16x32_bf16 v[114:117], v[152:155], v[172:175], v[114:117]
	v_mfma_f32_16x16x32_bf16 v[106:109], v[144:147], v[180:183], v[106:109]
	v_mfma_f32_16x16x32_bf16 v[98:101], v[152:155], v[180:183], v[98:101]
	v_mfma_f32_16x16x32_bf16 v[90:93], v[144:147], v[188:191], v[90:93]
	v_mfma_f32_16x16x32_bf16 v[82:85], v[152:155], v[188:191], v[82:85]
	v_mfma_f32_16x16x32_bf16 v[110:113], v[192:195], v[160:163], v[110:113]
	v_mfma_f32_16x16x32_bf16 v[102:105], v[200:203], v[160:163], v[102:105]
	v_mfma_f32_16x16x32_bf16 v[94:97], v[192:195], v[168:171], v[94:97]
	v_mfma_f32_16x16x32_bf16 v[86:89], v[200:203], v[168:171], v[86:89]
	v_mfma_f32_16x16x32_bf16 v[78:81], v[192:195], v[176:179], v[78:81]
	v_mfma_f32_16x16x32_bf16 v[74:77], v[200:203], v[176:179], v[74:77]
	v_mfma_f32_16x16x32_bf16 v[70:73], v[192:195], v[184:187], v[70:73]
	v_mfma_f32_16x16x32_bf16 v[66:69], v[200:203], v[184:187], v[66:69]
	v_mfma_f32_16x16x32_bf16 v[110:113], v[196:199], v[164:167], v[110:113]
	v_mfma_f32_16x16x32_bf16 v[102:105], v[204:207], v[164:167], v[102:105]
	v_mfma_f32_16x16x32_bf16 v[94:97], v[196:199], v[172:175], v[94:97]
	v_mfma_f32_16x16x32_bf16 v[86:89], v[204:207], v[172:175], v[86:89]
	v_mfma_f32_16x16x32_bf16 v[78:81], v[196:199], v[180:183], v[78:81]
	v_mfma_f32_16x16x32_bf16 v[74:77], v[204:207], v[180:183], v[74:77]
	v_mfma_f32_16x16x32_bf16 v[70:73], v[196:199], v[188:191], v[70:73]
	v_mfma_f32_16x16x32_bf16 v[66:69], v[204:207], v[188:191], v[66:69]
	s_barrier
	s_add_i32 s38, s52, s65
	s_add_u32 s100, s56, s36
	s_addc_u32 s101, s57, s37
	s_mov_b32 m0, s38
	ds_read_b128 v[160:163], v139 offset:49152
	global_load_lds_dwordx4 v0, s[100:101]
	s_add_i32 m0, s38, 0x2000
	ds_read_b128 v[164:167], v139 offset:50176
	global_load_lds_dwordx4 v130, s[100:101]
	s_mov_b32 m0, s68
	s_add_u32 s100, s58, s36
	s_addc_u32 s101, s59, s37
	global_load_lds_dwordx4 v0, s[100:101]
	s_mov_b32 m0, s69
	ds_read_b128 v[168:171], v139 offset:51200
	global_load_lds_dwordx4 v130, s[100:101]
	ds_read_b128 v[172:175], v139 offset:52224
	ds_read_b128 v[176:179], v139 offset:53248
	ds_read_b128 v[180:183], v139 offset:54272
	ds_read_b128 v[184:187], v139 offset:55296
	ds_read_b128 v[188:191], v139 offset:56320
	s_waitcnt vmcnt(4)
	s_waitcnt lgkmcnt(0)
	s_barrier
; #define PG8_STAGE(bufoff, gbase, voff) do { _Pragma("unroll") for (int _i = 0; _i < 2; ++_i) \
;         __builtin_amdgcn_global_load_lds((const unsigned*)((const char*)(gbase) + (voff)[_i]), (LAS unsigned*)(lds + (bufoff) + ldsw + _i * 8192), 16, 0, 0); } while (0)
; #define PG8_MMA(ai, bj, At, Bt) do { __builtin_amdgcn_s_setprio(1); _Pragma("unroll") for (int m = 0; m < 4; ++m) _Pragma("unroll") for (int n = 0; n < 2; ++n) _Pragma("unroll") for (int k = 0; k < 2; ++k) \
;         acc[ai][bj][m][n] = __builtin_amdgcn_mfma_f32_16x16x32_bf16(Bt[n][k], At[m][k], acc[ai][bj][m][n], 0, 0, 0); __builtin_amdgcn_s_setprio(0); } while (0)
; #define PG8_WAIT_V(n) asm volatile("s_waitcnt vmcnt(" #n ")" ::: "memory")
; #define PG8_BAR __builtin_amdgcn_s_barrier()
;     __device__ __forceinline__ void operator()(const f32x4 (&acc)[2][2][4][2], const Unit& u, int wr, int wc, int fr, int fq) const {
;         const int row0 = u.pm * BM + wr * 64 + fr, col0 = u.pn * BM + wc * 32 + 4 * fq;
;         float* base = part + (size_t)u.ks * Mp * ldc;
; #pragma unroll
;         for (int ai = 0; ai < 2; ++ai)
; #pragma unroll
;             for (int m = 0; m < 4; ++m) { float* rowp = base + (size_t)(row0 + ai * HALF + m * 16) * ldc + col0;
; #pragma unroll
;                 for (int bj = 0; bj < 2; ++bj)
; #pragma unroll
;                     for (int n = 0; n < 2; ++n) *(f32x4*)(rowp + bj * HALF + n * 16) = acc[ai][bj][m][n]; }
; template <class Epi, class Sched>
; __device__ __forceinline__ void gemm_phase(LAS unsigned char* lds, const Gemm g, const Sched& S, const Epi& E) {
;     ...
;             PG8_STAGE(PG8_SB(1, 1), b3 + hstep, voffB);
;             PG8_WAIT_V(6); PG8_BAR; PG8_MMA(1, 1, At, B1); PG8_BAR;
	v_mfma_f32_16x16x32_bf16 v[62:65], v[140:143], v[160:163], v[62:65]
	v_mfma_f32_16x16x32_bf16 v[58:61], v[148:151], v[160:163], v[58:61]
	v_mfma_f32_16x16x32_bf16 v[54:57], v[140:143], v[168:171], v[54:57]
	v_mfma_f32_16x16x32_bf16 v[50:53], v[148:151], v[168:171], v[50:53]
	v_mfma_f32_16x16x32_bf16 v[38:41], v[140:143], v[176:179], v[38:41]
	v_mfma_f32_16x16x32_bf16 v[34:37], v[148:151], v[176:179], v[34:37]
	v_mfma_f32_16x16x32_bf16 v[22:25], v[140:143], v[184:187], v[22:25]
	v_mfma_f32_16x16x32_bf16 v[18:21], v[148:151], v[184:187], v[18:21]
	v_mfma_f32_16x16x32_bf16 v[62:65], v[144:147], v[164:167], v[62:65]
	v_mfma_f32_16x16x32_bf16 v[58:61], v[152:155], v[164:167], v[58:61]
	v_mfma_f32_16x16x32_bf16 v[54:57], v[144:147], v[172:175], v[54:57]
	v_mfma_f32_16x16x32_bf16 v[50:53], v[152:155], v[172:175], v[50:53]
	v_mfma_f32_16x16x32_bf16 v[38:41], v[144:147], v[180:183], v[38:41]
	v_mfma_f32_16x16x32_bf16 v[34:37], v[152:155], v[180:183], v[34:37]
	v_mfma_f32_16x16x32_bf16 v[22:25], v[144:147], v[188:191], v[22:25]
	v_mfma_f32_16x16x32_bf16 v[18:21], v[152:155], v[188:191], v[18:21]
	s_add_u32 s38, s56, 0x80080
	s_addc_u32 s39, s57, 0
	s_add_i32 s52, s53, s65
	s_mov_b32 m0, s52
	s_nop 0
	global_load_lds_dwordx4 v0, s[38:39]
	s_add_i32 m0, s52, 0x2000
	s_nop 0
	global_load_lds_dwordx4 v130, s[38:39]
	v_mfma_f32_16x16x32_bf16 v[46:49], v[192:195], v[160:163], v[46:49]
	v_mfma_f32_16x16x32_bf16 v[42:45], v[200:203], v[160:163], v[42:45]
	v_mfma_f32_16x16x32_bf16 v[30:33], v[192:195], v[168:171], v[30:33]
	v_mfma_f32_16x16x32_bf16 v[26:29], v[200:203], v[168:171], v[26:29]
	v_mfma_f32_16x16x32_bf16 v[14:17], v[192:195], v[176:179], v[14:17]
	v_mfma_f32_16x16x32_bf16 v[10:13], v[200:203], v[176:179], v[10:13]
	v_mfma_f32_16x16x32_bf16 v[6:9], v[192:195], v[184:187], v[6:9]
	v_mfma_f32_16x16x32_bf16 v[2:5], v[200:203], v[184:187], v[2:5]
	v_mfma_f32_16x16x32_bf16 v[46:49], v[196:199], v[164:167], v[46:49]
	v_mfma_f32_16x16x32_bf16 v[42:45], v[204:207], v[164:167], v[42:45]
	v_mfma_f32_16x16x32_bf16 v[30:33], v[196:199], v[172:175], v[30:33]
	v_mfma_f32_16x16x32_bf16 v[26:29], v[204:207], v[172:175], v[26:29]
	v_mfma_f32_16x16x32_bf16 v[14:17], v[196:199], v[180:183], v[14:17]
	v_mfma_f32_16x16x32_bf16 v[10:13], v[204:207], v[180:183], v[10:13]
	v_mfma_f32_16x16x32_bf16 v[6:9], v[196:199], v[188:191], v[6:9]
	v_mfma_f32_16x16x32_bf16 v[2:5], v[204:207], v[188:191], v[2:5]
	s_add_i32 s73, s73, 2
	s_add_u32 s71, s71, 0x100
	s_addc_u32 s72, s72, 0
	s_cmp_gt_u32 s73, 5
	s_mov_b64 s[52:53], s[54:55]
	s_barrier
	s_cbranch_scc0 .LBB0_113
	s_ashr_i32 s11, s10, 31
	s_lshl_b64 s[10:11], s[10:11], 24
	v_lshl_or_b32 v140, s26, 8, v138
	s_add_u32 s10, s8, s10
	v_lshl_add_u32 v142, s24, 8, v136
	s_addc_u32 s11, s9, s11
	v_ashrrev_i32_e32 v141, 31, v140
	v_ashrrev_i32_e32 v143, 31, v142
	v_lshl_add_u64 v[140:141], v[140:141], 2, s[10:11]
	v_lshlrev_b64 v[144:145], 13, v[142:143]
	v_lshl_add_u64 v[144:145], v[140:141], 0, v[144:145]
	global_store_dwordx4 v[144:145], v[126:129], off
	global_store_dwordx4 v[144:145], v[122:125], off offset:64
	global_store_dwordx4 v[144:145], v[110:113], off offset:512
	global_store_dwordx4 v[144:145], v[102:105], off offset:576
	s_mov_b64 s[10:11], 0x100000
	s_mov_b32 s26, s40
	v_or_b32_e32 v102, 16, v142
	v_ashrrev_i32_e32 v103, 31, v102
	v_lshlrev_b64 v[102:103], 13, v[102:103]
	v_lshl_add_u64 v[102:103], v[140:141], 0, v[102:103]
	global_store_dwordx4 v[102:103], v[118:121], off
	global_store_dwordx4 v[102:103], v[114:117], off offset:64
	global_store_dwordx4 v[102:103], v[94:97], off offset:512
	global_store_dwordx4 v[102:103], v[86:89], off offset:576
	s_mov_b32 s24, s44
	s_mov_b64 s[54:55], s[50:51]
	v_or_b32_e32 v86, 32, v142
	v_ashrrev_i32_e32 v87, 31, v86
	v_lshlrev_b64 v[86:87], 13, v[86:87]
	v_lshl_add_u64 v[86:87], v[140:141], 0, v[86:87]
	global_store_dwordx4 v[86:87], v[106:109], off
	global_store_dwordx4 v[86:87], v[98:101], off offset:64
	global_store_dwordx4 v[86:87], v[78:81], off offset:512
	global_store_dwordx4 v[86:87], v[74:77], off offset:576
	s_mov_b64 s[52:53], s[48:49]
	s_nop 0
	v_or_b32_e32 v74, 48, v142
	v_ashrrev_i32_e32 v75, 31, v74
	v_lshlrev_b64 v[74:75], 13, v[74:75]
	v_lshl_add_u64 v[74:75], v[140:141], 0, v[74:75]
	global_store_dwordx4 v[74:75], v[90:93], off
	global_store_dwordx4 v[74:75], v[82:85], off offset:64
	global_store_dwordx4 v[74:75], v[70:73], off offset:512
	global_store_dwordx4 v[74:75], v[66:69], off offset:576
	s_nop 1
	v_add_co_u32_e32 v68, vcc, s93, v144
	v_lshl_add_u64 v[66:67], v[144:145], 0, s[10:11]
	s_nop 0
	v_addc_co_u32_e32 v69, vcc, 0, v145, vcc
	s_mov_b64 s[10:11], 0x120000
	global_store_dwordx4 v[68:69], v[62:65], off
	global_store_dwordx4 v[66:67], v[58:61], off offset:64
	global_store_dwordx4 v[66:67], v[46:49], off offset:512
	global_store_dwordx4 v[66:67], v[42:45], off offset:576
	s_nop 1
	v_lshl_add_u64 v[42:43], v[144:145], 0, s[10:11]
	s_mov_b32 s10, 0x120000
	v_add_co_u32_e32 v44, vcc, s10, v144
	s_mov_b64 s[10:11], 0x140000
	s_nop 0
	v_addc_co_u32_e32 v45, vcc, 0, v145, vcc
	global_store_dwordx4 v[44:45], v[54:57], off
	global_store_dwordx4 v[42:43], v[50:53], off offset:64
	global_store_dwordx4 v[42:43], v[30:33], off offset:512
	global_store_dwordx4 v[42:43], v[26:29], off offset:576
	s_nop 1
	v_lshl_add_u64 v[26:27], v[144:145], 0, s[10:11]
	s_mov_b32 s10, 0x140000
	v_add_co_u32_e32 v28, vcc, s10, v144
	s_mov_b64 s[10:11], 0x160000
	s_nop 0
	v_addc_co_u32_e32 v29, vcc, 0, v145, vcc
	global_store_dwordx4 v[28:29], v[38:41], off
	global_store_dwordx4 v[26:27], v[34:37], off offset:64
	global_store_dwordx4 v[26:27], v[14:17], off offset:512
	global_store_dwordx4 v[26:27], v[10:13], off offset:576
	s_nop 1
	v_add_co_u32_e32 v12, vcc, 0x160000, v144
	v_lshl_add_u64 v[10:11], v[144:145], 0, s[10:11]
	s_nop 0
	v_addc_co_u32_e32 v13, vcc, 0, v145, vcc
	s_and_b64 vcc, exec, s[46:47]
	s_mov_b32 s10, s28
	global_store_dwordx4 v[12:13], v[22:25], off
	global_store_dwordx4 v[10:11], v[18:21], off offset:64
	global_store_dwordx4 v[10:11], v[6:9], off offset:512
	global_store_dwordx4 v[10:11], v[2:5], off offset:576
	s_cbranch_vccz .LBB0_110
	s_waitcnt vmcnt(0)
	s_cmpk_gt_u32 s60, 0xff
	s_cbranch_scc1 .LBB0_117
	s_barrier

; #define PG8_STAGE(bufoff, gbase, voff) do { _Pragma("unroll") for (int _i = 0; _i < 2; ++_i) \
;         __builtin_amdgcn_global_load_lds((const unsigned*)((const char*)(gbase) + (voff)[_i]), (LAS unsigned*)(lds + (bufoff) + ldsw + _i * 8192), 16, 0, 0); } while (0)
; #define PG8_LDA(dst, b, h) do { _Pragma("unroll") for (int m = 0; m < 4; ++m) _Pragma("unroll") for (int k = 0; k < 2; ++k) dst[m][k] = *(const LAS bf16x8*)(lds + PG8_SA(b, h) + aoff + m * 2048 + k * 1024); } while (0)
; #define PG8_LDB(dst, b, h) do { _Pragma("unroll") for (int n = 0; n < 2; ++n) _Pragma("unroll") for (int k = 0; k < 2; ++k) dst[n][k] = *(const LAS bf16x8*)(lds + PG8_SB(b, h) + boff + n * 2048 + k * 1024); } while (0)
; #define PG8_MMA(ai, bj, At, Bt) do { __builtin_amdgcn_s_setprio(1); _Pragma("unroll") for (int m = 0; m < 4; ++m) _Pragma("unroll") for (int n = 0; n < 2; ++n) _Pragma("unroll") for (int k = 0; k < 2; ++k) \
;         acc[ai][bj][m][n] = __builtin_amdgcn_mfma_f32_16x16x32_bf16(Bt[n][k], At[m][k], acc[ai][bj][m][n], 0, 0, 0); __builtin_amdgcn_s_setprio(0); } while (0)
; #define PG8_WAIT_V(n) asm volatile("s_waitcnt vmcnt(" #n ")" ::: "memory")
; #define PG8_WAIT_L(n) asm volatile("s_waitcnt lgkmcnt(" #n ")" ::: "memory")
; template <class Epi, class Sched>
; __device__ __forceinline__ void gemm_phase(LAS unsigned char* lds, const Gemm g, const Sched& S, const Epi& E) {
;     ...
;         for (int t = 0; t < nt; t += 2) {
;             const bool last = (t == nt - 2);
;             const char* a1 = cA + (size_t)(t + 1) * kstep;
;             const char* a2 = last ? nA : cA + (size_t)(t + 2) * kstep; const char* b2 = last ? nB : cB + (size_t)(t + 2) * kstep;
;             const char* a3 = a2 + kstep; const char* b3 = b2 + kstep;
;             PG8_LDB(B0, 0, 0); PG8_SCHED; PG8_LDA(At, 0, 0); PG8_STAGE(PG8_SA(1, 1), a1 + hstep, voffA);
;             PG8_WAIT_L(8); PG8_BAR; PG8_WAIT_L(0); PG8_MMA(0, 0, At, B0); PG8_BAR; PG8_SCHED;
;             PG8_LDB(B1, 0, 1); PG8_STAGE(PG8_SB(0, 0), b2, voffB);
;             PG8_BAR; PG8_WAIT_L(0); PG8_MMA(0, 1, At, B1); PG8_BAR;
;             PG8_LDA(At, 0, 1); PG8_STAGE(PG8_SA(0, 0), a2, voffA);
;             PG8_BAR; PG8_WAIT_L(0); PG8_MMA(1, 0, At, B0); PG8_BAR; PG8_SCHED;
;             PG8_STAGE(PG8_SB(0, 1), b2 + hstep, voffB);
;             PG8_WAIT_V(6); PG8_BAR; PG8_MMA(1, 1, At, B1); PG8_BAR;
.LBB0_354:
	s_add_u32 s38, s50, 0xfff80080
	s_addc_u32 s39, s51, -1
	s_cmp_eq_u32 s70, 28
	s_cselect_b32 s55, s9, s39
	s_cselect_b32 s54, s66, s38
	s_cselect_b32 s53, s43, s69
	s_cselect_b32 s52, s67, s68
	s_add_i32 m0, s29, 0xc000
	ds_read_b128 v[140:143], v226
	global_load_lds_dwordx4 v138, s[50:51]
	s_add_i32 m0, s29, 0xe000
	ds_read_b128 v[148:151], v226 offset:1024
	global_load_lds_dwordx4 v136, s[50:51]
	s_add_i32 s71, 0, 0x10000
	ds_read_b128 v[152:155], v226 offset:2048
	ds_read_b128 v[160:163], v226 offset:3072
	ds_read_b128 v[164:167], v147
	ds_read_b128 v[168:171], v147 offset:1024
	ds_read_b128 v[172:175], v147 offset:2048
	ds_read_b128 v[176:179], v147 offset:3072
	ds_read_b128 v[180:183], v147 offset:4096
	ds_read_b128 v[184:187], v147 offset:5120
	ds_read_b128 v[188:191], v147 offset:6144
	ds_read_b128 v[192:195], v147 offset:7168
	s_add_i32 s38, 0, 0x14000
	ds_read_b128 v[196:199], v226 offset:16384
	ds_read_b128 v[200:203], v226 offset:17408
	ds_read_b128 v[204:207], v226 offset:18432
	ds_read_b128 v[210:213], v226 offset:19456
	s_waitcnt lgkmcnt(4)
	s_barrier
	s_waitcnt lgkmcnt(0)
	v_mfma_f32_16x16x32_bf16 v[126:129], v[140:143], v[164:167], v[126:129]
	v_mfma_f32_16x16x32_bf16 v[122:125], v[152:155], v[164:167], v[122:125]
	v_mfma_f32_16x16x32_bf16 v[118:121], v[140:143], v[172:175], v[118:121]
	v_mfma_f32_16x16x32_bf16 v[110:113], v[152:155], v[172:175], v[110:113]
	v_mfma_f32_16x16x32_bf16 v[102:105], v[140:143], v[180:183], v[102:105]
	v_mfma_f32_16x16x32_bf16 v[94:97], v[152:155], v[180:183], v[94:97]
	v_mfma_f32_16x16x32_bf16 v[86:89], v[140:143], v[188:191], v[86:89]
	v_mfma_f32_16x16x32_bf16 v[78:81], v[152:155], v[188:191], v[78:81]
	v_mfma_f32_16x16x32_bf16 v[126:129], v[148:151], v[168:171], v[126:129]
	v_mfma_f32_16x16x32_bf16 v[122:125], v[160:163], v[168:171], v[122:125]
	v_mfma_f32_16x16x32_bf16 v[118:121], v[148:151], v[176:179], v[118:121]
	v_mfma_f32_16x16x32_bf16 v[110:113], v[160:163], v[176:179], v[110:113]
	v_mfma_f32_16x16x32_bf16 v[102:105], v[148:151], v[184:187], v[102:105]
	v_mfma_f32_16x16x32_bf16 v[94:97], v[160:163], v[184:187], v[94:97]
	v_mfma_f32_16x16x32_bf16 v[86:89], v[148:151], v[192:195], v[86:89]
	v_mfma_f32_16x16x32_bf16 v[78:81], v[160:163], v[192:195], v[78:81]
	v_mfma_f32_16x16x32_bf16 v[114:117], v[196:199], v[164:167], v[114:117]
	v_mfma_f32_16x16x32_bf16 v[106:109], v[204:207], v[164:167], v[106:109]
	v_mfma_f32_16x16x32_bf16 v[98:101], v[196:199], v[172:175], v[98:101]
	v_mfma_f32_16x16x32_bf16 v[90:93], v[204:207], v[172:175], v[90:93]
	v_mfma_f32_16x16x32_bf16 v[82:85], v[196:199], v[180:183], v[82:85]
	v_mfma_f32_16x16x32_bf16 v[74:77], v[204:207], v[180:183], v[74:77]
	v_mfma_f32_16x16x32_bf16 v[70:73], v[196:199], v[188:191], v[70:73]
	v_mfma_f32_16x16x32_bf16 v[66:69], v[204:207], v[188:191], v[66:69]
	v_mfma_f32_16x16x32_bf16 v[114:117], v[200:203], v[168:171], v[114:117]
	v_mfma_f32_16x16x32_bf16 v[106:109], v[210:213], v[168:171], v[106:109]
	v_mfma_f32_16x16x32_bf16 v[98:101], v[200:203], v[176:179], v[98:101]
	v_mfma_f32_16x16x32_bf16 v[90:93], v[210:213], v[176:179], v[90:93]
	v_mfma_f32_16x16x32_bf16 v[82:85], v[200:203], v[184:187], v[82:85]
	v_mfma_f32_16x16x32_bf16 v[74:77], v[210:213], v[184:187], v[74:77]
	v_mfma_f32_16x16x32_bf16 v[70:73], v[200:203], v[192:195], v[70:73]
	v_mfma_f32_16x16x32_bf16 v[66:69], v[210:213], v[192:195], v[66:69]
	s_barrier
	s_add_i32 s39, s71, s56
	s_mov_b32 m0, s39
	ds_read_b128 v[164:167], v147 offset:16384
	global_load_lds_dwordx4 v0, s[52:53]
	s_add_i32 m0, s39, 0x2000
	ds_read_b128 v[168:171], v147 offset:17408
	global_load_lds_dwordx4 v134, s[52:53]
	s_mov_b32 m0, s29
	ds_read_b128 v[172:175], v147 offset:18432
	global_load_lds_dwordx4 v130, s[54:55]
	s_mov_b32 m0, s41
	ds_read_b128 v[176:179], v147 offset:19456
	global_load_lds_dwordx4 v132, s[54:55]
	ds_read_b128 v[180:183], v147 offset:20480
	ds_read_b128 v[184:187], v147 offset:21504
	ds_read_b128 v[188:191], v147 offset:22528
	ds_read_b128 v[192:195], v147 offset:23552
	s_waitcnt vmcnt(4)
	s_waitcnt lgkmcnt(0)
	s_barrier
	v_mfma_f32_16x16x32_bf16 v[62:65], v[140:143], v[164:167], v[62:65]
	v_mfma_f32_16x16x32_bf16 v[58:61], v[152:155], v[164:167], v[58:61]
	v_mfma_f32_16x16x32_bf16 v[54:57], v[140:143], v[172:175], v[54:57]
	v_mfma_f32_16x16x32_bf16 v[46:49], v[152:155], v[172:175], v[46:49]
	v_mfma_f32_16x16x32_bf16 v[38:41], v[140:143], v[180:183], v[38:41]
	v_mfma_f32_16x16x32_bf16 v[30:33], v[152:155], v[180:183], v[30:33]
	v_mfma_f32_16x16x32_bf16 v[22:25], v[140:143], v[188:191], v[22:25]
	v_mfma_f32_16x16x32_bf16 v[14:17], v[152:155], v[188:191], v[14:17]
	v_mfma_f32_16x16x32_bf16 v[62:65], v[148:151], v[168:171], v[62:65]
	v_mfma_f32_16x16x32_bf16 v[58:61], v[160:163], v[168:171], v[58:61]
	v_mfma_f32_16x16x32_bf16 v[54:57], v[148:151], v[176:179], v[54:57]
	v_mfma_f32_16x16x32_bf16 v[46:49], v[160:163], v[176:179], v[46:49]
	v_mfma_f32_16x16x32_bf16 v[38:41], v[148:151], v[184:187], v[38:41]
	v_mfma_f32_16x16x32_bf16 v[30:33], v[160:163], v[184:187], v[30:33]
	v_mfma_f32_16x16x32_bf16 v[22:25], v[148:151], v[192:195], v[22:25]
	v_mfma_f32_16x16x32_bf16 v[14:17], v[160:163], v[192:195], v[14:17]
	v_mfma_f32_16x16x32_bf16 v[50:53], v[196:199], v[164:167], v[50:53]
	v_mfma_f32_16x16x32_bf16 v[42:45], v[204:207], v[164:167], v[42:45]
	v_mfma_f32_16x16x32_bf16 v[34:37], v[196:199], v[172:175], v[34:37]
	v_mfma_f32_16x16x32_bf16 v[26:29], v[204:207], v[172:175], v[26:29]
	v_mfma_f32_16x16x32_bf16 v[18:21], v[196:199], v[180:183], v[18:21]
	v_mfma_f32_16x16x32_bf16 v[10:13], v[204:207], v[180:183], v[10:13]
	v_mfma_f32_16x16x32_bf16 v[6:9], v[196:199], v[188:191], v[6:9]
	v_mfma_f32_16x16x32_bf16 v[2:5], v[204:207], v[188:191], v[2:5]
	v_mfma_f32_16x16x32_bf16 v[50:53], v[200:203], v[168:171], v[50:53]
	v_mfma_f32_16x16x32_bf16 v[42:45], v[210:213], v[168:171], v[42:45]
	v_mfma_f32_16x16x32_bf16 v[34:37], v[200:203], v[176:179], v[34:37]
	v_mfma_f32_16x16x32_bf16 v[26:29], v[210:213], v[176:179], v[26:29]
	v_mfma_f32_16x16x32_bf16 v[18:21], v[200:203], v[184:187], v[18:21]
	v_mfma_f32_16x16x32_bf16 v[10:13], v[210:213], v[184:187], v[10:13]
	v_mfma_f32_16x16x32_bf16 v[6:9], v[200:203], v[192:195], v[6:9]
	v_mfma_f32_16x16x32_bf16 v[2:5], v[210:213], v[192:195], v[2:5]
	s_barrier
; #define PG8_STAGE(bufoff, gbase, voff) do { _Pragma("unroll") for (int _i = 0; _i < 2; ++_i) \
;         __builtin_amdgcn_global_load_lds((const unsigned*)((const char*)(gbase) + (voff)[_i]), (LAS unsigned*)(lds + (bufoff) + ldsw + _i * 8192), 16, 0, 0); } while (0)
; #define PG8_LDA(dst, b, h) do { _Pragma("unroll") for (int m = 0; m < 4; ++m) _Pragma("unroll") for (int k = 0; k < 2; ++k) dst[m][k] = *(const LAS bf16x8*)(lds + PG8_SA(b, h) + aoff + m * 2048 + k * 1024); } while (0)
; #define PG8_LDB(dst, b, h) do { _Pragma("unroll") for (int n = 0; n < 2; ++n) _Pragma("unroll") for (int k = 0; k < 2; ++k) dst[n][k] = *(const LAS bf16x8*)(lds + PG8_SB(b, h) + boff + n * 2048 + k * 1024); } while (0)
; #define PG8_MMA(ai, bj, At, Bt) do { __builtin_amdgcn_s_setprio(1); _Pragma("unroll") for (int m = 0; m < 4; ++m) _Pragma("unroll") for (int n = 0; n < 2; ++n) _Pragma("unroll") for (int k = 0; k < 2; ++k) \
;         acc[ai][bj][m][n] = __builtin_amdgcn_mfma_f32_16x16x32_bf16(Bt[n][k], At[m][k], acc[ai][bj][m][n], 0, 0, 0); __builtin_amdgcn_s_setprio(0); } while (0)
; #define PG8_WAIT_V(n) asm volatile("s_waitcnt vmcnt(" #n ")" ::: "memory")
; #define PG8_WAIT_L(n) asm volatile("s_waitcnt lgkmcnt(" #n ")" ::: "memory")
; #define PG8_BAR __builtin_amdgcn_s_barrier()
; #define PG8_SCHED __builtin_amdgcn_sched_barrier(0)
; template <class Epi, class Sched>
; __device__ __forceinline__ void gemm_phase(LAS unsigned char* lds, const Gemm g, const Sched& S, const Epi& E) {
;     ...
;             PG8_LDB(B0, 1, 0); PG8_SCHED; PG8_LDA(At, 1, 0); PG8_STAGE(PG8_SA(0, 1), a2 + hstep, voffA);
;             PG8_WAIT_L(8); PG8_BAR; PG8_WAIT_L(0); PG8_MMA(0, 0, At, B0); PG8_BAR; PG8_SCHED;
;             PG8_LDB(B1, 1, 1); PG8_STAGE(PG8_SB(1, 0), b3, voffB);
;             PG8_BAR; PG8_WAIT_L(0); PG8_MMA(0, 1, At, B1); PG8_BAR;
;             PG8_LDA(At, 1, 1); PG8_STAGE(PG8_SA(1, 0), a3, voffA);
;             PG8_BAR; PG8_WAIT_L(0); PG8_MMA(1, 0, At, B0); PG8_BAR; PG8_SCHED;
;             PG8_STAGE(PG8_SB(1, 1), b3 + hstep, voffB);
;             PG8_WAIT_V(6); PG8_BAR; PG8_MMA(1, 1, At, B1); PG8_BAR;
	s_add_u32 s72, s52, 0x80000
	s_addc_u32 s73, s53, 0
	s_add_i32 s38, s38, s56
	s_mov_b32 m0, s38
	ds_read_b128 v[140:143], v226 offset:32768
	global_load_lds_dwordx4 v0, s[72:73]
	s_add_i32 m0, s38, 0x2000
	ds_read_b128 v[148:151], v226 offset:33792
	global_load_lds_dwordx4 v134, s[72:73]
	s_add_u32 s54, s54, 0x80000
	s_addc_u32 s55, s55, 0
	s_mov_b32 m0, s57
	ds_read_b128 v[152:155], v226 offset:34816
	global_load_lds_dwordx4 v130, s[54:55]
	s_mov_b32 m0, s58
	ds_read_b128 v[160:163], v226 offset:35840
	global_load_lds_dwordx4 v132, s[54:55]
	s_add_i32 s38, 0, 0x18000
	ds_read_b128 v[164:167], v147 offset:32768
	ds_read_b128 v[168:171], v147 offset:33792
	ds_read_b128 v[172:175], v147 offset:34816
	ds_read_b128 v[176:179], v147 offset:35840
	ds_read_b128 v[180:183], v147 offset:36864
	ds_read_b128 v[184:187], v147 offset:37888
	ds_read_b128 v[188:191], v147 offset:38912
	ds_read_b128 v[192:195], v147 offset:39936
	s_add_i32 s39, 0, 0x1c000
	ds_read_b128 v[196:199], v226 offset:49152
	ds_read_b128 v[200:203], v226 offset:50176
	ds_read_b128 v[204:207], v226 offset:51200
	ds_read_b128 v[210:213], v226 offset:52224
	s_waitcnt lgkmcnt(4)
	s_barrier
	s_waitcnt lgkmcnt(0)
	v_mfma_f32_16x16x32_bf16 v[126:129], v[140:143], v[164:167], v[126:129]
	v_mfma_f32_16x16x32_bf16 v[122:125], v[152:155], v[164:167], v[122:125]
	v_mfma_f32_16x16x32_bf16 v[118:121], v[140:143], v[172:175], v[118:121]
	v_mfma_f32_16x16x32_bf16 v[110:113], v[152:155], v[172:175], v[110:113]
	v_mfma_f32_16x16x32_bf16 v[102:105], v[140:143], v[180:183], v[102:105]
	v_mfma_f32_16x16x32_bf16 v[94:97], v[152:155], v[180:183], v[94:97]
	v_mfma_f32_16x16x32_bf16 v[86:89], v[140:143], v[188:191], v[86:89]
	v_mfma_f32_16x16x32_bf16 v[78:81], v[152:155], v[188:191], v[78:81]
	v_mfma_f32_16x16x32_bf16 v[126:129], v[148:151], v[168:171], v[126:129]
	v_mfma_f32_16x16x32_bf16 v[122:125], v[160:163], v[168:171], v[122:125]
	v_mfma_f32_16x16x32_bf16 v[118:121], v[148:151], v[176:179], v[118:121]
	v_mfma_f32_16x16x32_bf16 v[110:113], v[160:163], v[176:179], v[110:113]
	v_mfma_f32_16x16x32_bf16 v[102:105], v[148:151], v[184:187], v[102:105]
	v_mfma_f32_16x16x32_bf16 v[94:97], v[160:163], v[184:187], v[94:97]
	v_mfma_f32_16x16x32_bf16 v[86:89], v[148:151], v[192:195], v[86:89]
	v_mfma_f32_16x16x32_bf16 v[78:81], v[160:163], v[192:195], v[78:81]
	v_mfma_f32_16x16x32_bf16 v[114:117], v[196:199], v[164:167], v[114:117]
	v_mfma_f32_16x16x32_bf16 v[106:109], v[204:207], v[164:167], v[106:109]
	v_mfma_f32_16x16x32_bf16 v[98:101], v[196:199], v[172:175], v[98:101]
	v_mfma_f32_16x16x32_bf16 v[90:93], v[204:207], v[172:175], v[90:93]
	v_mfma_f32_16x16x32_bf16 v[82:85], v[196:199], v[180:183], v[82:85]
	v_mfma_f32_16x16x32_bf16 v[74:77], v[204:207], v[180:183], v[74:77]
	v_mfma_f32_16x16x32_bf16 v[70:73], v[196:199], v[188:191], v[70:73]
	v_mfma_f32_16x16x32_bf16 v[66:69], v[204:207], v[188:191], v[66:69]
	v_mfma_f32_16x16x32_bf16 v[114:117], v[200:203], v[168:171], v[114:117]
	v_mfma_f32_16x16x32_bf16 v[106:109], v[210:213], v[168:171], v[106:109]
	v_mfma_f32_16x16x32_bf16 v[98:101], v[200:203], v[176:179], v[98:101]
	v_mfma_f32_16x16x32_bf16 v[90:93], v[210:213], v[176:179], v[90:93]
	v_mfma_f32_16x16x32_bf16 v[82:85], v[200:203], v[184:187], v[82:85]
	v_mfma_f32_16x16x32_bf16 v[74:77], v[210:213], v[184:187], v[74:77]
	v_mfma_f32_16x16x32_bf16 v[70:73], v[200:203], v[192:195], v[70:73]
	v_mfma_f32_16x16x32_bf16 v[66:69], v[210:213], v[192:195], v[66:69]
	s_barrier
	s_add_i32 s38, s38, s56
	s_add_u32 s100, s52, s36
	s_addc_u32 s101, s53, s37
	s_mov_b32 m0, s38
	ds_read_b128 v[164:167], v147 offset:49152
	global_load_lds_dwordx4 v0, s[100:101]
	s_add_i32 m0, s38, 0x2000
	ds_read_b128 v[168:171], v147 offset:50176
	global_load_lds_dwordx4 v134, s[100:101]
	s_mov_b32 m0, s59
	s_add_u32 s100, s54, s36
	s_addc_u32 s101, s55, s37
	s_sub_u32 s100, s100, 0x80000
	s_subb_u32 s101, s101, 0
	global_load_lds_dwordx4 v130, s[100:101]
	s_mov_b32 m0, s60
	ds_read_b128 v[172:175], v147 offset:51200
	global_load_lds_dwordx4 v132, s[100:101]
	ds_read_b128 v[176:179], v147 offset:52224
	ds_read_b128 v[180:183], v147 offset:53248
	ds_read_b128 v[184:187], v147 offset:54272
	ds_read_b128 v[188:191], v147 offset:55296
	ds_read_b128 v[192:195], v147 offset:56320
	s_waitcnt vmcnt(4)
	s_waitcnt lgkmcnt(0)
	s_barrier
	v_mfma_f32_16x16x32_bf16 v[62:65], v[140:143], v[164:167], v[62:65]
	v_mfma_f32_16x16x32_bf16 v[58:61], v[152:155], v[164:167], v[58:61]
	v_mfma_f32_16x16x32_bf16 v[54:57], v[140:143], v[172:175], v[54:57]
	v_mfma_f32_16x16x32_bf16 v[46:49], v[152:155], v[172:175], v[46:49]
	v_mfma_f32_16x16x32_bf16 v[38:41], v[140:143], v[180:183], v[38:41]
	v_mfma_f32_16x16x32_bf16 v[30:33], v[152:155], v[180:183], v[30:33]
	v_mfma_f32_16x16x32_bf16 v[22:25], v[140:143], v[188:191], v[22:25]
	v_mfma_f32_16x16x32_bf16 v[14:17], v[152:155], v[188:191], v[14:17]
	v_mfma_f32_16x16x32_bf16 v[62:65], v[148:151], v[168:171], v[62:65]
	v_mfma_f32_16x16x32_bf16 v[58:61], v[160:163], v[168:171], v[58:61]
	v_mfma_f32_16x16x32_bf16 v[54:57], v[148:151], v[176:179], v[54:57]
	v_mfma_f32_16x16x32_bf16 v[46:49], v[160:163], v[176:179], v[46:49]
	v_mfma_f32_16x16x32_bf16 v[38:41], v[148:151], v[184:187], v[38:41]
	v_mfma_f32_16x16x32_bf16 v[30:33], v[160:163], v[184:187], v[30:33]
	v_mfma_f32_16x16x32_bf16 v[22:25], v[148:151], v[192:195], v[22:25]
	v_mfma_f32_16x16x32_bf16 v[14:17], v[160:163], v[192:195], v[14:17]
	s_add_u32 s52, s52, 0x80080
	s_addc_u32 s53, s53, 0
	s_add_i32 s38, s39, s56
	s_mov_b32 m0, s38
	s_nop 0
	global_load_lds_dwordx4 v0, s[52:53]
	s_add_i32 m0, s38, 0x2000
	s_nop 0
	global_load_lds_dwordx4 v134, s[52:53]
	v_mfma_f32_16x16x32_bf16 v[50:53], v[196:199], v[164:167], v[50:53]
	v_mfma_f32_16x16x32_bf16 v[42:45], v[204:207], v[164:167], v[42:45]
	v_mfma_f32_16x16x32_bf16 v[34:37], v[196:199], v[172:175], v[34:37]
	v_mfma_f32_16x16x32_bf16 v[26:29], v[204:207], v[172:175], v[26:29]
	v_mfma_f32_16x16x32_bf16 v[18:21], v[196:199], v[180:183], v[18:21]
	v_mfma_f32_16x16x32_bf16 v[10:13], v[204:207], v[180:183], v[10:13]
	v_mfma_f32_16x16x32_bf16 v[6:9], v[196:199], v[188:191], v[6:9]
	v_mfma_f32_16x16x32_bf16 v[2:5], v[204:207], v[188:191], v[2:5]
	v_mfma_f32_16x16x32_bf16 v[50:53], v[200:203], v[168:171], v[50:53]
	v_mfma_f32_16x16x32_bf16 v[42:45], v[210:213], v[168:171], v[42:45]
	v_mfma_f32_16x16x32_bf16 v[34:37], v[200:203], v[176:179], v[34:37]
	v_mfma_f32_16x16x32_bf16 v[26:29], v[210:213], v[176:179], v[26:29]
	v_mfma_f32_16x16x32_bf16 v[18:21], v[200:203], v[184:187], v[18:21]
	v_mfma_f32_16x16x32_bf16 v[10:13], v[210:213], v[184:187], v[10:13]
	v_mfma_f32_16x16x32_bf16 v[6:9], v[200:203], v[192:195], v[6:9]
	v_mfma_f32_16x16x32_bf16 v[2:5], v[210:213], v[192:195], v[2:5]
	s_add_i32 s70, s70, 2
	s_add_u32 s68, s68, 0x100
	s_addc_u32 s69, s69, 0
	s_add_u32 s50, s50, 0x100
	s_addc_u32 s51, s51, 0
	s_cmp_gt_u32 s70, 29
	s_barrier
; __device__ __forceinline__ unsigned cvt_pk_bf16(float lo, float hi) { unsigned r; asm("v_cvt_pk_bf16_f32 %0, %1, %2" : "=v"(r) : "v"(lo), "v"(hi)); return r; }
;     __device__ __forceinline__ void operator()(const f32x4 (&acc)[2][2][4][2], const Unit& u, int wr, int wc, int fr, int fq) const {
;         const int row0 = u.pm * BM + wr * 64 + fr, col0 = u.pn * BM + wc * 32 + 8 * fq;
; #pragma unroll
;         for (int ai = 0; ai < 2; ++ai)
; #pragma unroll
;             for (int m = 0; m < 4; ++m) { bf16_t* rowp = O + (size_t)(row0 + ai * HALF + m * 16) * ldc + col0;
; #pragma unroll
;                 for (int bj = 0; bj < 2; ++bj) { f32x4 v0 = acc[ai][bj][m][0], v1 = acc[ai][bj][m][1];
;                     if (ACT == 1) {
; #pragma unroll
;                         for (int j = 0; j < 4; ++j) { float a = fmaxf(v0[j], 0.f), b = fmaxf(v1[j], 0.f); v0[j] = a * a; v1[j] = b * b; } }
;                     u32x4 w; w.x = cvt_pk_bf16(v0[0], v0[1]); w.y = cvt_pk_bf16(v0[2], v0[3]); w.z = cvt_pk_bf16(v1[0], v1[1]); w.w = cvt_pk_bf16(v1[2], v1[3]);
;                     if (ACT == 1) __builtin_nontemporal_store(w, (u32x4*)(rowp + bj * HALF));
;                     else *(u32x4*)(rowp + bj * HALF) = w; } }
	s_cbranch_scc0 .LBB0_354
	s_load_dwordx2 s[50:51], s[0:1], 0xc0
	v_lshl_add_u32 v150, s28, 8, v144
	v_lshl_or_b32 v142, s40, 8, v146
	v_ashrrev_i32_e32 v143, 31, v142
	v_cvt_pk_bf16_f32 v70, v70, v71
	s_waitcnt lgkmcnt(0)
	v_mov_b64_e32 v[140:141], s[50:51]
	v_cvt_pk_bf16_f32 v71, v72, v73
	v_cvt_pk_bf16_f32 v72, v66, v67
	v_add_u32_e32 v66, 0x80, v150
	v_mad_i64_i32 v[148:149], s[50:51], v150, s17, v[140:141]
	v_lshlrev_b64 v[142:143], 1, v[142:143]
	v_cvt_pk_bf16_f32 v114, v114, v115
	v_cvt_pk_bf16_f32 v115, v116, v117
	v_cvt_pk_bf16_f32 v116, v106, v107
	v_or_b32_e32 v106, 16, v150
	v_mad_i64_i32 v[66:67], s[50:51], v66, s17, v[140:141]
	v_cvt_pk_bf16_f32 v50, v50, v51
	v_cvt_pk_bf16_f32 v51, v52, v53
	v_cvt_pk_bf16_f32 v52, v42, v43
	v_add_u32_e32 v42, 0x90, v150
	v_lshl_add_u64 v[148:149], v[148:149], 0, v[142:143]
	v_mad_i64_i32 v[106:107], s[50:51], v106, s17, v[140:141]
	v_cvt_pk_bf16_f32 v98, v98, v99
	v_cvt_pk_bf16_f32 v99, v100, v101
	v_cvt_pk_bf16_f32 v100, v90, v91
	v_or_b32_e32 v90, 32, v150
	v_lshl_add_u64 v[66:67], v[66:67], 0, v[142:143]
	v_mad_i64_i32 v[42:43], s[50:51], v42, s17, v[140:141]
	v_cvt_pk_bf16_f32 v34, v34, v35
	v_cvt_pk_bf16_f32 v35, v36, v37
	v_cvt_pk_bf16_f32 v36, v26, v27
	v_add_u32_e32 v26, 0xa0, v150
	v_cvt_pk_bf16_f32 v117, v108, v109
	global_store_dwordx4 v[148:149], v[114:117], off offset:256
	v_mad_i64_i32 v[90:91], s[50:51], v90, s17, v[140:141]
	s_nop 0
	v_lshl_add_u64 v[114:115], v[106:107], 0, v[142:143]
	v_cvt_pk_bf16_f32 v82, v82, v83
	v_cvt_pk_bf16_f32 v83, v84, v85
	v_cvt_pk_bf16_f32 v84, v74, v75
	v_or_b32_e32 v74, 48, v150
	v_cvt_pk_bf16_f32 v53, v44, v45
	global_store_dwordx4 v[66:67], v[50:53], off offset:256
	v_mad_i64_i32 v[26:27], s[50:51], v26, s17, v[140:141]
	s_nop 0
	v_lshl_add_u64 v[50:51], v[42:43], 0, v[142:143]
	v_cvt_pk_bf16_f32 v18, v18, v19
	v_cvt_pk_bf16_f32 v19, v20, v21
	v_cvt_pk_bf16_f32 v20, v10, v11
	v_add_u32_e32 v10, 0xb0, v150
	v_cvt_pk_bf16_f32 v101, v92, v93
	global_store_dwordx4 v[114:115], v[98:101], off offset:256
	v_mad_i64_i32 v[74:75], s[50:51], v74, s17, v[140:141]
	s_nop 0
	v_lshl_add_u64 v[98:99], v[90:91], 0, v[142:143]
	v_cvt_pk_bf16_f32 v37, v28, v29
	global_store_dwordx4 v[50:51], v[34:37], off offset:256
	v_mad_i64_i32 v[10:11], s[50:51], v10, s17, v[140:141]
	s_nop 0
	v_lshl_add_u64 v[34:35], v[26:27], 0, v[142:143]
	v_cvt_pk_bf16_f32 v85, v76, v77
	global_store_dwordx4 v[98:99], v[82:85], off offset:256
	v_cvt_pk_bf16_f32 v21, v12, v13
	global_store_dwordx4 v[34:35], v[18:21], off offset:256
	s_and_b64 vcc, exec, s[46:47]
	v_lshl_add_u64 v[82:83], v[74:75], 0, v[142:143]
	v_lshl_add_u64 v[18:19], v[10:11], 0, v[142:143]
	s_mov_b32 s40, s42
	s_mov_b32 s28, s8
	s_mov_b32 s43, s42
	s_mov_b32 s46, s8
	s_mov_b64 s[50:51], s[48:49]
	s_mov_b64 s[52:53], s[44:45]
	v_cvt_pk_bf16_f32 v126, v126, v127
	v_cvt_pk_bf16_f32 v127, v128, v129
	v_cvt_pk_bf16_f32 v128, v122, v123
	v_cvt_pk_bf16_f32 v129, v124, v125
	global_store_dwordx4 v[148:149], v[126:129], off
	v_cvt_pk_bf16_f32 v106, v118, v119
	v_cvt_pk_bf16_f32 v107, v120, v121
	v_cvt_pk_bf16_f32 v108, v110, v111
	v_cvt_pk_bf16_f32 v109, v112, v113
	global_store_dwordx4 v[114:115], v[106:109], off
	v_cvt_pk_bf16_f32 v90, v102, v103
	v_cvt_pk_bf16_f32 v91, v104, v105
	v_cvt_pk_bf16_f32 v92, v94, v95
	v_cvt_pk_bf16_f32 v93, v96, v97
	global_store_dwordx4 v[98:99], v[90:93], off
	v_cvt_pk_bf16_f32 v74, v86, v87
	v_cvt_pk_bf16_f32 v75, v88, v89
	v_cvt_pk_bf16_f32 v76, v78, v79
	v_cvt_pk_bf16_f32 v77, v80, v81
	global_store_dwordx4 v[82:83], v[74:77], off
	v_cvt_pk_bf16_f32 v73, v68, v69
	global_store_dwordx4 v[82:83], v[70:73], off offset:256
	v_cvt_pk_bf16_f32 v62, v62, v63
	v_cvt_pk_bf16_f32 v63, v64, v65
	v_cvt_pk_bf16_f32 v64, v58, v59
	v_cvt_pk_bf16_f32 v65, v60, v61
	global_store_dwordx4 v[66:67], v[62:65], off
	v_cvt_pk_bf16_f32 v42, v54, v55
	v_cvt_pk_bf16_f32 v43, v56, v57
	v_cvt_pk_bf16_f32 v44, v46, v47
	v_cvt_pk_bf16_f32 v45, v48, v49
	global_store_dwordx4 v[50:51], v[42:45], off
	v_cvt_pk_bf16_f32 v26, v38, v39
	v_cvt_pk_bf16_f32 v27, v40, v41
	v_cvt_pk_bf16_f32 v28, v30, v31
	v_cvt_pk_bf16_f32 v29, v32, v33
	global_store_dwordx4 v[34:35], v[26:29], off
	v_cvt_pk_bf16_f32 v10, v22, v23
	v_cvt_pk_bf16_f32 v11, v24, v25
	v_cvt_pk_bf16_f32 v12, v14, v15
	v_cvt_pk_bf16_f32 v13, v16, v17
	global_store_dwordx4 v[18:19], v[10:13], off
	v_cvt_pk_bf16_f32 v6, v6, v7
	v_cvt_pk_bf16_f32 v7, v8, v9
	v_cvt_pk_bf16_f32 v8, v2, v3
	v_cvt_pk_bf16_f32 v9, v4, v5
	global_store_dwordx4 v[18:19], v[6:9], off offset:256
	s_cbranch_vccz .LBB0_346
	s_waitcnt vmcnt(0)
	s_cmpk_gt_u32 s25, 0xff
	s_cbranch_scc1 .LBB0_358
	s_barrier
